# hand-written packed-math (v_pk_mul/v_pk_add) SwiGLU epilogues for both gate/up GEMM phases, same f32 ops per element; compute dtype unchanged
# speedup vs baseline: 1.0098x; 1.0025x over previous
; __device__ __forceinline__ float silu_f(float x) { return x * __builtin_amdgcn_rcpf(1.0f + __builtin_amdgcn_exp2f(-1.4426950408889634f * x)); }
;     __device__ __forceinline__ void operator()(const f32x4 (&acc)[2][2][4][2], const Unit& u, int wr, int wc, int fr, int fq) const {
;         const int row0 = u.pm * BM + wr * 64 + fr, col0 = u.pn * HALF + wc * 32 + 8 * fq;
; #pragma unroll
;         for (int ai = 0; ai < 2; ++ai)
; #pragma unroll
;             for (int m = 0; m < 4; ++m) {
;                 unsigned char* rowp = O + (size_t)(row0 + ai * HALF + m * 16) * DFF + col0;
;                 const f32x4 g0 = acc[ai][0][m][0], g1 = acc[ai][0][m][1], u0 = acc[ai][1][m][0], u1 = acc[ai][1][m][1];
;                 u32x2 w;
;                 w.x = pk4_fp8_nc(silu_f(g0[0]) * u0[0], silu_f(g0[1]) * u0[1], silu_f(g0[2]) * u0[2], silu_f(g0[3]) * u0[3]);
;                 w.y = pk4_fp8_nc(silu_f(g1[0]) * u1[0], silu_f(g1[1]) * u1[1], silu_f(g1[2]) * u1[2], silu_f(g1[3]) * u1[3]);
;                 *(u32x2*)rowp = w;
;             }
.LBB0_328:
	s_mov_b32 s64, 0xbfb8aa3b
	s_mov_b32 s65, 0xbfb8aa3b
	v_lshl_add_u32 v230, s20, 8, v189
	v_lshl_or_b32 v231, s60, 7, v190
	v_mad_u32_u24 v197, v230, s59, v231
	v_pk_mul_f32 v[198:199], v[158:159], s[64:65] op_sel_hi:[1,0]
	v_pk_mul_f32 v[200:201], v[160:161], s[64:65] op_sel_hi:[1,0]
	v_pk_mul_f32 v[202:203], v[150:151], s[64:65] op_sel_hi:[1,0]
	v_pk_mul_f32 v[204:205], v[152:153], s[64:65] op_sel_hi:[1,0]
	v_pk_mul_f32 v[206:207], v[142:143], s[64:65] op_sel_hi:[1,0]
	v_pk_mul_f32 v[208:209], v[144:145], s[64:65] op_sel_hi:[1,0]
	v_pk_mul_f32 v[210:211], v[134:135], s[64:65] op_sel_hi:[1,0]
	v_pk_mul_f32 v[212:213], v[136:137], s[64:65] op_sel_hi:[1,0]
	v_exp_f32_e32 v198, v198
	v_exp_f32_e32 v199, v199
	v_exp_f32_e32 v200, v200
	v_exp_f32_e32 v201, v201
	v_exp_f32_e32 v202, v202
	v_exp_f32_e32 v203, v203
	v_exp_f32_e32 v204, v204
	v_exp_f32_e32 v205, v205
	v_exp_f32_e32 v206, v206
	v_exp_f32_e32 v207, v207
	v_exp_f32_e32 v208, v208
	v_exp_f32_e32 v209, v209
	v_exp_f32_e32 v210, v210
	v_exp_f32_e32 v211, v211
	v_exp_f32_e32 v212, v212
	v_exp_f32_e32 v213, v213
	v_pk_add_f32 v[198:199], v[198:199], 1.0 op_sel_hi:[1,0]
	v_pk_add_f32 v[200:201], v[200:201], 1.0 op_sel_hi:[1,0]
	v_pk_add_f32 v[202:203], v[202:203], 1.0 op_sel_hi:[1,0]
	v_pk_add_f32 v[204:205], v[204:205], 1.0 op_sel_hi:[1,0]
	v_pk_add_f32 v[206:207], v[206:207], 1.0 op_sel_hi:[1,0]
	v_pk_add_f32 v[208:209], v[208:209], 1.0 op_sel_hi:[1,0]
	v_pk_add_f32 v[210:211], v[210:211], 1.0 op_sel_hi:[1,0]
	v_pk_add_f32 v[212:213], v[212:213], 1.0 op_sel_hi:[1,0]
	v_rcp_f32_e32 v198, v198
	v_rcp_f32_e32 v199, v199
	v_rcp_f32_e32 v200, v200
	v_rcp_f32_e32 v201, v201
	v_rcp_f32_e32 v202, v202
	v_rcp_f32_e32 v203, v203
	v_rcp_f32_e32 v204, v204
	v_rcp_f32_e32 v205, v205
	v_rcp_f32_e32 v206, v206
	v_rcp_f32_e32 v207, v207
	v_rcp_f32_e32 v208, v208
	v_rcp_f32_e32 v209, v209
	v_rcp_f32_e32 v210, v210
	v_rcp_f32_e32 v211, v211
	v_rcp_f32_e32 v212, v212
	v_rcp_f32_e32 v213, v213
	v_pk_mul_f32 v[198:199], v[158:159], v[198:199]
	v_pk_mul_f32 v[200:201], v[160:161], v[200:201]
	v_pk_mul_f32 v[202:203], v[150:151], v[202:203]
	v_pk_mul_f32 v[204:205], v[152:153], v[204:205]
	v_pk_mul_f32 v[206:207], v[142:143], v[206:207]
	v_pk_mul_f32 v[208:209], v[144:145], v[208:209]
	v_pk_mul_f32 v[210:211], v[134:135], v[210:211]
	v_pk_mul_f32 v[212:213], v[136:137], v[212:213]
	v_pk_mul_f32 v[198:199], v[198:199], v[154:155]
	v_pk_mul_f32 v[200:201], v[200:201], v[156:157]
	v_pk_mul_f32 v[202:203], v[202:203], v[146:147]
	v_pk_mul_f32 v[204:205], v[204:205], v[148:149]
	v_pk_mul_f32 v[206:207], v[206:207], v[138:139]
	v_pk_mul_f32 v[208:209], v[208:209], v[140:141]
	v_pk_mul_f32 v[210:211], v[210:211], v[130:131]
	v_pk_mul_f32 v[212:213], v[212:213], v[132:133]
	v_cvt_pk_fp8_f32 v214, v198, v199
	v_cvt_pk_fp8_f32 v215, v202, v203
	v_cvt_pk_fp8_f32 v216, v206, v207
	v_cvt_pk_fp8_f32 v217, v210, v211
	v_cvt_pk_fp8_f32 v214, v200, v201 op_sel:[0,0,1]
	v_cvt_pk_fp8_f32 v215, v204, v205 op_sel:[0,0,1]
	v_cvt_pk_fp8_f32 v216, v208, v209 op_sel:[0,0,1]
	v_cvt_pk_fp8_f32 v217, v212, v213 op_sel:[0,0,1]
	global_store_dwordx2 v197, v[214:215], s[6:7]
	s_add_u32 s66, s6, 0x16000
	s_addc_u32 s67, s7, 0
	global_store_dwordx2 v197, v[216:217], s[66:67]
	v_pk_mul_f32 v[198:199], v[126:127], s[64:65] op_sel_hi:[1,0]
	v_pk_mul_f32 v[200:201], v[128:129], s[64:65] op_sel_hi:[1,0]
	v_pk_mul_f32 v[202:203], v[118:119], s[64:65] op_sel_hi:[1,0]
	v_pk_mul_f32 v[204:205], v[120:121], s[64:65] op_sel_hi:[1,0]
	v_pk_mul_f32 v[206:207], v[110:111], s[64:65] op_sel_hi:[1,0]
	v_pk_mul_f32 v[208:209], v[112:113], s[64:65] op_sel_hi:[1,0]
	v_pk_mul_f32 v[210:211], v[102:103], s[64:65] op_sel_hi:[1,0]
	v_pk_mul_f32 v[212:213], v[104:105], s[64:65] op_sel_hi:[1,0]
	v_exp_f32_e32 v198, v198
	v_exp_f32_e32 v199, v199
	v_exp_f32_e32 v200, v200
	v_exp_f32_e32 v201, v201
	v_exp_f32_e32 v202, v202
	v_exp_f32_e32 v203, v203
	v_exp_f32_e32 v204, v204
	v_exp_f32_e32 v205, v205
	v_exp_f32_e32 v206, v206
	v_exp_f32_e32 v207, v207
	v_exp_f32_e32 v208, v208
	v_exp_f32_e32 v209, v209
	v_exp_f32_e32 v210, v210
	v_exp_f32_e32 v211, v211
	v_exp_f32_e32 v212, v212
	v_exp_f32_e32 v213, v213
	v_pk_add_f32 v[198:199], v[198:199], 1.0 op_sel_hi:[1,0]
	v_pk_add_f32 v[200:201], v[200:201], 1.0 op_sel_hi:[1,0]
	v_pk_add_f32 v[202:203], v[202:203], 1.0 op_sel_hi:[1,0]
	v_pk_add_f32 v[204:205], v[204:205], 1.0 op_sel_hi:[1,0]
	v_pk_add_f32 v[206:207], v[206:207], 1.0 op_sel_hi:[1,0]
	v_pk_add_f32 v[208:209], v[208:209], 1.0 op_sel_hi:[1,0]
	v_pk_add_f32 v[210:211], v[210:211], 1.0 op_sel_hi:[1,0]
	v_pk_add_f32 v[212:213], v[212:213], 1.0 op_sel_hi:[1,0]
	v_rcp_f32_e32 v198, v198
	v_rcp_f32_e32 v199, v199
	v_rcp_f32_e32 v200, v200
	v_rcp_f32_e32 v201, v201
	v_rcp_f32_e32 v202, v202
	v_rcp_f32_e32 v203, v203
	v_rcp_f32_e32 v204, v204
	v_rcp_f32_e32 v205, v205
	v_rcp_f32_e32 v206, v206
	v_rcp_f32_e32 v207, v207
	v_rcp_f32_e32 v208, v208
	v_rcp_f32_e32 v209, v209
	v_rcp_f32_e32 v210, v210
	v_rcp_f32_e32 v211, v211
	v_rcp_f32_e32 v212, v212
	v_rcp_f32_e32 v213, v213
	v_pk_mul_f32 v[198:199], v[126:127], v[198:199]
	v_pk_mul_f32 v[200:201], v[128:129], v[200:201]
	v_pk_mul_f32 v[202:203], v[118:119], v[202:203]
	v_pk_mul_f32 v[204:205], v[120:121], v[204:205]
	v_pk_mul_f32 v[206:207], v[110:111], v[206:207]
	v_pk_mul_f32 v[208:209], v[112:113], v[208:209]
	v_pk_mul_f32 v[210:211], v[102:103], v[210:211]
	v_pk_mul_f32 v[212:213], v[104:105], v[212:213]
	v_pk_mul_f32 v[198:199], v[198:199], v[122:123]
	v_pk_mul_f32 v[200:201], v[200:201], v[124:125]
	v_pk_mul_f32 v[202:203], v[202:203], v[114:115]
	v_pk_mul_f32 v[204:205], v[204:205], v[116:117]
; __device__ __forceinline__ float silu_f(float x) { return x * __builtin_amdgcn_rcpf(1.0f + __builtin_amdgcn_exp2f(-1.4426950408889634f * x)); }
;     __device__ __forceinline__ void operator()(const f32x4 (&acc)[2][2][4][2], const Unit& u, int wr, int wc, int fr, int fq) const {
;         const int row0 = u.pm * BM + wr * 64 + fr, col0 = u.pn * HALF + wc * 32 + 8 * fq;
; #pragma unroll
;         for (int ai = 0; ai < 2; ++ai)
; #pragma unroll
;             for (int m = 0; m < 4; ++m) {
;                 unsigned char* rowp = O + (size_t)(row0 + ai * HALF + m * 16) * DFF + col0;
;                 const f32x4 g0 = acc[ai][0][m][0], g1 = acc[ai][0][m][1], u0 = acc[ai][1][m][0], u1 = acc[ai][1][m][1];
;                 u32x2 w;
;                 w.x = pk4_fp8_nc(silu_f(g0[0]) * u0[0], silu_f(g0[1]) * u0[1], silu_f(g0[2]) * u0[2], silu_f(g0[3]) * u0[3]);
;                 w.y = pk4_fp8_nc(silu_f(g1[0]) * u1[0], silu_f(g1[1]) * u1[1], silu_f(g1[2]) * u1[2], silu_f(g1[3]) * u1[3]);
;                 *(u32x2*)rowp = w;
;             }
	v_pk_mul_f32 v[206:207], v[206:207], v[106:107]
	v_pk_mul_f32 v[208:209], v[208:209], v[108:109]
	v_pk_mul_f32 v[210:211], v[210:211], v[98:99]
	v_pk_mul_f32 v[212:213], v[212:213], v[100:101]
	v_cvt_pk_fp8_f32 v218, v198, v199
	v_cvt_pk_fp8_f32 v219, v202, v203
	v_cvt_pk_fp8_f32 v220, v206, v207
	v_cvt_pk_fp8_f32 v221, v210, v211
	v_cvt_pk_fp8_f32 v218, v200, v201 op_sel:[0,0,1]
	v_cvt_pk_fp8_f32 v219, v204, v205 op_sel:[0,0,1]
	v_cvt_pk_fp8_f32 v220, v208, v209 op_sel:[0,0,1]
	v_cvt_pk_fp8_f32 v221, v212, v213 op_sel:[0,0,1]
	s_add_u32 s66, s6, 0x2c000
	s_addc_u32 s67, s7, 0
	global_store_dwordx2 v197, v[218:219], s[66:67]
	s_add_u32 s66, s6, 0x42000
	s_addc_u32 s67, s7, 0
	global_store_dwordx2 v197, v[220:221], s[66:67]
	v_pk_mul_f32 v[198:199], v[94:95], s[64:65] op_sel_hi:[1,0]
	v_pk_mul_f32 v[200:201], v[96:97], s[64:65] op_sel_hi:[1,0]
	v_pk_mul_f32 v[202:203], v[86:87], s[64:65] op_sel_hi:[1,0]
	v_pk_mul_f32 v[204:205], v[88:89], s[64:65] op_sel_hi:[1,0]
	v_pk_mul_f32 v[206:207], v[78:79], s[64:65] op_sel_hi:[1,0]
	v_pk_mul_f32 v[208:209], v[80:81], s[64:65] op_sel_hi:[1,0]
	v_pk_mul_f32 v[210:211], v[70:71], s[64:65] op_sel_hi:[1,0]
	v_pk_mul_f32 v[212:213], v[72:73], s[64:65] op_sel_hi:[1,0]
	v_exp_f32_e32 v198, v198
	v_exp_f32_e32 v199, v199
	v_exp_f32_e32 v200, v200
	v_exp_f32_e32 v201, v201
	v_exp_f32_e32 v202, v202
	v_exp_f32_e32 v203, v203
	v_exp_f32_e32 v204, v204
	v_exp_f32_e32 v205, v205
	v_exp_f32_e32 v206, v206
	v_exp_f32_e32 v207, v207
	v_exp_f32_e32 v208, v208
	v_exp_f32_e32 v209, v209
	v_exp_f32_e32 v210, v210
	v_exp_f32_e32 v211, v211
	v_exp_f32_e32 v212, v212
	v_exp_f32_e32 v213, v213
	v_pk_add_f32 v[198:199], v[198:199], 1.0 op_sel_hi:[1,0]
	v_pk_add_f32 v[200:201], v[200:201], 1.0 op_sel_hi:[1,0]
	v_pk_add_f32 v[202:203], v[202:203], 1.0 op_sel_hi:[1,0]
	v_pk_add_f32 v[204:205], v[204:205], 1.0 op_sel_hi:[1,0]
	v_pk_add_f32 v[206:207], v[206:207], 1.0 op_sel_hi:[1,0]
	v_pk_add_f32 v[208:209], v[208:209], 1.0 op_sel_hi:[1,0]
	v_pk_add_f32 v[210:211], v[210:211], 1.0 op_sel_hi:[1,0]
	v_pk_add_f32 v[212:213], v[212:213], 1.0 op_sel_hi:[1,0]
	v_rcp_f32_e32 v198, v198
	v_rcp_f32_e32 v199, v199
	v_rcp_f32_e32 v200, v200
	v_rcp_f32_e32 v201, v201
	v_rcp_f32_e32 v202, v202
	v_rcp_f32_e32 v203, v203
	v_rcp_f32_e32 v204, v204
	v_rcp_f32_e32 v205, v205
	v_rcp_f32_e32 v206, v206
	v_rcp_f32_e32 v207, v207
	v_rcp_f32_e32 v208, v208
	v_rcp_f32_e32 v209, v209
	v_rcp_f32_e32 v210, v210
	v_rcp_f32_e32 v211, v211
	v_rcp_f32_e32 v212, v212
	v_rcp_f32_e32 v213, v213
	v_pk_mul_f32 v[198:199], v[94:95], v[198:199]
	v_pk_mul_f32 v[200:201], v[96:97], v[200:201]
	v_pk_mul_f32 v[202:203], v[86:87], v[202:203]
	v_pk_mul_f32 v[204:205], v[88:89], v[204:205]
	v_pk_mul_f32 v[206:207], v[78:79], v[206:207]
	v_pk_mul_f32 v[208:209], v[80:81], v[208:209]
	v_pk_mul_f32 v[210:211], v[70:71], v[210:211]
	v_pk_mul_f32 v[212:213], v[72:73], v[212:213]
	v_pk_mul_f32 v[198:199], v[198:199], v[90:91]
	v_pk_mul_f32 v[200:201], v[200:201], v[92:93]
	v_pk_mul_f32 v[202:203], v[202:203], v[82:83]
	v_pk_mul_f32 v[204:205], v[204:205], v[84:85]
	v_pk_mul_f32 v[206:207], v[206:207], v[74:75]
	v_pk_mul_f32 v[208:209], v[208:209], v[76:77]
	v_pk_mul_f32 v[210:211], v[210:211], v[66:67]
	v_pk_mul_f32 v[212:213], v[212:213], v[68:69]
	v_cvt_pk_fp8_f32 v222, v198, v199
	v_cvt_pk_fp8_f32 v223, v202, v203
	v_cvt_pk_fp8_f32 v224, v206, v207
	v_cvt_pk_fp8_f32 v225, v210, v211
	v_cvt_pk_fp8_f32 v222, v200, v201 op_sel:[0,0,1]
	v_cvt_pk_fp8_f32 v223, v204, v205 op_sel:[0,0,1]
	v_cvt_pk_fp8_f32 v224, v208, v209 op_sel:[0,0,1]
	v_cvt_pk_fp8_f32 v225, v212, v213 op_sel:[0,0,1]
	s_add_u32 s66, s6, 0xb0000
	s_addc_u32 s67, s7, 0
	global_store_dwordx2 v197, v[222:223], s[66:67]
	s_add_u32 s66, s6, 0xc6000
	s_addc_u32 s67, s7, 0
	global_store_dwordx2 v197, v[224:225], s[66:67]
; __device__ __forceinline__ float silu_f(float x) { return x * __builtin_amdgcn_rcpf(1.0f + __builtin_amdgcn_exp2f(-1.4426950408889634f * x)); }
;     __device__ __forceinline__ void operator()(const f32x4 (&acc)[2][2][4][2], const Unit& u, int wr, int wc, int fr, int fq) const {
;         const int row0 = u.pm * BM + wr * 64 + fr, col0 = u.pn * HALF + wc * 32 + 8 * fq;
; #pragma unroll
;         for (int ai = 0; ai < 2; ++ai)
; #pragma unroll
;             for (int m = 0; m < 4; ++m) {
;                 unsigned char* rowp = O + (size_t)(row0 + ai * HALF + m * 16) * DFF + col0;
;                 const f32x4 g0 = acc[ai][0][m][0], g1 = acc[ai][0][m][1], u0 = acc[ai][1][m][0], u1 = acc[ai][1][m][1];
;                 u32x2 w;
;                 w.x = pk4_fp8_nc(silu_f(g0[0]) * u0[0], silu_f(g0[1]) * u0[1], silu_f(g0[2]) * u0[2], silu_f(g0[3]) * u0[3]);
;                 w.y = pk4_fp8_nc(silu_f(g1[0]) * u1[0], silu_f(g1[1]) * u1[1], silu_f(g1[2]) * u1[2], silu_f(g1[3]) * u1[3]);
;                 *(u32x2*)rowp = w;
;             }
	v_pk_mul_f32 v[198:199], v[62:63], s[64:65] op_sel_hi:[1,0]
	v_pk_mul_f32 v[200:201], v[64:65], s[64:65] op_sel_hi:[1,0]
	v_pk_mul_f32 v[202:203], v[54:55], s[64:65] op_sel_hi:[1,0]
	v_pk_mul_f32 v[204:205], v[56:57], s[64:65] op_sel_hi:[1,0]
	v_pk_mul_f32 v[206:207], v[46:47], s[64:65] op_sel_hi:[1,0]
	v_pk_mul_f32 v[208:209], v[48:49], s[64:65] op_sel_hi:[1,0]
	v_pk_mul_f32 v[210:211], v[38:39], s[64:65] op_sel_hi:[1,0]
	v_pk_mul_f32 v[212:213], v[40:41], s[64:65] op_sel_hi:[1,0]
	v_exp_f32_e32 v198, v198
	v_exp_f32_e32 v199, v199
	v_exp_f32_e32 v200, v200
	v_exp_f32_e32 v201, v201
	v_exp_f32_e32 v202, v202
	v_exp_f32_e32 v203, v203
	v_exp_f32_e32 v204, v204
	v_exp_f32_e32 v205, v205
	v_exp_f32_e32 v206, v206
	v_exp_f32_e32 v207, v207
	v_exp_f32_e32 v208, v208
	v_exp_f32_e32 v209, v209
	v_exp_f32_e32 v210, v210
	v_exp_f32_e32 v211, v211
	v_exp_f32_e32 v212, v212
	v_exp_f32_e32 v213, v213
	v_pk_add_f32 v[198:199], v[198:199], 1.0 op_sel_hi:[1,0]
	v_pk_add_f32 v[200:201], v[200:201], 1.0 op_sel_hi:[1,0]
	v_pk_add_f32 v[202:203], v[202:203], 1.0 op_sel_hi:[1,0]
	v_pk_add_f32 v[204:205], v[204:205], 1.0 op_sel_hi:[1,0]
	v_pk_add_f32 v[206:207], v[206:207], 1.0 op_sel_hi:[1,0]
	v_pk_add_f32 v[208:209], v[208:209], 1.0 op_sel_hi:[1,0]
	v_pk_add_f32 v[210:211], v[210:211], 1.0 op_sel_hi:[1,0]
	v_pk_add_f32 v[212:213], v[212:213], 1.0 op_sel_hi:[1,0]
	v_rcp_f32_e32 v198, v198
	v_rcp_f32_e32 v199, v199
	v_rcp_f32_e32 v200, v200
	v_rcp_f32_e32 v201, v201
	v_rcp_f32_e32 v202, v202
	v_rcp_f32_e32 v203, v203
	v_rcp_f32_e32 v204, v204
	v_rcp_f32_e32 v205, v205
	v_rcp_f32_e32 v206, v206
	v_rcp_f32_e32 v207, v207
	v_rcp_f32_e32 v208, v208
	v_rcp_f32_e32 v209, v209
	v_rcp_f32_e32 v210, v210
	v_rcp_f32_e32 v211, v211
	v_rcp_f32_e32 v212, v212
	v_rcp_f32_e32 v213, v213
	v_pk_mul_f32 v[198:199], v[62:63], v[198:199]
	v_pk_mul_f32 v[200:201], v[64:65], v[200:201]
	v_pk_mul_f32 v[202:203], v[54:55], v[202:203]
	v_pk_mul_f32 v[204:205], v[56:57], v[204:205]
	v_pk_mul_f32 v[206:207], v[46:47], v[206:207]
	v_pk_mul_f32 v[208:209], v[48:49], v[208:209]
	v_pk_mul_f32 v[210:211], v[38:39], v[210:211]
	v_pk_mul_f32 v[212:213], v[40:41], v[212:213]
	v_pk_mul_f32 v[198:199], v[198:199], v[58:59]
	v_pk_mul_f32 v[200:201], v[200:201], v[60:61]
	v_pk_mul_f32 v[202:203], v[202:203], v[50:51]
	v_pk_mul_f32 v[204:205], v[204:205], v[52:53]
	v_pk_mul_f32 v[206:207], v[206:207], v[42:43]
	v_pk_mul_f32 v[208:209], v[208:209], v[44:45]
	v_pk_mul_f32 v[210:211], v[210:211], v[34:35]
	v_pk_mul_f32 v[212:213], v[212:213], v[36:37]
	v_cvt_pk_fp8_f32 v226, v198, v199
	v_cvt_pk_fp8_f32 v227, v202, v203
	v_cvt_pk_fp8_f32 v228, v206, v207
	v_cvt_pk_fp8_f32 v229, v210, v211
	v_cvt_pk_fp8_f32 v226, v200, v201 op_sel:[0,0,1]
	v_cvt_pk_fp8_f32 v227, v204, v205 op_sel:[0,0,1]
	v_cvt_pk_fp8_f32 v228, v208, v209 op_sel:[0,0,1]
	v_cvt_pk_fp8_f32 v229, v212, v213 op_sel:[0,0,1]
	s_add_u32 s66, s6, 0xdc000
	s_addc_u32 s67, s7, 0
	global_store_dwordx2 v197, v[226:227], s[66:67]
	s_add_u32 s66, s6, 0xf2000
	s_addc_u32 s67, s7, 0
	global_store_dwordx2 v197, v[228:229], s[66:67]
	v_readlane_b32 s64, v253, 42
	v_lshl_add_u64 v[2:3], v[4:5], 0, v[2:3]
	s_andn2_b64 vcc, exec, s[2:3]
	s_mov_b64 s[2:3], -1
	v_readlane_b32 s65, v253, 43
	v_readlane_b32 s66, v253, 44
	v_readlane_b32 s67, v253, 45
	v_readlane_b32 s68, v253, 46
	v_readlane_b32 s69, v253, 47
	v_readlane_b32 s70, v253, 48
	v_readlane_b32 s71, v253, 49
	v_readlane_b32 s72, v253, 50
	v_readlane_b32 s73, v253, 51
	v_readlane_b32 s74, v253, 52
	v_readlane_b32 s75, v253, 53
	v_readlane_b32 s76, v253, 54
	v_readlane_b32 s77, v253, 55
	v_readlane_b32 s78, v253, 56
	v_readlane_b32 s79, v253, 57
	s_cbranch_vccnz .LBB0_321
	s_andn2_b64 vcc, exec, s[0:1]
	s_cbranch_vccnz .LBB0_320
	s_barrier
	s_branch .LBB0_320

; __device__ __forceinline__ unsigned cvt_pk_bf16(float lo, float hi) { unsigned r; asm volatile("v_cvt_pk_bf16_f32 %0, %1, %2" : "=v"(r) : "v"(lo), "v"(hi)); return r; }
;     __device__ __forceinline__ void operator()(const f32x4 (&acc)[2][2][4][2], const Unit& u, int wr, int wc, int fr, int fq) const {
;     ...
; #pragma unroll
;             for (int ai = 0; ai < 2; ++ai)
; #pragma unroll
;                 for (int m = 0; m < 4; ++m) {
;                     const int row = row0 + ai * HALF + m * 16;
;                     const float* gp = gate + (size_t)modrow_of(row) * NMOD + col0;
;                     bf16_t* op = (bf16_t*)((char*)X + SLAB_MINUS_X) + ((size_t)u.kp * MS + (row - MP)) * DM + col0;
; #pragma unroll
;                     for (int bj = 0; bj < 2; ++bj) {
;                         const f32x4 g0 = (*(const f32x4*)(gp + bj * HALF) + *(const f32x4*)(gp + MODSB_DELTA + bj * HALF)) * coef, g1 = (*(const f32x4*)(gp + bj * HALF + 4) + *(const f32x4*)(gp + MODSB_DELTA + bj * HALF + 4)) * coef;
;                         const f32x4 o0 = g0 * acc[ai][bj][m][0], o1 = g1 * acc[ai][bj][m][1];
;                         u32x4 w; w.x = cvt_pk_bf16(o0[0], o0[1]); w.y = cvt_pk_bf16(o0[2], o0[3]); w.z = cvt_pk_bf16(o1[0], o1[1]); w.w = cvt_pk_bf16(o1[2], o1[3]);
;                         *(u32x4*)(op + bj * HALF) = w;
;                     }
;                     if (m & 1) asm volatile("" ::: "memory");
;                 }
.LBB0_505:
	s_lshl_b32 s30, s75, 8
	s_nop 15
	s_nop 15
	s_add_i32 s30, s30, s62
	v_or_b32_e32 v2, s30, v183
	v_lshl_or_b32 v10, s80, 8, v186
	s_mov_b64 s[28:29], -1
	s_andn2_b64 vcc, exec, s[26:27]
	v_ashrrev_i32_e32 v11, 31, v10
	v_or_b32_e32 v8, 16, v2
	v_or_b32_e32 v6, 32, v2
	v_or_b32_e32 v4, 48, v2
	s_cbranch_vccnz .LBB0_508
	v_add_u32_e32 v16, 0xffffe000, v2
	s_ashr_i32 s25, s30, 11
	v_lshrrev_b32_e32 v3, 2, v16
	v_cmp_gt_i32_e32 vcc, s59, v2
	v_or_b32_e32 v5, 4, v3
	v_mov_b32_e32 v3, s25
	v_cndmask_b32_e32 v5, v5, v3, vcc
	v_mov_b64_e32 v[12:13], s[10:11]
	s_mov_b32 s25, s1
	v_mad_i64_i32 v[18:19], s[26:27], v5, s58, v[12:13]
	v_lshlrev_b64 v[14:15], 2, v[10:11]
	s_lshl_b64 s[24:25], s[24:25], 21
	v_lshl_add_u64 v[174:175], v[18:19], 0, v[14:15]
	v_ashrrev_i32_e32 v17, 31, v16
	s_add_u32 s24, s60, s24
	s_addc_u32 s25, s61, s25
	v_lshlrev_b64 v[16:17], 12, v[16:17]
	v_add_co_u32_e32 v178, vcc, s67, v174
	v_lshl_add_u64 v[18:19], s[24:25], 0, v[16:17]
	v_lshlrev_b64 v[16:17], 1, v[10:11]
	v_lshl_add_u64 v[30:31], v[174:175], 0, s[16:17]
	v_addc_co_u32_e32 v179, vcc, 0, v175, vcc
	v_lshl_add_u64 v[176:177], v[18:19], 0, v[16:17]
	global_load_dwordx4 v[18:21], v[174:175], off offset:16
	global_load_dwordx4 v[22:25], v[174:175], off
	global_load_dwordx4 v[26:29], v[178:179], off
	s_nop 0
	global_load_dwordx4 v[30:33], v[30:31], off offset:16
	v_cmp_gt_i32_e32 vcc, s59, v8
	s_addk_i32 s30, 0x80
	s_waitcnt vmcnt(0)
	v_pk_add_f32 v[24:25], v[24:25], v[28:29]
	v_pk_add_f32 v[20:21], v[20:21], v[32:33]
	v_pk_add_f32 v[18:19], v[18:19], v[30:31]
	v_pk_add_f32 v[22:23], v[22:23], v[26:27]
	v_pk_mul_f32 v[20:21], v[20:21], 0.5 op_sel_hi:[1,0]
	v_pk_mul_f32 v[18:19], v[18:19], 0.5 op_sel_hi:[1,0]
	v_pk_mul_f32 v[24:25], v[24:25], 0.5 op_sel_hi:[1,0]
	v_pk_mul_f32 v[22:23], v[22:23], 0.5 op_sel_hi:[1,0]
	v_pk_mul_f32 v[26:27], v[156:157], v[20:21]
	v_pk_mul_f32 v[20:21], v[154:155], v[18:19]
	v_pk_mul_f32 v[24:25], v[160:161], v[24:25]
	v_pk_mul_f32 v[22:23], v[158:159], v[22:23]
	v_lshl_add_u64 v[30:31], v[174:175], 0, s[18:19]
	v_cvt_pk_bf16_f32 v18, v22, v23
	v_cvt_pk_bf16_f32 v19, v24, v25
	v_cvt_pk_bf16_f32 v20, v20, v21
	v_cvt_pk_bf16_f32 v21, v26, v27
	global_store_dwordx4 v[176:177], v[18:21], off
	global_load_dwordx4 v[18:21], v[174:175], off offset:528
	s_nop 0
	global_load_dwordx4 v[22:25], v[174:175], off offset:512
	global_load_dwordx4 v[26:29], v[178:179], off offset:512
	s_nop 0
	global_load_dwordx4 v[30:33], v[30:31], off offset:16
	s_waitcnt vmcnt(1)
	v_pk_add_f32 v[22:23], v[22:23], v[26:27]
	s_waitcnt vmcnt(0)
	v_pk_add_f32 v[20:21], v[20:21], v[32:33]
	v_pk_add_f32 v[18:19], v[18:19], v[30:31]
	v_pk_add_f32 v[24:25], v[24:25], v[28:29]
	v_pk_mul_f32 v[22:23], v[22:23], 0.5 op_sel_hi:[1,0]
	v_pk_mul_f32 v[20:21], v[20:21], 0.5 op_sel_hi:[1,0]
	v_pk_mul_f32 v[18:19], v[18:19], 0.5 op_sel_hi:[1,0]
	v_pk_mul_f32 v[24:25], v[24:25], 0.5 op_sel_hi:[1,0]
	v_pk_mul_f32 v[22:23], v[150:151], v[22:23]
	v_pk_mul_f32 v[26:27], v[148:149], v[20:21]
	v_pk_mul_f32 v[20:21], v[146:147], v[18:19]
	v_cvt_pk_bf16_f32 v18, v22, v23
	v_pk_mul_f32 v[24:25], v[152:153], v[24:25]
	s_nop 0
	v_cvt_pk_bf16_f32 v19, v24, v25
	v_cvt_pk_bf16_f32 v20, v20, v21
	v_cvt_pk_bf16_f32 v21, v26, v27
	global_store_dwordx4 v[176:177], v[18:21], off offset:256
	s_nop 1
	v_add_u32_e32 v18, 0xffffe010, v2
	v_lshrrev_b32_e32 v5, 2, v18
	v_add_u32_e32 v5, 4, v5
	v_cndmask_b32_e32 v5, v5, v3, vcc
	v_mad_i64_i32 v[20:21], s[26:27], v5, s58, v[12:13]
	v_lshl_add_u64 v[174:175], v[20:21], 0, v[14:15]
	v_ashrrev_i32_e32 v19, 31, v18
	v_lshlrev_b64 v[18:19], 12, v[18:19]
	v_add_co_u32_e32 v178, vcc, s67, v174
	v_lshl_add_u64 v[18:19], s[24:25], 0, v[18:19]
	v_lshl_add_u64 v[30:31], v[174:175], 0, s[16:17]
	v_addc_co_u32_e32 v179, vcc, 0, v175, vcc
	v_lshl_add_u64 v[176:177], v[18:19], 0, v[16:17]
	global_load_dwordx4 v[18:21], v[174:175], off offset:16
	global_load_dwordx4 v[22:25], v[174:175], off
	global_load_dwordx4 v[26:29], v[178:179], off
	s_nop 0
	global_load_dwordx4 v[30:33], v[30:31], off offset:16
	v_cmp_gt_i32_e32 vcc, s59, v6
	s_waitcnt vmcnt(1)
	v_pk_add_f32 v[24:25], v[24:25], v[28:29]
	s_waitcnt vmcnt(0)
	v_pk_add_f32 v[20:21], v[20:21], v[32:33]
	v_pk_add_f32 v[18:19], v[18:19], v[30:31]
	v_pk_add_f32 v[22:23], v[22:23], v[26:27]
	v_pk_mul_f32 v[20:21], v[20:21], 0.5 op_sel_hi:[1,0]
	v_pk_mul_f32 v[18:19], v[18:19], 0.5 op_sel_hi:[1,0]
	v_pk_mul_f32 v[24:25], v[24:25], 0.5 op_sel_hi:[1,0]
	v_pk_mul_f32 v[22:23], v[22:23], 0.5 op_sel_hi:[1,0]
	v_pk_mul_f32 v[26:27], v[140:141], v[20:21]
	v_pk_mul_f32 v[20:21], v[138:139], v[18:19]
	v_pk_mul_f32 v[24:25], v[144:145], v[24:25]
	v_pk_mul_f32 v[22:23], v[142:143], v[22:23]
	v_lshl_add_u64 v[30:31], v[174:175], 0, s[18:19]
	v_cvt_pk_bf16_f32 v18, v22, v23
	v_cvt_pk_bf16_f32 v19, v24, v25
	v_cvt_pk_bf16_f32 v20, v20, v21
	v_cvt_pk_bf16_f32 v21, v26, v27
	global_store_dwordx4 v[176:177], v[18:21], off
	global_load_dwordx4 v[18:21], v[174:175], off offset:528
	s_nop 0
	global_load_dwordx4 v[22:25], v[174:175], off offset:512
	global_load_dwordx4 v[26:29], v[178:179], off offset:512
	s_nop 0
	global_load_dwordx4 v[30:33], v[30:31], off offset:16
	s_waitcnt vmcnt(1)
	v_pk_add_f32 v[22:23], v[22:23], v[26:27]
	s_waitcnt vmcnt(0)
; __device__ __forceinline__ unsigned cvt_pk_bf16(float lo, float hi) { unsigned r; asm volatile("v_cvt_pk_bf16_f32 %0, %1, %2" : "=v"(r) : "v"(lo), "v"(hi)); return r; }
;     __device__ __forceinline__ void operator()(const f32x4 (&acc)[2][2][4][2], const Unit& u, int wr, int wc, int fr, int fq) const {
;     ...
; #pragma unroll
;             for (int ai = 0; ai < 2; ++ai)
; #pragma unroll
;                 for (int m = 0; m < 4; ++m) {
;                     const int row = row0 + ai * HALF + m * 16;
;                     const float* gp = gate + (size_t)modrow_of(row) * NMOD + col0;
;                     bf16_t* op = (bf16_t*)((char*)X + SLAB_MINUS_X) + ((size_t)u.kp * MS + (row - MP)) * DM + col0;
; #pragma unroll
;                     for (int bj = 0; bj < 2; ++bj) {
;                         const f32x4 g0 = (*(const f32x4*)(gp + bj * HALF) + *(const f32x4*)(gp + MODSB_DELTA + bj * HALF)) * coef, g1 = (*(const f32x4*)(gp + bj * HALF + 4) + *(const f32x4*)(gp + MODSB_DELTA + bj * HALF + 4)) * coef;
;                         const f32x4 o0 = g0 * acc[ai][bj][m][0], o1 = g1 * acc[ai][bj][m][1];
;                         u32x4 w; w.x = cvt_pk_bf16(o0[0], o0[1]); w.y = cvt_pk_bf16(o0[2], o0[3]); w.z = cvt_pk_bf16(o1[0], o1[1]); w.w = cvt_pk_bf16(o1[2], o1[3]);
;                         *(u32x4*)(op + bj * HALF) = w;
;                     }
;                     if (m & 1) asm volatile("" ::: "memory");
;                 }
	v_pk_add_f32 v[20:21], v[20:21], v[32:33]
	v_pk_add_f32 v[18:19], v[18:19], v[30:31]
	v_pk_add_f32 v[24:25], v[24:25], v[28:29]
	v_pk_mul_f32 v[22:23], v[22:23], 0.5 op_sel_hi:[1,0]
	v_pk_mul_f32 v[20:21], v[20:21], 0.5 op_sel_hi:[1,0]
	v_pk_mul_f32 v[18:19], v[18:19], 0.5 op_sel_hi:[1,0]
	v_pk_mul_f32 v[24:25], v[24:25], 0.5 op_sel_hi:[1,0]
	v_pk_mul_f32 v[22:23], v[134:135], v[22:23]
	v_pk_mul_f32 v[26:27], v[132:133], v[20:21]
	v_pk_mul_f32 v[20:21], v[130:131], v[18:19]
	v_cvt_pk_bf16_f32 v18, v22, v23
	v_pk_mul_f32 v[24:25], v[136:137], v[24:25]
	s_nop 0
	v_cvt_pk_bf16_f32 v19, v24, v25
	v_cvt_pk_bf16_f32 v20, v20, v21
	v_cvt_pk_bf16_f32 v21, v26, v27
	global_store_dwordx4 v[176:177], v[18:21], off offset:256
	s_nop 1
	v_add_u32_e32 v18, 0xffffe020, v2
	v_lshrrev_b32_e32 v5, 2, v18
	v_or_b32_e32 v5, 4, v5
	v_cndmask_b32_e32 v5, v5, v3, vcc
	v_mad_i64_i32 v[20:21], s[26:27], v5, s58, v[12:13]
	v_lshl_add_u64 v[32:33], v[20:21], 0, v[14:15]
	v_add_co_u32_e32 v178, vcc, s67, v32
	v_lshl_add_u64 v[174:175], v[32:33], 0, s[16:17]
	s_nop 0
	v_addc_co_u32_e32 v179, vcc, 0, v33, vcc
	global_load_dwordx4 v[20:23], v[32:33], off offset:16
	global_load_dwordx4 v[24:27], v[32:33], off
	global_load_dwordx4 v[28:31], v[178:179], off
	s_nop 0
	global_load_dwordx4 v[174:177], v[174:175], off offset:16
	v_ashrrev_i32_e32 v19, 31, v18
	v_lshlrev_b64 v[18:19], 12, v[18:19]
	v_lshl_add_u64 v[18:19], s[24:25], 0, v[18:19]
	v_lshl_add_u64 v[18:19], v[18:19], 0, v[16:17]
	v_cmp_gt_i32_e32 vcc, s59, v4
	s_waitcnt vmcnt(1)
	v_pk_add_f32 v[26:27], v[26:27], v[30:31]
	s_waitcnt vmcnt(0)
	v_pk_add_f32 v[22:23], v[22:23], v[176:177]
	v_pk_add_f32 v[20:21], v[20:21], v[174:175]
	v_pk_add_f32 v[24:25], v[24:25], v[28:29]
	v_pk_mul_f32 v[22:23], v[22:23], 0.5 op_sel_hi:[1,0]
	v_pk_mul_f32 v[20:21], v[20:21], 0.5 op_sel_hi:[1,0]
	v_pk_mul_f32 v[26:27], v[26:27], 0.5 op_sel_hi:[1,0]
	v_pk_mul_f32 v[24:25], v[24:25], 0.5 op_sel_hi:[1,0]
	v_pk_mul_f32 v[28:29], v[124:125], v[22:23]
	v_pk_mul_f32 v[22:23], v[122:123], v[20:21]
	v_pk_mul_f32 v[26:27], v[128:129], v[26:27]
	v_pk_mul_f32 v[24:25], v[126:127], v[24:25]
	s_nop 0
	v_cvt_pk_bf16_f32 v20, v24, v25
	v_cvt_pk_bf16_f32 v21, v26, v27
	v_cvt_pk_bf16_f32 v22, v22, v23
	v_cvt_pk_bf16_f32 v23, v28, v29
	global_store_dwordx4 v[18:19], v[20:23], off
	global_load_dwordx4 v[20:23], v[32:33], off offset:528
	s_nop 0
	global_load_dwordx4 v[24:27], v[32:33], off offset:512
	v_lshl_add_u64 v[32:33], v[32:33], 0, s[18:19]
	global_load_dwordx4 v[28:31], v[178:179], off offset:512
	global_load_dwordx4 v[174:177], v[32:33], off offset:16
	s_waitcnt vmcnt(1)
	v_pk_add_f32 v[26:27], v[26:27], v[30:31]
	s_waitcnt vmcnt(0)
	v_pk_add_f32 v[22:23], v[22:23], v[176:177]
	v_pk_add_f32 v[20:21], v[20:21], v[174:175]
	v_pk_add_f32 v[24:25], v[24:25], v[28:29]
	v_pk_mul_f32 v[22:23], v[22:23], 0.5 op_sel_hi:[1,0]
	v_pk_mul_f32 v[20:21], v[20:21], 0.5 op_sel_hi:[1,0]
	v_pk_mul_f32 v[26:27], v[26:27], 0.5 op_sel_hi:[1,0]
	v_pk_mul_f32 v[24:25], v[24:25], 0.5 op_sel_hi:[1,0]
	v_pk_mul_f32 v[28:29], v[116:117], v[22:23]
	v_pk_mul_f32 v[22:23], v[114:115], v[20:21]
	v_pk_mul_f32 v[26:27], v[120:121], v[26:27]
	v_pk_mul_f32 v[24:25], v[118:119], v[24:25]
	s_nop 0
	v_cvt_pk_bf16_f32 v20, v24, v25
	v_cvt_pk_bf16_f32 v21, v26, v27
	v_cvt_pk_bf16_f32 v22, v22, v23
	v_cvt_pk_bf16_f32 v23, v28, v29
	global_store_dwordx4 v[18:19], v[20:23], off offset:256
	v_add_u32_e32 v18, 0xffffe030, v2
	v_lshrrev_b32_e32 v5, 2, v18
	v_add_u32_e32 v5, 4, v5
	v_cndmask_b32_e32 v3, v5, v3, vcc
	v_mad_i64_i32 v[20:21], s[26:27], v3, s58, v[12:13]
	v_lshl_add_u64 v[174:175], v[20:21], 0, v[14:15]
	v_ashrrev_i32_e32 v19, 31, v18
	v_lshlrev_b64 v[18:19], 12, v[18:19]
	v_add_co_u32_e32 v178, vcc, s67, v174
	v_lshl_add_u64 v[18:19], s[24:25], 0, v[18:19]
	v_lshl_add_u64 v[30:31], v[174:175], 0, s[16:17]
	v_addc_co_u32_e32 v179, vcc, 0, v175, vcc
	v_lshl_add_u64 v[176:177], v[18:19], 0, v[16:17]
	global_load_dwordx4 v[18:21], v[174:175], off offset:16
	global_load_dwordx4 v[22:25], v[174:175], off
	global_load_dwordx4 v[26:29], v[178:179], off
	s_nop 0
	global_load_dwordx4 v[30:33], v[30:31], off offset:16
	s_ashr_i32 s26, s30, 11
	s_movk_i32 s27, 0x1f80
	v_cmp_gt_i32_e32 vcc, s27, v2
	s_waitcnt vmcnt(1)
	v_pk_add_f32 v[24:25], v[24:25], v[28:29]
	s_waitcnt vmcnt(0)
	v_pk_add_f32 v[20:21], v[20:21], v[32:33]
	v_pk_add_f32 v[18:19], v[18:19], v[30:31]
	v_pk_add_f32 v[22:23], v[22:23], v[26:27]
	v_pk_mul_f32 v[20:21], v[20:21], 0.5 op_sel_hi:[1,0]
	v_pk_mul_f32 v[18:19], v[18:19], 0.5 op_sel_hi:[1,0]
	v_pk_mul_f32 v[24:25], v[24:25], 0.5 op_sel_hi:[1,0]
	v_pk_mul_f32 v[22:23], v[22:23], 0.5 op_sel_hi:[1,0]
	v_pk_mul_f32 v[26:27], v[108:109], v[20:21]
	v_pk_mul_f32 v[20:21], v[106:107], v[18:19]
	v_pk_mul_f32 v[24:25], v[112:113], v[24:25]
	v_pk_mul_f32 v[22:23], v[110:111], v[22:23]
	v_lshl_add_u64 v[30:31], v[174:175], 0, s[18:19]
	v_cvt_pk_bf16_f32 v18, v22, v23
	v_cvt_pk_bf16_f32 v19, v24, v25
	v_cvt_pk_bf16_f32 v20, v20, v21
	v_cvt_pk_bf16_f32 v21, v26, v27
	global_store_dwordx4 v[176:177], v[18:21], off
	global_load_dwordx4 v[18:21], v[174:175], off offset:528
	s_nop 0
	global_load_dwordx4 v[22:25], v[174:175], off offset:512
	global_load_dwordx4 v[26:29], v[178:179], off offset:512
	s_nop 0
	global_load_dwordx4 v[30:33], v[30:31], off offset:16
	s_waitcnt vmcnt(1)
	v_pk_add_f32 v[22:23], v[22:23], v[26:27]
	s_waitcnt vmcnt(0)
; __device__ __forceinline__ unsigned cvt_pk_bf16(float lo, float hi) { unsigned r; asm volatile("v_cvt_pk_bf16_f32 %0, %1, %2" : "=v"(r) : "v"(lo), "v"(hi)); return r; }
;     __device__ __forceinline__ void operator()(const f32x4 (&acc)[2][2][4][2], const Unit& u, int wr, int wc, int fr, int fq) const {
;     ...
; #pragma unroll
;             for (int ai = 0; ai < 2; ++ai)
; #pragma unroll
;                 for (int m = 0; m < 4; ++m) {
;                     const int row = row0 + ai * HALF + m * 16;
;                     const float* gp = gate + (size_t)modrow_of(row) * NMOD + col0;
;                     bf16_t* op = (bf16_t*)((char*)X + SLAB_MINUS_X) + ((size_t)u.kp * MS + (row - MP)) * DM + col0;
; #pragma unroll
;                     for (int bj = 0; bj < 2; ++bj) {
;                         const f32x4 g0 = (*(const f32x4*)(gp + bj * HALF) + *(const f32x4*)(gp + MODSB_DELTA + bj * HALF)) * coef, g1 = (*(const f32x4*)(gp + bj * HALF + 4) + *(const f32x4*)(gp + MODSB_DELTA + bj * HALF + 4)) * coef;
;                         const f32x4 o0 = g0 * acc[ai][bj][m][0], o1 = g1 * acc[ai][bj][m][1];
;                         u32x4 w; w.x = cvt_pk_bf16(o0[0], o0[1]); w.y = cvt_pk_bf16(o0[2], o0[3]); w.z = cvt_pk_bf16(o1[0], o1[1]); w.w = cvt_pk_bf16(o1[2], o1[3]);
;                         *(u32x4*)(op + bj * HALF) = w;
;                     }
;                     if (m & 1) asm volatile("" ::: "memory");
;                 }
	v_pk_add_f32 v[20:21], v[20:21], v[32:33]
	v_pk_add_f32 v[18:19], v[18:19], v[30:31]
	v_pk_add_f32 v[24:25], v[24:25], v[28:29]
	v_pk_mul_f32 v[22:23], v[22:23], 0.5 op_sel_hi:[1,0]
	v_pk_mul_f32 v[20:21], v[20:21], 0.5 op_sel_hi:[1,0]
	v_pk_mul_f32 v[18:19], v[18:19], 0.5 op_sel_hi:[1,0]
	v_pk_mul_f32 v[24:25], v[24:25], 0.5 op_sel_hi:[1,0]
	v_pk_mul_f32 v[22:23], v[102:103], v[22:23]
	v_pk_mul_f32 v[26:27], v[100:101], v[20:21]
	v_pk_mul_f32 v[20:21], v[98:99], v[18:19]
	v_cvt_pk_bf16_f32 v18, v22, v23
	v_pk_mul_f32 v[24:25], v[104:105], v[24:25]
	s_nop 0
	v_cvt_pk_bf16_f32 v19, v24, v25
	v_cvt_pk_bf16_f32 v20, v20, v21
	v_cvt_pk_bf16_f32 v21, v26, v27
	global_store_dwordx4 v[176:177], v[18:21], off offset:256
	s_nop 1
	v_add_u32_e32 v18, 0xffffe080, v2
	v_lshrrev_b32_e32 v3, 2, v18
	v_or_b32_e32 v5, 4, v3
	v_mov_b32_e32 v3, s26
	v_cndmask_b32_e32 v5, v5, v3, vcc
	v_mad_i64_i32 v[20:21], s[26:27], v5, s58, v[12:13]
	v_lshl_add_u64 v[32:33], v[20:21], 0, v[14:15]
	v_add_co_u32_e32 v178, vcc, s67, v32
	v_lshl_add_u64 v[174:175], v[32:33], 0, s[16:17]
	s_nop 0
	v_addc_co_u32_e32 v179, vcc, 0, v33, vcc
	global_load_dwordx4 v[20:23], v[32:33], off offset:16
	global_load_dwordx4 v[24:27], v[32:33], off
	global_load_dwordx4 v[28:31], v[178:179], off
	s_nop 0
	global_load_dwordx4 v[174:177], v[174:175], off offset:16
	v_ashrrev_i32_e32 v19, 31, v18
	v_lshlrev_b64 v[18:19], 12, v[18:19]
	v_lshl_add_u64 v[18:19], s[24:25], 0, v[18:19]
	v_lshl_add_u64 v[18:19], v[18:19], 0, v[16:17]
	s_movk_i32 s26, 0x1f70
	v_cmp_gt_i32_e32 vcc, s26, v2
	s_waitcnt vmcnt(1)
	v_pk_add_f32 v[26:27], v[26:27], v[30:31]
	s_waitcnt vmcnt(0)
	v_pk_add_f32 v[22:23], v[22:23], v[176:177]
	v_pk_add_f32 v[20:21], v[20:21], v[174:175]
	v_pk_add_f32 v[24:25], v[24:25], v[28:29]
	v_pk_mul_f32 v[22:23], v[22:23], 0.5 op_sel_hi:[1,0]
	v_pk_mul_f32 v[20:21], v[20:21], 0.5 op_sel_hi:[1,0]
	v_pk_mul_f32 v[26:27], v[26:27], 0.5 op_sel_hi:[1,0]
	v_pk_mul_f32 v[24:25], v[24:25], 0.5 op_sel_hi:[1,0]
	v_pk_mul_f32 v[28:29], v[92:93], v[22:23]
	v_pk_mul_f32 v[22:23], v[90:91], v[20:21]
	v_pk_mul_f32 v[26:27], v[96:97], v[26:27]
	v_pk_mul_f32 v[24:25], v[94:95], v[24:25]
	s_nop 0
	v_cvt_pk_bf16_f32 v20, v24, v25
	v_cvt_pk_bf16_f32 v21, v26, v27
	v_cvt_pk_bf16_f32 v22, v22, v23
	v_cvt_pk_bf16_f32 v23, v28, v29
	global_store_dwordx4 v[18:19], v[20:23], off
	global_load_dwordx4 v[20:23], v[32:33], off offset:528
	s_nop 0
	global_load_dwordx4 v[24:27], v[32:33], off offset:512
	v_lshl_add_u64 v[32:33], v[32:33], 0, s[18:19]
	global_load_dwordx4 v[28:31], v[178:179], off offset:512
	global_load_dwordx4 v[174:177], v[32:33], off offset:16
	s_waitcnt vmcnt(1)
	v_pk_add_f32 v[26:27], v[26:27], v[30:31]
	s_waitcnt vmcnt(0)
	v_pk_add_f32 v[22:23], v[22:23], v[176:177]
	v_pk_add_f32 v[20:21], v[20:21], v[174:175]
	v_pk_add_f32 v[24:25], v[24:25], v[28:29]
	v_pk_mul_f32 v[22:23], v[22:23], 0.5 op_sel_hi:[1,0]
	v_pk_mul_f32 v[20:21], v[20:21], 0.5 op_sel_hi:[1,0]
	v_pk_mul_f32 v[26:27], v[26:27], 0.5 op_sel_hi:[1,0]
	v_pk_mul_f32 v[24:25], v[24:25], 0.5 op_sel_hi:[1,0]
	v_pk_mul_f32 v[28:29], v[84:85], v[22:23]
	v_pk_mul_f32 v[22:23], v[82:83], v[20:21]
	v_pk_mul_f32 v[26:27], v[88:89], v[26:27]
	v_pk_mul_f32 v[24:25], v[86:87], v[24:25]
	s_nop 0
	v_cvt_pk_bf16_f32 v20, v24, v25
	v_cvt_pk_bf16_f32 v21, v26, v27
	v_cvt_pk_bf16_f32 v22, v22, v23
	v_cvt_pk_bf16_f32 v23, v28, v29
	global_store_dwordx4 v[18:19], v[20:23], off offset:256
	v_add_u32_e32 v18, 0xffffe090, v2
	v_lshrrev_b32_e32 v5, 2, v18
	v_add_u32_e32 v5, 4, v5
	v_cndmask_b32_e32 v5, v5, v3, vcc
	v_mad_i64_i32 v[20:21], s[26:27], v5, s58, v[12:13]
	v_lshl_add_u64 v[174:175], v[20:21], 0, v[14:15]
	v_ashrrev_i32_e32 v19, 31, v18
	v_lshlrev_b64 v[18:19], 12, v[18:19]
	v_add_co_u32_e32 v178, vcc, s67, v174
	v_lshl_add_u64 v[18:19], s[24:25], 0, v[18:19]
	v_lshl_add_u64 v[30:31], v[174:175], 0, s[16:17]
	v_addc_co_u32_e32 v179, vcc, 0, v175, vcc
	v_lshl_add_u64 v[176:177], v[18:19], 0, v[16:17]
	global_load_dwordx4 v[18:21], v[174:175], off offset:16
	global_load_dwordx4 v[22:25], v[174:175], off
	global_load_dwordx4 v[26:29], v[178:179], off
	s_nop 0
	global_load_dwordx4 v[30:33], v[30:31], off offset:16
	s_movk_i32 s26, 0x1f60
	v_cmp_gt_i32_e32 vcc, s26, v2
	s_waitcnt vmcnt(1)
	v_pk_add_f32 v[24:25], v[24:25], v[28:29]
	s_waitcnt vmcnt(0)
	v_pk_add_f32 v[20:21], v[20:21], v[32:33]
	v_pk_add_f32 v[18:19], v[18:19], v[30:31]
	v_pk_add_f32 v[22:23], v[22:23], v[26:27]
	v_pk_mul_f32 v[20:21], v[20:21], 0.5 op_sel_hi:[1,0]
	v_pk_mul_f32 v[18:19], v[18:19], 0.5 op_sel_hi:[1,0]
	v_pk_mul_f32 v[24:25], v[24:25], 0.5 op_sel_hi:[1,0]
	v_pk_mul_f32 v[22:23], v[22:23], 0.5 op_sel_hi:[1,0]
	v_pk_mul_f32 v[26:27], v[76:77], v[20:21]
	v_pk_mul_f32 v[20:21], v[74:75], v[18:19]
	v_pk_mul_f32 v[24:25], v[80:81], v[24:25]
	v_pk_mul_f32 v[22:23], v[78:79], v[22:23]
	v_lshl_add_u64 v[30:31], v[174:175], 0, s[18:19]
	v_cvt_pk_bf16_f32 v18, v22, v23
	v_cvt_pk_bf16_f32 v19, v24, v25
	v_cvt_pk_bf16_f32 v20, v20, v21
	v_cvt_pk_bf16_f32 v21, v26, v27
	global_store_dwordx4 v[176:177], v[18:21], off
	global_load_dwordx4 v[18:21], v[174:175], off offset:528
	s_nop 0
	global_load_dwordx4 v[22:25], v[174:175], off offset:512
	global_load_dwordx4 v[26:29], v[178:179], off offset:512
	s_nop 0
	global_load_dwordx4 v[30:33], v[30:31], off offset:16
	s_waitcnt vmcnt(1)
	v_pk_add_f32 v[22:23], v[22:23], v[26:27]
	s_waitcnt vmcnt(0)
; __device__ __forceinline__ unsigned cvt_pk_bf16(float lo, float hi) { unsigned r; asm volatile("v_cvt_pk_bf16_f32 %0, %1, %2" : "=v"(r) : "v"(lo), "v"(hi)); return r; }
;     __device__ __forceinline__ void operator()(const f32x4 (&acc)[2][2][4][2], const Unit& u, int wr, int wc, int fr, int fq) const {
;     ...
; #pragma unroll
;             for (int ai = 0; ai < 2; ++ai)
; #pragma unroll
;                 for (int m = 0; m < 4; ++m) {
;                     const int row = row0 + ai * HALF + m * 16;
;                     const float* gp = gate + (size_t)modrow_of(row) * NMOD + col0;
;                     bf16_t* op = (bf16_t*)((char*)X + SLAB_MINUS_X) + ((size_t)u.kp * MS + (row - MP)) * DM + col0;
; #pragma unroll
;                     for (int bj = 0; bj < 2; ++bj) {
;                         const f32x4 g0 = (*(const f32x4*)(gp + bj * HALF) + *(const f32x4*)(gp + MODSB_DELTA + bj * HALF)) * coef, g1 = (*(const f32x4*)(gp + bj * HALF + 4) + *(const f32x4*)(gp + MODSB_DELTA + bj * HALF + 4)) * coef;
;                         const f32x4 o0 = g0 * acc[ai][bj][m][0], o1 = g1 * acc[ai][bj][m][1];
;                         u32x4 w; w.x = cvt_pk_bf16(o0[0], o0[1]); w.y = cvt_pk_bf16(o0[2], o0[3]); w.z = cvt_pk_bf16(o1[0], o1[1]); w.w = cvt_pk_bf16(o1[2], o1[3]);
;                         *(u32x4*)(op + bj * HALF) = w;
;                     }
;                     if (m & 1) asm volatile("" ::: "memory");
;                 }
	v_pk_add_f32 v[20:21], v[20:21], v[32:33]
	v_pk_add_f32 v[18:19], v[18:19], v[30:31]
	v_pk_add_f32 v[24:25], v[24:25], v[28:29]
	v_pk_mul_f32 v[22:23], v[22:23], 0.5 op_sel_hi:[1,0]
	v_pk_mul_f32 v[20:21], v[20:21], 0.5 op_sel_hi:[1,0]
	v_pk_mul_f32 v[18:19], v[18:19], 0.5 op_sel_hi:[1,0]
	v_pk_mul_f32 v[24:25], v[24:25], 0.5 op_sel_hi:[1,0]
	v_pk_mul_f32 v[22:23], v[70:71], v[22:23]
	v_pk_mul_f32 v[26:27], v[68:69], v[20:21]
	v_pk_mul_f32 v[20:21], v[66:67], v[18:19]
	v_cvt_pk_bf16_f32 v18, v22, v23
	v_pk_mul_f32 v[24:25], v[72:73], v[24:25]
	s_nop 0
	v_cvt_pk_bf16_f32 v19, v24, v25
	v_cvt_pk_bf16_f32 v20, v20, v21
	v_cvt_pk_bf16_f32 v21, v26, v27
	global_store_dwordx4 v[176:177], v[18:21], off offset:256
	s_nop 1
	v_add_u32_e32 v18, 0xffffe0a0, v2
	v_lshrrev_b32_e32 v5, 2, v18
	v_or_b32_e32 v5, 4, v5
	v_cndmask_b32_e32 v5, v5, v3, vcc
	v_mad_i64_i32 v[20:21], s[26:27], v5, s58, v[12:13]
	v_lshl_add_u64 v[32:33], v[20:21], 0, v[14:15]
	v_add_co_u32_e32 v178, vcc, s67, v32
	v_lshl_add_u64 v[174:175], v[32:33], 0, s[16:17]
	s_nop 0
	v_addc_co_u32_e32 v179, vcc, 0, v33, vcc
	global_load_dwordx4 v[20:23], v[32:33], off offset:16
	global_load_dwordx4 v[24:27], v[32:33], off
	global_load_dwordx4 v[28:31], v[178:179], off
	s_nop 0
	global_load_dwordx4 v[174:177], v[174:175], off offset:16
	v_ashrrev_i32_e32 v19, 31, v18
	v_lshlrev_b64 v[18:19], 12, v[18:19]
	v_lshl_add_u64 v[18:19], s[24:25], 0, v[18:19]
	v_lshl_add_u64 v[18:19], v[18:19], 0, v[16:17]
	s_movk_i32 s26, 0x1f50
	v_cmp_gt_i32_e32 vcc, s26, v2
	s_waitcnt vmcnt(1)
	v_pk_add_f32 v[26:27], v[26:27], v[30:31]
	s_waitcnt vmcnt(0)
	v_pk_add_f32 v[22:23], v[22:23], v[176:177]
	v_pk_add_f32 v[20:21], v[20:21], v[174:175]
	v_pk_add_f32 v[24:25], v[24:25], v[28:29]
	v_pk_mul_f32 v[22:23], v[22:23], 0.5 op_sel_hi:[1,0]
	v_pk_mul_f32 v[20:21], v[20:21], 0.5 op_sel_hi:[1,0]
	v_pk_mul_f32 v[26:27], v[26:27], 0.5 op_sel_hi:[1,0]
	v_pk_mul_f32 v[24:25], v[24:25], 0.5 op_sel_hi:[1,0]
	v_pk_mul_f32 v[28:29], v[60:61], v[22:23]
	v_pk_mul_f32 v[22:23], v[58:59], v[20:21]
	v_pk_mul_f32 v[26:27], v[64:65], v[26:27]
	v_pk_mul_f32 v[24:25], v[62:63], v[24:25]
	s_nop 0
	v_cvt_pk_bf16_f32 v20, v24, v25
	v_cvt_pk_bf16_f32 v21, v26, v27
	v_cvt_pk_bf16_f32 v22, v22, v23
	v_cvt_pk_bf16_f32 v23, v28, v29
	global_store_dwordx4 v[18:19], v[20:23], off
	global_load_dwordx4 v[20:23], v[32:33], off offset:528
	s_nop 0
	global_load_dwordx4 v[24:27], v[32:33], off offset:512
	v_lshl_add_u64 v[32:33], v[32:33], 0, s[18:19]
	global_load_dwordx4 v[28:31], v[178:179], off offset:512
	global_load_dwordx4 v[174:177], v[32:33], off offset:16
	s_waitcnt vmcnt(1)
	v_pk_add_f32 v[26:27], v[26:27], v[30:31]
	s_waitcnt vmcnt(0)
	v_pk_add_f32 v[22:23], v[22:23], v[176:177]
	v_pk_add_f32 v[20:21], v[20:21], v[174:175]
	v_pk_add_f32 v[24:25], v[24:25], v[28:29]
	v_pk_mul_f32 v[22:23], v[22:23], 0.5 op_sel_hi:[1,0]
	v_pk_mul_f32 v[20:21], v[20:21], 0.5 op_sel_hi:[1,0]
	v_pk_mul_f32 v[26:27], v[26:27], 0.5 op_sel_hi:[1,0]
	v_pk_mul_f32 v[24:25], v[24:25], 0.5 op_sel_hi:[1,0]
	v_pk_mul_f32 v[28:29], v[52:53], v[22:23]
	v_pk_mul_f32 v[22:23], v[50:51], v[20:21]
	v_pk_mul_f32 v[26:27], v[56:57], v[26:27]
	v_pk_mul_f32 v[24:25], v[54:55], v[24:25]
	s_nop 0
	v_cvt_pk_bf16_f32 v20, v24, v25
	v_cvt_pk_bf16_f32 v21, v26, v27
	v_cvt_pk_bf16_f32 v22, v22, v23
	v_cvt_pk_bf16_f32 v23, v28, v29
	global_store_dwordx4 v[18:19], v[20:23], off offset:256
	v_add_u32_e32 v18, 0xffffe0b0, v2
	v_lshrrev_b32_e32 v5, 2, v18
	v_add_u32_e32 v5, 4, v5
	v_cndmask_b32_e32 v3, v5, v3, vcc
	v_mad_i64_i32 v[12:13], s[26:27], v3, s58, v[12:13]
	v_lshl_add_u64 v[30:31], v[12:13], 0, v[14:15]
	v_ashrrev_i32_e32 v19, 31, v18
	v_lshlrev_b64 v[12:13], 12, v[18:19]
	v_add_co_u32_e32 v32, vcc, s67, v30
	v_lshl_add_u64 v[12:13], s[24:25], 0, v[12:13]
	v_lshl_add_u64 v[26:27], v[30:31], 0, s[16:17]
	v_addc_co_u32_e32 v33, vcc, 0, v31, vcc
	v_lshl_add_u64 v[12:13], v[12:13], 0, v[16:17]
	global_load_dwordx4 v[14:17], v[30:31], off offset:16
	global_load_dwordx4 v[18:21], v[30:31], off
	global_load_dwordx4 v[22:25], v[32:33], off
	s_nop 0
	global_load_dwordx4 v[26:29], v[26:27], off offset:16
	s_waitcnt vmcnt(1)
	v_pk_add_f32 v[20:21], v[20:21], v[24:25]
	s_waitcnt vmcnt(0)
	v_pk_add_f32 v[16:17], v[16:17], v[28:29]
	v_pk_add_f32 v[14:15], v[14:15], v[26:27]
	v_pk_add_f32 v[18:19], v[18:19], v[22:23]
	v_pk_mul_f32 v[16:17], v[16:17], 0.5 op_sel_hi:[1,0]
	v_pk_mul_f32 v[14:15], v[14:15], 0.5 op_sel_hi:[1,0]
	v_pk_mul_f32 v[20:21], v[20:21], 0.5 op_sel_hi:[1,0]
	v_pk_mul_f32 v[18:19], v[18:19], 0.5 op_sel_hi:[1,0]
	v_pk_mul_f32 v[22:23], v[44:45], v[16:17]
	v_pk_mul_f32 v[16:17], v[42:43], v[14:15]
	v_pk_mul_f32 v[20:21], v[48:49], v[20:21]
	v_pk_mul_f32 v[18:19], v[46:47], v[18:19]
	v_lshl_add_u64 v[26:27], v[30:31], 0, s[18:19]
	v_cvt_pk_bf16_f32 v14, v18, v19
	v_cvt_pk_bf16_f32 v15, v20, v21
	v_cvt_pk_bf16_f32 v16, v16, v17
	v_cvt_pk_bf16_f32 v17, v22, v23
	global_store_dwordx4 v[12:13], v[14:17], off
	global_load_dwordx4 v[14:17], v[30:31], off offset:528
	s_nop 0
	global_load_dwordx4 v[18:21], v[30:31], off offset:512
	global_load_dwordx4 v[22:25], v[32:33], off offset:512
	s_nop 0
	global_load_dwordx4 v[26:29], v[26:27], off offset:16
	s_waitcnt vmcnt(1)
	v_pk_add_f32 v[20:21], v[20:21], v[24:25]
	s_waitcnt vmcnt(0)
	v_pk_add_f32 v[16:17], v[16:17], v[28:29]
	v_pk_add_f32 v[14:15], v[14:15], v[26:27]
	v_pk_add_f32 v[18:19], v[18:19], v[22:23]
	v_pk_mul_f32 v[16:17], v[16:17], 0.5 op_sel_hi:[1,0]
	v_pk_mul_f32 v[14:15], v[14:15], 0.5 op_sel_hi:[1,0]
	v_pk_mul_f32 v[20:21], v[20:21], 0.5 op_sel_hi:[1,0]
	v_pk_mul_f32 v[18:19], v[18:19], 0.5 op_sel_hi:[1,0]
	v_pk_mul_f32 v[22:23], v[36:37], v[16:17]
	v_pk_mul_f32 v[16:17], v[34:35], v[14:15]
	v_pk_mul_f32 v[20:21], v[40:41], v[20:21]
	v_pk_mul_f32 v[18:19], v[38:39], v[18:19]
	s_nop 0
	v_cvt_pk_bf16_f32 v14, v18, v19
	v_cvt_pk_bf16_f32 v15, v20, v21
	v_cvt_pk_bf16_f32 v16, v16, v17
	v_cvt_pk_bf16_f32 v17, v22, v23
	global_store_dwordx4 v[12:13], v[14:17], off offset:256
	s_cbranch_execz .LBB0_509

; __device__ __forceinline__ unsigned cvt_pk_bf16(float lo, float hi) { unsigned r; asm volatile("v_cvt_pk_bf16_f32 %0, %1, %2" : "=v"(r) : "v"(lo), "v"(hi)); return r; }
;     __device__ __forceinline__ void operator()(const f32x4 (&acc)[2][2][4][2], const Unit& u, int wr, int wc, int fr, int fq) const {
;     ...
;         if (u.kp < 0) {
;             const float* gp = gate + (size_t)(u.pm >> 3) * NMOD + col0;
;             f32x4 gg[2][2];
; #pragma unroll
;             for (int bj = 0; bj < 2; ++bj)
; #pragma unroll
;                 for (int n = 0; n < 2; ++n) gg[bj][n] = (*(const f32x4*)(gp + bj * HALF + 4 * n) + *(const f32x4*)(gp + MODSB_DELTA + bj * HALF + 4 * n)) * coef;
; #pragma unroll
;             for (int ai = 0; ai < 2; ++ai)
; #pragma unroll
;                 for (int m = 0; m < 4; ++m) {
;                     const int row = row0 + ai * HALF + m * 16;
;                     bf16_t* xp = X + (size_t)row * DM + col0;
; #pragma unroll
;                     for (int bj = 0; bj < 2; ++bj) {
;                         f32x4 b0, b1;
;                         if (BASE16) { const u32x4 bv = *(const u32x4*)(xp + bj * HALF);
;                             b0 = (f32x4){__builtin_bit_cast(float, bv.x << 16), __builtin_bit_cast(float, bv.x & 0xffff0000u), __builtin_bit_cast(float, bv.y << 16), __builtin_bit_cast(float, bv.y & 0xffff0000u)};
;                             b1 = (f32x4){__builtin_bit_cast(float, bv.z << 16), __builtin_bit_cast(float, bv.z & 0xffff0000u), __builtin_bit_cast(float, bv.w << 16), __builtin_bit_cast(float, bv.w & 0xffff0000u)}; }
;                         else { const float* bp = base32 + (size_t)row * DM + col0 + bj * HALF; b0 = __builtin_nontemporal_load((const f32x4*)bp); b1 = __builtin_nontemporal_load((const f32x4*)(bp + 4)); }
;                         const f32x4 o0 = b0 + gg[bj][0] * acc[ai][bj][m][0], o1 = b1 + gg[bj][1] * acc[ai][bj][m][1];
;                         u32x4 w; w.x = cvt_pk_bf16(o0[0], o0[1]); w.y = cvt_pk_bf16(o0[2], o0[3]); w.z = cvt_pk_bf16(o1[0], o1[1]); w.w = cvt_pk_bf16(o1[2], o1[3]);
;                         *(u32x4*)(xp + bj * HALF) = w;
;                     }
;                     if (m & 1) asm volatile("" ::: "memory");
;                 }
.LBB0_509:
	s_ashr_i32 s24, s75, 3
	s_mul_hi_i32 s25, s24, 0x12000
	s_mul_i32 s24, s24, 0x12000
	s_add_u32 s24, s10, s24
	s_addc_u32 s25, s11, s25
	v_lshlrev_b64 v[28:29], 2, v[10:11]
	v_lshl_add_u64 v[174:175], s[24:25], 0, v[28:29]
	v_add_co_u32_e32 v176, vcc, s67, v174
	v_lshl_add_u64 v[24:25], v[174:175], 0, s[16:17]
	s_nop 0
	v_addc_co_u32_e32 v177, vcc, 0, v175, vcc
	global_load_dwordx4 v[12:15], v[174:175], off offset:16
	global_load_dwordx4 v[16:19], v[174:175], off
	global_load_dwordx4 v[20:23], v[176:177], off
	global_load_dwordx4 v[30:33], v[24:25], off offset:16
	v_lshl_add_u64 v[178:179], v[174:175], 0, s[18:19]
	v_ashrrev_i32_e32 v3, 31, v2
	v_lshlrev_b64 v[10:11], 1, v[10:11]
	v_ashrrev_i32_e32 v9, 31, v8
	v_ashrrev_i32_e32 v7, 31, v6
	v_ashrrev_i32_e32 v5, 31, v4
	s_waitcnt vmcnt(0)
	v_pk_add_f32 v[18:19], v[18:19], v[22:23]
	v_pk_add_f32 v[16:17], v[16:17], v[20:21]
	v_pk_add_f32 v[14:15], v[14:15], v[32:33]
	v_pk_add_f32 v[12:13], v[12:13], v[30:31]
	v_pk_mul_f32 v[24:25], v[18:19], 0.5 op_sel_hi:[1,0]
	v_pk_mul_f32 v[26:27], v[16:17], 0.5 op_sel_hi:[1,0]
	v_pk_mul_f32 v[20:21], v[14:15], 0.5 op_sel_hi:[1,0]
	v_pk_mul_f32 v[22:23], v[12:13], 0.5 op_sel_hi:[1,0]
	global_load_dwordx4 v[12:15], v[174:175], off offset:528
	global_load_dwordx4 v[16:19], v[174:175], off offset:512
	global_load_dwordx4 v[30:33], v[176:177], off offset:512
	s_nop 0
	global_load_dwordx4 v[174:177], v[178:179], off offset:16
	s_waitcnt vmcnt(1)
	v_pk_add_f32 v[18:19], v[18:19], v[32:33]
	v_pk_add_f32 v[30:31], v[16:17], v[30:31]
	v_pk_mul_f32 v[16:17], v[18:19], 0.5 op_sel_hi:[1,0]
	v_pk_mul_f32 v[18:19], v[30:31], 0.5 op_sel_hi:[1,0]
	s_waitcnt vmcnt(0)
	v_pk_add_f32 v[14:15], v[14:15], v[176:177]
	v_pk_add_f32 v[30:31], v[12:13], v[174:175]
	v_pk_mul_f32 v[12:13], v[14:15], 0.5 op_sel_hi:[1,0]
	v_pk_mul_f32 v[14:15], v[30:31], 0.5 op_sel_hi:[1,0]
	v_lshlrev_b64 v[30:31], 12, v[2:3]
	v_lshl_add_u64 v[30:31], s[8:9], 0, v[30:31]
	v_lshl_add_u64 v[178:179], v[30:31], 0, v[10:11]
	v_lshlrev_b64 v[30:31], 13, v[2:3]
	v_lshl_add_u64 v[30:31], s[36:37], 0, v[30:31]
	v_lshl_add_u64 v[180:181], v[30:31], 0, v[28:29]
	global_load_dwordx4 v[30:33], v[180:181], off offset:16 nt
	global_load_dwordx4 v[174:177], v[180:181], off nt
	s_waitcnt vmcnt(1)
	v_pk_fma_f32 v[156:157], v[156:157], v[20:21], v[32:33]
	v_pk_fma_f32 v[32:33], v[154:155], v[22:23], v[30:31]
	s_waitcnt vmcnt(0)
	v_pk_fma_f32 v[160:161], v[160:161], v[24:25], v[176:177]
	v_pk_fma_f32 v[158:159], v[158:159], v[26:27], v[174:175]
	s_nop 0
	v_cvt_pk_bf16_f32 v30, v158, v159
	v_cvt_pk_bf16_f32 v31, v160, v161
	v_cvt_pk_bf16_f32 v32, v32, v33
	v_cvt_pk_bf16_f32 v33, v156, v157
	global_store_dwordx4 v[178:179], v[30:33], off
	global_load_dwordx4 v[30:33], v[180:181], off offset:528 nt
	s_nop 0
	global_load_dwordx4 v[154:157], v[180:181], off offset:512 nt
	s_waitcnt vmcnt(1)
	v_pk_fma_f32 v[148:149], v[148:149], v[12:13], v[32:33]
	s_waitcnt vmcnt(0)
	v_pk_fma_f32 v[152:153], v[152:153], v[16:17], v[156:157]
	v_pk_fma_f32 v[150:151], v[150:151], v[18:19], v[154:155]
	v_pk_fma_f32 v[32:33], v[146:147], v[14:15], v[30:31]
	v_cvt_pk_bf16_f32 v30, v150, v151
	v_cvt_pk_bf16_f32 v31, v152, v153
	s_nop 0
	v_cvt_pk_bf16_f32 v32, v32, v33
	v_cvt_pk_bf16_f32 v33, v148, v149
	global_store_dwordx4 v[178:179], v[30:33], off offset:256
	s_nop 1
	v_lshlrev_b64 v[30:31], 12, v[8:9]
	v_lshlrev_b64 v[8:9], 13, v[8:9]
	v_lshl_add_u64 v[8:9], s[36:37], 0, v[8:9]
	v_lshl_add_u64 v[30:31], s[8:9], 0, v[30:31]
	v_lshl_add_u64 v[8:9], v[8:9], 0, v[28:29]
	v_lshl_add_u64 v[150:151], v[30:31], 0, v[10:11]
	global_load_dwordx4 v[30:33], v[8:9], off offset:16 nt
	global_load_dwordx4 v[146:149], v[8:9], off nt
	s_waitcnt vmcnt(1)
	v_pk_fma_f32 v[140:141], v[140:141], v[20:21], v[32:33]
	v_pk_fma_f32 v[32:33], v[138:139], v[22:23], v[30:31]
	s_waitcnt vmcnt(0)
	v_pk_fma_f32 v[144:145], v[144:145], v[24:25], v[148:149]
	v_pk_fma_f32 v[142:143], v[142:143], v[26:27], v[146:147]
	s_nop 0
	v_cvt_pk_bf16_f32 v30, v142, v143
	v_cvt_pk_bf16_f32 v31, v144, v145
	v_cvt_pk_bf16_f32 v32, v32, v33
	v_cvt_pk_bf16_f32 v33, v140, v141
	global_store_dwordx4 v[150:151], v[30:33], off
	global_load_dwordx4 v[30:33], v[8:9], off offset:528 nt
	s_nop 0
	global_load_dwordx4 v[138:141], v[8:9], off offset:512 nt
	s_waitcnt vmcnt(1)
	v_pk_fma_f32 v[132:133], v[132:133], v[12:13], v[32:33]
	s_waitcnt vmcnt(0)
	v_pk_fma_f32 v[8:9], v[136:137], v[16:17], v[140:141]
	v_pk_fma_f32 v[134:135], v[134:135], v[18:19], v[138:139]
	v_pk_fma_f32 v[32:33], v[130:131], v[14:15], v[30:31]
	v_cvt_pk_bf16_f32 v30, v134, v135
	v_cvt_pk_bf16_f32 v31, v8, v9
	v_lshlrev_b64 v[8:9], 12, v[6:7]
	v_lshlrev_b64 v[6:7], 13, v[6:7]
	v_cvt_pk_bf16_f32 v32, v32, v33
	v_cvt_pk_bf16_f32 v33, v132, v133
	global_store_dwordx4 v[150:151], v[30:33], off offset:256
	v_lshl_add_u64 v[6:7], s[36:37], 0, v[6:7]
	v_lshl_add_u64 v[8:9], s[8:9], 0, v[8:9]
	v_lshl_add_u64 v[132:133], v[6:7], 0, v[28:29]
	v_lshl_add_u64 v[130:131], v[8:9], 0, v[10:11]
	global_load_dwordx4 v[6:9], v[132:133], off offset:16 nt
	global_load_dwordx4 v[30:33], v[132:133], off nt
	s_waitcnt vmcnt(1)
	v_pk_fma_f32 v[124:125], v[124:125], v[20:21], v[8:9]
	v_pk_fma_f32 v[8:9], v[122:123], v[22:23], v[6:7]
	s_waitcnt vmcnt(0)
	v_pk_fma_f32 v[32:33], v[128:129], v[24:25], v[32:33]
	v_pk_fma_f32 v[30:31], v[126:127], v[26:27], v[30:31]
	s_nop 0
	v_cvt_pk_bf16_f32 v6, v30, v31
	v_cvt_pk_bf16_f32 v7, v32, v33
	v_cvt_pk_bf16_f32 v8, v8, v9
	v_cvt_pk_bf16_f32 v9, v124, v125
	global_store_dwordx4 v[130:131], v[6:9], off
	global_load_dwordx4 v[6:9], v[132:133], off offset:528 nt
	s_nop 0
	global_load_dwordx4 v[30:33], v[132:133], off offset:512 nt
	s_waitcnt vmcnt(1)
; __device__ __forceinline__ unsigned cvt_pk_bf16(float lo, float hi) { unsigned r; asm volatile("v_cvt_pk_bf16_f32 %0, %1, %2" : "=v"(r) : "v"(lo), "v"(hi)); return r; }
;     __device__ __forceinline__ void operator()(const f32x4 (&acc)[2][2][4][2], const Unit& u, int wr, int wc, int fr, int fq) const {
;     ...
;         if (u.kp < 0) {
;             const float* gp = gate + (size_t)(u.pm >> 3) * NMOD + col0;
;             f32x4 gg[2][2];
; #pragma unroll
;             for (int bj = 0; bj < 2; ++bj)
; #pragma unroll
;                 for (int n = 0; n < 2; ++n) gg[bj][n] = (*(const f32x4*)(gp + bj * HALF + 4 * n) + *(const f32x4*)(gp + MODSB_DELTA + bj * HALF + 4 * n)) * coef;
; #pragma unroll
;             for (int ai = 0; ai < 2; ++ai)
; #pragma unroll
;                 for (int m = 0; m < 4; ++m) {
;                     const int row = row0 + ai * HALF + m * 16;
;                     bf16_t* xp = X + (size_t)row * DM + col0;
; #pragma unroll
;                     for (int bj = 0; bj < 2; ++bj) {
;                         f32x4 b0, b1;
;                         if (BASE16) { const u32x4 bv = *(const u32x4*)(xp + bj * HALF);
;                             b0 = (f32x4){__builtin_bit_cast(float, bv.x << 16), __builtin_bit_cast(float, bv.x & 0xffff0000u), __builtin_bit_cast(float, bv.y << 16), __builtin_bit_cast(float, bv.y & 0xffff0000u)};
;                             b1 = (f32x4){__builtin_bit_cast(float, bv.z << 16), __builtin_bit_cast(float, bv.z & 0xffff0000u), __builtin_bit_cast(float, bv.w << 16), __builtin_bit_cast(float, bv.w & 0xffff0000u)}; }
;                         else { const float* bp = base32 + (size_t)row * DM + col0 + bj * HALF; b0 = __builtin_nontemporal_load((const f32x4*)bp); b1 = __builtin_nontemporal_load((const f32x4*)(bp + 4)); }
;                         const f32x4 o0 = b0 + gg[bj][0] * acc[ai][bj][m][0], o1 = b1 + gg[bj][1] * acc[ai][bj][m][1];
;                         u32x4 w; w.x = cvt_pk_bf16(o0[0], o0[1]); w.y = cvt_pk_bf16(o0[2], o0[3]); w.z = cvt_pk_bf16(o1[0], o1[1]); w.w = cvt_pk_bf16(o1[2], o1[3]);
;                         *(u32x4*)(xp + bj * HALF) = w;
;                     }
;                     if (m & 1) asm volatile("" ::: "memory");
;                 }
	v_pk_fma_f32 v[116:117], v[116:117], v[12:13], v[8:9]
	s_waitcnt vmcnt(0)
	v_pk_fma_f32 v[32:33], v[120:121], v[16:17], v[32:33]
	v_pk_fma_f32 v[30:31], v[118:119], v[18:19], v[30:31]
	v_pk_fma_f32 v[8:9], v[114:115], v[14:15], v[6:7]
	v_cvt_pk_bf16_f32 v6, v30, v31
	v_cvt_pk_bf16_f32 v7, v32, v33
	s_nop 0
	v_cvt_pk_bf16_f32 v8, v8, v9
	v_cvt_pk_bf16_f32 v9, v116, v117
	global_store_dwordx4 v[130:131], v[6:9], off offset:256
	s_nop 1
	v_lshlrev_b64 v[6:7], 12, v[4:5]
	v_lshlrev_b64 v[4:5], 13, v[4:5]
	v_lshl_add_u64 v[4:5], s[36:37], 0, v[4:5]
	v_lshl_add_u64 v[6:7], s[8:9], 0, v[6:7]
	v_lshl_add_u64 v[114:115], v[4:5], 0, v[28:29]
	v_lshl_add_u64 v[8:9], v[6:7], 0, v[10:11]
	global_load_dwordx4 v[4:7], v[114:115], off offset:16 nt
	global_load_dwordx4 v[30:33], v[114:115], off nt
	s_waitcnt vmcnt(1)
	v_pk_fma_f32 v[108:109], v[108:109], v[20:21], v[6:7]
	v_pk_fma_f32 v[6:7], v[106:107], v[22:23], v[4:5]
	s_waitcnt vmcnt(0)
	v_pk_fma_f32 v[32:33], v[112:113], v[24:25], v[32:33]
	v_pk_fma_f32 v[30:31], v[110:111], v[26:27], v[30:31]
	s_nop 0
	v_cvt_pk_bf16_f32 v4, v30, v31
	v_cvt_pk_bf16_f32 v5, v32, v33
	v_cvt_pk_bf16_f32 v6, v6, v7
	v_cvt_pk_bf16_f32 v7, v108, v109
	global_store_dwordx4 v[8:9], v[4:7], off
	global_load_dwordx4 v[4:7], v[114:115], off offset:528 nt
	s_nop 0
	global_load_dwordx4 v[30:33], v[114:115], off offset:512 nt
	s_waitcnt vmcnt(1)
	v_pk_fma_f32 v[100:101], v[100:101], v[12:13], v[6:7]
	s_waitcnt vmcnt(0)
	v_pk_fma_f32 v[30:31], v[102:103], v[18:19], v[30:31]
	v_pk_fma_f32 v[6:7], v[98:99], v[14:15], v[4:5]
	v_cvt_pk_bf16_f32 v4, v30, v31
	v_pk_fma_f32 v[32:33], v[104:105], v[16:17], v[32:33]
	s_nop 0
	v_cvt_pk_bf16_f32 v5, v32, v33
	v_cvt_pk_bf16_f32 v6, v6, v7
	v_cvt_pk_bf16_f32 v7, v100, v101
	global_store_dwordx4 v[8:9], v[4:7], off offset:256
	s_nop 1
	v_add_u32_e32 v4, 0x80, v2
	v_ashrrev_i32_e32 v5, 31, v4
	v_lshlrev_b64 v[6:7], 12, v[4:5]
	v_lshlrev_b64 v[4:5], 13, v[4:5]
	v_lshl_add_u64 v[4:5], s[36:37], 0, v[4:5]
	v_lshl_add_u64 v[6:7], s[8:9], 0, v[6:7]
	v_lshl_add_u64 v[98:99], v[4:5], 0, v[28:29]
	v_lshl_add_u64 v[8:9], v[6:7], 0, v[10:11]
	global_load_dwordx4 v[4:7], v[98:99], off offset:16 nt
	global_load_dwordx4 v[30:33], v[98:99], off nt
	s_waitcnt vmcnt(1)
	v_pk_fma_f32 v[92:93], v[92:93], v[20:21], v[6:7]
	v_pk_fma_f32 v[6:7], v[90:91], v[22:23], v[4:5]
	s_waitcnt vmcnt(0)
	v_pk_fma_f32 v[32:33], v[96:97], v[24:25], v[32:33]
	v_pk_fma_f32 v[30:31], v[94:95], v[26:27], v[30:31]
	s_nop 0
	v_cvt_pk_bf16_f32 v4, v30, v31
	v_cvt_pk_bf16_f32 v5, v32, v33
	v_cvt_pk_bf16_f32 v6, v6, v7
	v_cvt_pk_bf16_f32 v7, v92, v93
	global_store_dwordx4 v[8:9], v[4:7], off
	global_load_dwordx4 v[4:7], v[98:99], off offset:528 nt
	s_nop 0
	global_load_dwordx4 v[30:33], v[98:99], off offset:512 nt
	s_waitcnt vmcnt(1)
	v_pk_fma_f32 v[84:85], v[84:85], v[12:13], v[6:7]
	s_waitcnt vmcnt(0)
	v_pk_fma_f32 v[30:31], v[86:87], v[18:19], v[30:31]
	v_pk_fma_f32 v[6:7], v[82:83], v[14:15], v[4:5]
	v_cvt_pk_bf16_f32 v4, v30, v31
	v_pk_fma_f32 v[32:33], v[88:89], v[16:17], v[32:33]
	s_nop 0
	v_cvt_pk_bf16_f32 v5, v32, v33
	v_cvt_pk_bf16_f32 v6, v6, v7
	v_cvt_pk_bf16_f32 v7, v84, v85
	global_store_dwordx4 v[8:9], v[4:7], off offset:256
	s_nop 1
	v_add_u32_e32 v4, 0x90, v2
	v_ashrrev_i32_e32 v5, 31, v4
	v_lshlrev_b64 v[6:7], 12, v[4:5]
	v_lshlrev_b64 v[4:5], 13, v[4:5]
	v_lshl_add_u64 v[4:5], s[36:37], 0, v[4:5]
	v_lshl_add_u64 v[6:7], s[8:9], 0, v[6:7]
	v_lshl_add_u64 v[82:83], v[4:5], 0, v[28:29]
	v_lshl_add_u64 v[8:9], v[6:7], 0, v[10:11]
	global_load_dwordx4 v[4:7], v[82:83], off offset:16 nt
	global_load_dwordx4 v[30:33], v[82:83], off nt
	s_waitcnt vmcnt(1)
	v_pk_fma_f32 v[76:77], v[76:77], v[20:21], v[6:7]
	v_pk_fma_f32 v[6:7], v[74:75], v[22:23], v[4:5]
	s_waitcnt vmcnt(0)
; __device__ __forceinline__ unsigned cvt_pk_bf16(float lo, float hi) { unsigned r; asm volatile("v_cvt_pk_bf16_f32 %0, %1, %2" : "=v"(r) : "v"(lo), "v"(hi)); return r; }
;     __device__ __forceinline__ void operator()(const f32x4 (&acc)[2][2][4][2], const Unit& u, int wr, int wc, int fr, int fq) const {
;     ...
;         if (u.kp < 0) {
;             const float* gp = gate + (size_t)(u.pm >> 3) * NMOD + col0;
;             f32x4 gg[2][2];
; #pragma unroll
;             for (int bj = 0; bj < 2; ++bj)
; #pragma unroll
;                 for (int n = 0; n < 2; ++n) gg[bj][n] = (*(const f32x4*)(gp + bj * HALF + 4 * n) + *(const f32x4*)(gp + MODSB_DELTA + bj * HALF + 4 * n)) * coef;
; #pragma unroll
;             for (int ai = 0; ai < 2; ++ai)
; #pragma unroll
;                 for (int m = 0; m < 4; ++m) {
;                     const int row = row0 + ai * HALF + m * 16;
;                     bf16_t* xp = X + (size_t)row * DM + col0;
; #pragma unroll
;                     for (int bj = 0; bj < 2; ++bj) {
;                         f32x4 b0, b1;
;                         if (BASE16) { const u32x4 bv = *(const u32x4*)(xp + bj * HALF);
;                             b0 = (f32x4){__builtin_bit_cast(float, bv.x << 16), __builtin_bit_cast(float, bv.x & 0xffff0000u), __builtin_bit_cast(float, bv.y << 16), __builtin_bit_cast(float, bv.y & 0xffff0000u)};
;                             b1 = (f32x4){__builtin_bit_cast(float, bv.z << 16), __builtin_bit_cast(float, bv.z & 0xffff0000u), __builtin_bit_cast(float, bv.w << 16), __builtin_bit_cast(float, bv.w & 0xffff0000u)}; }
;                         else { const float* bp = base32 + (size_t)row * DM + col0 + bj * HALF; b0 = __builtin_nontemporal_load((const f32x4*)bp); b1 = __builtin_nontemporal_load((const f32x4*)(bp + 4)); }
;                         const f32x4 o0 = b0 + gg[bj][0] * acc[ai][bj][m][0], o1 = b1 + gg[bj][1] * acc[ai][bj][m][1];
;                         u32x4 w; w.x = cvt_pk_bf16(o0[0], o0[1]); w.y = cvt_pk_bf16(o0[2], o0[3]); w.z = cvt_pk_bf16(o1[0], o1[1]); w.w = cvt_pk_bf16(o1[2], o1[3]);
;                         *(u32x4*)(xp + bj * HALF) = w;
;                     }
;                     if (m & 1) asm volatile("" ::: "memory");
;                 }
	v_pk_fma_f32 v[32:33], v[80:81], v[24:25], v[32:33]
	v_pk_fma_f32 v[30:31], v[78:79], v[26:27], v[30:31]
	s_nop 0
	v_cvt_pk_bf16_f32 v4, v30, v31
	v_cvt_pk_bf16_f32 v5, v32, v33
	v_cvt_pk_bf16_f32 v6, v6, v7
	v_cvt_pk_bf16_f32 v7, v76, v77
	global_store_dwordx4 v[8:9], v[4:7], off
	global_load_dwordx4 v[4:7], v[82:83], off offset:528 nt
	s_nop 0
	global_load_dwordx4 v[30:33], v[82:83], off offset:512 nt
	s_waitcnt vmcnt(1)
	v_pk_fma_f32 v[68:69], v[68:69], v[12:13], v[6:7]
	s_waitcnt vmcnt(0)
	v_pk_fma_f32 v[30:31], v[70:71], v[18:19], v[30:31]
	v_pk_fma_f32 v[6:7], v[66:67], v[14:15], v[4:5]
	v_cvt_pk_bf16_f32 v4, v30, v31
	v_pk_fma_f32 v[32:33], v[72:73], v[16:17], v[32:33]
	s_nop 0
	v_cvt_pk_bf16_f32 v5, v32, v33
	v_cvt_pk_bf16_f32 v6, v6, v7
	v_cvt_pk_bf16_f32 v7, v68, v69
	global_store_dwordx4 v[8:9], v[4:7], off offset:256
	s_nop 1
	v_add_u32_e32 v4, 0xa0, v2
	v_ashrrev_i32_e32 v5, 31, v4
	v_lshlrev_b64 v[6:7], 12, v[4:5]
	v_lshlrev_b64 v[4:5], 13, v[4:5]
	v_lshl_add_u64 v[4:5], s[36:37], 0, v[4:5]
	v_lshl_add_u64 v[6:7], s[8:9], 0, v[6:7]
	v_lshl_add_u64 v[66:67], v[4:5], 0, v[28:29]
	v_lshl_add_u64 v[8:9], v[6:7], 0, v[10:11]
	global_load_dwordx4 v[4:7], v[66:67], off offset:16 nt
	global_load_dwordx4 v[30:33], v[66:67], off nt
	v_add_u32_e32 v2, 0xb0, v2
	v_ashrrev_i32_e32 v3, 31, v2
	s_waitcnt vmcnt(1)
	v_pk_fma_f32 v[60:61], v[60:61], v[20:21], v[6:7]
	v_pk_fma_f32 v[6:7], v[58:59], v[22:23], v[4:5]
	s_waitcnt vmcnt(0)
	v_pk_fma_f32 v[32:33], v[64:65], v[24:25], v[32:33]
	v_pk_fma_f32 v[30:31], v[62:63], v[26:27], v[30:31]
	s_nop 0
	v_cvt_pk_bf16_f32 v4, v30, v31
	v_cvt_pk_bf16_f32 v5, v32, v33
	v_cvt_pk_bf16_f32 v6, v6, v7
	v_cvt_pk_bf16_f32 v7, v60, v61
	global_store_dwordx4 v[8:9], v[4:7], off
	global_load_dwordx4 v[4:7], v[66:67], off offset:528 nt
	s_nop 0
	global_load_dwordx4 v[30:33], v[66:67], off offset:512 nt
	s_waitcnt vmcnt(1)
	v_pk_fma_f32 v[52:53], v[52:53], v[12:13], v[6:7]
	s_waitcnt vmcnt(0)
	v_pk_fma_f32 v[32:33], v[56:57], v[16:17], v[32:33]
	v_pk_fma_f32 v[30:31], v[54:55], v[18:19], v[30:31]
	v_pk_fma_f32 v[6:7], v[50:51], v[14:15], v[4:5]
	v_cvt_pk_bf16_f32 v4, v30, v31
	v_cvt_pk_bf16_f32 v5, v32, v33
	s_nop 0
	v_cvt_pk_bf16_f32 v6, v6, v7
	v_cvt_pk_bf16_f32 v7, v52, v53
	global_store_dwordx4 v[8:9], v[4:7], off offset:256
	s_nop 1
	v_lshlrev_b64 v[4:5], 12, v[2:3]
	v_lshlrev_b64 v[2:3], 13, v[2:3]
	v_lshl_add_u64 v[2:3], s[36:37], 0, v[2:3]
	v_lshl_add_u64 v[4:5], s[8:9], 0, v[4:5]
	v_lshl_add_u64 v[28:29], v[2:3], 0, v[28:29]
	v_lshl_add_u64 v[10:11], v[4:5], 0, v[10:11]
	global_load_dwordx4 v[2:5], v[28:29], off offset:16 nt
	global_load_dwordx4 v[6:9], v[28:29], off nt
	s_waitcnt vmcnt(1)
	v_pk_fma_f32 v[20:21], v[44:45], v[20:21], v[4:5]
	v_pk_fma_f32 v[4:5], v[42:43], v[22:23], v[2:3]
	s_waitcnt vmcnt(0)
	v_pk_fma_f32 v[8:9], v[48:49], v[24:25], v[8:9]
	v_pk_fma_f32 v[6:7], v[46:47], v[26:27], v[6:7]
	s_nop 0
	v_cvt_pk_bf16_f32 v2, v6, v7
	v_cvt_pk_bf16_f32 v3, v8, v9
	v_cvt_pk_bf16_f32 v4, v4, v5
	v_cvt_pk_bf16_f32 v5, v20, v21
	global_store_dwordx4 v[10:11], v[2:5], off
	global_load_dwordx4 v[2:5], v[28:29], off offset:528 nt
	s_nop 0
	global_load_dwordx4 v[6:9], v[28:29], off offset:512 nt
	s_waitcnt vmcnt(1)
	v_pk_fma_f32 v[12:13], v[36:37], v[12:13], v[4:5]
	v_pk_fma_f32 v[4:5], v[34:35], v[14:15], v[2:3]
	s_waitcnt vmcnt(0)
	v_pk_fma_f32 v[8:9], v[40:41], v[16:17], v[8:9]
	v_pk_fma_f32 v[6:7], v[38:39], v[18:19], v[6:7]
	s_nop 0
	v_cvt_pk_bf16_f32 v2, v6, v7
	v_cvt_pk_bf16_f32 v3, v8, v9
	v_cvt_pk_bf16_f32 v4, v4, v5
	v_cvt_pk_bf16_f32 v5, v12, v13
	global_store_dwordx4 v[10:11], v[2:5], off offset:256
	s_and_b64 vcc, exec, s[2:3]
	s_mov_b64 s[2:3], -1
	s_cbranch_vccnz .LBB0_492

; #define GAS __attribute__((address_space(1)))
; #define LAS __attribute__((address_space(3)))
; #define CQ_TICKET() ((taken < maxb) ? (++taken, (int)__hip_atomic_fetch_add(qhead, 1u, __ATOMIC_RELAXED, __HIP_MEMORY_SCOPE_AGENT)) : T_END)
; __device__ __forceinline__ void p0_convert(const P0Item& d, const LAS float* buf, int w, int lane, bool NT) {
;     ...
;         for (int j = 0; j < 2; ++j) { const int n = (lane >> 2) + 16 * j; const LAS float* s = buf + (16 * c) * TPITCH + 32 * w + n;
;             v4u o; o.x = pg8::pk4_fp8(s[0 * TPITCH], s[1 * TPITCH], s[2 * TPITCH], s[3 * TPITCH]); o.y = pg8::pk4_fp8(s[4 * TPITCH], s[5 * TPITCH], s[6 * TPITCH], s[7 * TPITCH]);
;             o.z = pg8::pk4_fp8(s[8 * TPITCH], s[9 * TPITCH], s[10 * TPITCH], s[11 * TPITCH]); o.w = pg8::pk4_fp8(s[12 * TPITCH], s[13 * TPITCH], s[14 * TPITCH], s[15 * TPITCH]);
;             if (NT) __builtin_nontemporal_store(o, (v4u*)(d.dst + (size_t)n * d.ldkb + 16 * c)); else *(GAS v4u*)(d.dst + (size_t)n * d.ldkb + 16 * c) = o; }
; __device__ __forceinline__ void conv_queue(Frame& F, const Args& A, int qw, int vsplit, int vskip, int nv, int maxb) {
;     ...
;             if (sb == 0 && F.tid == 0) qslot[bp] = CQ_TICKET();
.LBB0_597:
	s_or_b64 exec, exec, s[22:23]
	s_lshl_b32 s22, s67, 2
	s_add_i32 s22, s22, 0
	s_add_i32 s22, s22, 0x22180
	v_mov_b32_e32 v35, s22
	v_mov_b32_e32 v41, 1
	ds_write_b32 v35, v34
.LBB0_598:
	s_or_b64 exec, exec, s[0:1]
	s_cmp_eq_u32 s68, 0
	s_cselect_b64 s[22:23], -1, 0
	s_and_b64 s[0:1], s[22:23], exec
	s_cselect_b32 s24, 0, s63
	s_cmp_eq_u32 s30, 0
	s_cbranch_scc1 .LBB0_606
	s_add_i32 s0, s59, s24
	v_lshlrev_b32_e32 v34, 2, v40
	v_add3_u32 v37, s0, v47, v34
	ds_read2_b32 v[56:57], v37 offset1:16
	v_add_u32_e32 v34, 0x400, v37
	ds_read2_b32 v[58:59], v34 offset0:4 offset1:20
	v_add_u32_e32 v34, 0x800, v37
	ds_read2_b32 v[60:61], v34 offset0:8 offset1:24
	v_add_u32_e32 v34, 0xc00, v37
	ds_read2_b32 v[62:63], v34 offset0:12 offset1:28
	s_waitcnt lgkmcnt(3)
	v_max_f32_e32 v34, v56, v56
	v_med3_f32 v35, v34, s64, v53
	s_waitcnt lgkmcnt(2)
	v_max_f32_e32 v34, v58, v58
	v_med3_f32 v36, v34, s64, v53
	v_mov_b32_e32 v34, 0
	v_cvt_pk_fp8_f32 v34, v35, v36
	s_waitcnt lgkmcnt(1)
	v_max_f32_e32 v35, v60, v60
	s_waitcnt lgkmcnt(0)
	v_max_f32_e32 v36, v62, v62
	v_med3_f32 v35, v35, s64, v53
	v_med3_f32 v36, v36, s64, v53
	v_cvt_pk_fp8_f32 v34, v35, v36 op_sel:[0,0,1]
	v_add_u32_e32 v35, 0x1000, v37
	ds_read2_b32 v[64:65], v35 offset0:16 offset1:32
	v_add_u32_e32 v35, 0x1400, v37
	ds_read2_b32 v[66:67], v35 offset0:20 offset1:36
	v_add_u32_e32 v35, 0x1800, v37
	ds_read2_b32 v[68:69], v35 offset0:24 offset1:40
	v_add_u32_e32 v35, 0x1c00, v37
	ds_read2_b32 v[70:71], v35 offset0:28 offset1:44
	s_waitcnt lgkmcnt(3)
	v_max_f32_e32 v35, v64, v64
	v_med3_f32 v36, v35, s64, v53
	s_waitcnt lgkmcnt(2)
	v_max_f32_e32 v35, v66, v66
	v_med3_f32 v55, v35, s64, v53
	v_mov_b32_e32 v35, 0
	v_cvt_pk_fp8_f32 v35, v36, v55
	s_waitcnt lgkmcnt(1)
	v_max_f32_e32 v36, v68, v68
	s_waitcnt lgkmcnt(0)
	v_max_f32_e32 v55, v70, v70
	v_med3_f32 v36, v36, s64, v53
	v_med3_f32 v55, v55, s64, v53
	v_cvt_pk_fp8_f32 v35, v36, v55 op_sel:[0,0,1]
	v_add_u32_e32 v36, 0x2000, v37
	ds_read2_b32 v[72:73], v36 offset0:32 offset1:48
	v_add_u32_e32 v36, 0x2400, v37
	ds_read2_b32 v[74:75], v36 offset0:36 offset1:52
	v_add_u32_e32 v36, 0x2800, v37
	ds_read2_b32 v[76:77], v36 offset0:40 offset1:56
	v_add_u32_e32 v36, 0x2c00, v37
	ds_read2_b32 v[78:79], v36 offset0:44 offset1:60
	s_waitcnt lgkmcnt(3)
	v_max_f32_e32 v36, v72, v72
	v_med3_f32 v55, v36, s64, v53
	s_waitcnt lgkmcnt(2)
	v_max_f32_e32 v36, v74, v74
	v_med3_f32 v56, v36, s64, v53
	v_mov_b32_e32 v36, 0
	v_cvt_pk_fp8_f32 v36, v55, v56
	s_waitcnt lgkmcnt(1)
	v_max_f32_e32 v55, v76, v76
	s_waitcnt lgkmcnt(0)
	v_max_f32_e32 v56, v78, v78
	v_med3_f32 v55, v55, s64, v53
	v_med3_f32 v56, v56, s64, v53
	v_cvt_pk_fp8_f32 v36, v55, v56 op_sel:[0,0,1]
	v_add_u32_e32 v55, 0x3000, v37
	ds_read2_b32 v[80:81], v55 offset0:48 offset1:64
	v_add_u32_e32 v55, 0x3400, v37
	ds_read2_b32 v[82:83], v55 offset0:52 offset1:68
	v_add_u32_e32 v55, 0x3800, v37
	v_add_u32_e32 v37, 0x3c00, v37
	ds_read2_b32 v[84:85], v55 offset0:56 offset1:72
	ds_read2_b32 v[86:87], v37 offset0:60 offset1:76
	s_waitcnt lgkmcnt(3)
	v_max_f32_e32 v37, v80, v80
	v_med3_f32 v55, v37, s64, v53
	s_waitcnt lgkmcnt(2)
	v_max_f32_e32 v37, v82, v82
	v_med3_f32 v56, v37, s64, v53
	v_mov_b32_e32 v37, 0
	v_cvt_pk_fp8_f32 v37, v55, v56
	s_waitcnt lgkmcnt(1)
	v_max_f32_e32 v55, v84, v84
	s_waitcnt lgkmcnt(0)
	v_max_f32_e32 v56, v86, v86
	v_med3_f32 v55, v55, s64, v53
	v_med3_f32 v56, v56, s64, v53
	v_cvt_pk_fp8_f32 v37, v55, v56 op_sel:[0,0,1]
	v_mov_b64_e32 v[88:89], s[16:17]
	v_mad_i64_i32 v[88:89], s[0:1], s62, v40, v[88:89]
	v_lshl_add_u64 v[88:89], v[88:89], 0, v[42:43]
	global_store_dwordx4 v[88:89], v[34:37], off
	s_nop 1
	v_max_f32_e32 v34, v57, v57
	v_med3_f32 v35, v34, s64, v53
	v_max_f32_e32 v34, v59, v59
	v_med3_f32 v36, v34, s64, v53
	v_mov_b32_e32 v34, 0
	v_cvt_pk_fp8_f32 v34, v35, v36
	v_max_f32_e32 v35, v61, v61
	v_max_f32_e32 v36, v63, v63
	v_med3_f32 v35, v35, s64, v53
	v_med3_f32 v36, v36, s64, v53
	v_cvt_pk_fp8_f32 v34, v35, v36 op_sel:[0,0,1]
	v_max_f32_e32 v35, v65, v65
	v_med3_f32 v36, v35, s64, v53
	v_max_f32_e32 v35, v67, v67
	v_med3_f32 v37, v35, s64, v53
	v_mov_b32_e32 v35, 0
	v_cvt_pk_fp8_f32 v35, v36, v37
	v_max_f32_e32 v36, v69, v69
	v_max_f32_e32 v37, v71, v71
	v_med3_f32 v36, v36, s64, v53
	v_med3_f32 v37, v37, s64, v53
	v_cvt_pk_fp8_f32 v35, v36, v37 op_sel:[0,0,1]
	v_max_f32_e32 v36, v73, v73
	v_med3_f32 v37, v36, s64, v53
	v_max_f32_e32 v36, v75, v75
	v_med3_f32 v55, v36, s64, v53
	v_mov_b32_e32 v36, 0
	v_cvt_pk_fp8_f32 v36, v37, v55
	v_max_f32_e32 v37, v77, v77
	v_max_f32_e32 v55, v79, v79
	v_med3_f32 v37, v37, s64, v53
	v_med3_f32 v55, v55, s64, v53
	v_cvt_pk_fp8_f32 v36, v37, v55 op_sel:[0,0,1]
	v_max_f32_e32 v37, v81, v81
	v_med3_f32 v55, v37, s64, v53
	v_max_f32_e32 v37, v83, v83
	v_med3_f32 v56, v37, s64, v53
	v_mov_b32_e32 v37, 0
	v_cvt_pk_fp8_f32 v37, v55, v56
	v_max_f32_e32 v55, v85, v85
	v_max_f32_e32 v56, v87, v87
	v_med3_f32 v55, v55, s64, v53
	v_med3_f32 v56, v56, s64, v53
	v_cvt_pk_fp8_f32 v37, v55, v56 op_sel:[0,0,1]
	v_mad_i64_i32 v[56:57], s[0:1], s62, v44, 0
	v_mov_b64_e32 v[58:59], v[42:43]
	s_cbranch_execnz .LBB0_601

; #define GAS __attribute__((address_space(1)))
; #define LAS __attribute__((address_space(3)))
; __device__ __forceinline__ void tile_store(LAS float* buf, const f32x4 (&t)[8], float mul, int w, int lane) {
; #pragma unroll
;     for (int i = 0; i < 8; ++i) *(LAS f32x4*)(buf + (8 * w + i) * TPITCH + 4 * lane) = t[i] * mul;
; }
; __device__ __forceinline__ void p0_convert(const P0Item& d, const LAS float* buf, int w, int lane, bool NT) {
;     ...
;         for (int j = 0; j < 2; ++j) { const int n = (lane >> 2) + 16 * j; const LAS float* s = buf + (16 * c) * TPITCH + 32 * w + n;
;             v4u o; o.x = pg8::pk4_fp8(s[0 * TPITCH], s[1 * TPITCH], s[2 * TPITCH], s[3 * TPITCH]); o.y = pg8::pk4_fp8(s[4 * TPITCH], s[5 * TPITCH], s[6 * TPITCH], s[7 * TPITCH]);
;             o.z = pg8::pk4_fp8(s[8 * TPITCH], s[9 * TPITCH], s[10 * TPITCH], s[11 * TPITCH]); o.w = pg8::pk4_fp8(s[12 * TPITCH], s[13 * TPITCH], s[14 * TPITCH], s[15 * TPITCH]);
;             if (NT) __builtin_nontemporal_store(o, (v4u*)(d.dst + (size_t)n * d.ldkb + 16 * c)); else *(GAS v4u*)(d.dst + (size_t)n * d.ldkb + 16 * c) = o; }
.LBB0_601:
	v_lshl_add_u64 v[56:57], s[16:17], 0, v[56:57]
	v_cndmask_b32_e64 v55, 0, 1, s[18:19]
	v_lshl_add_u64 v[56:57], v[56:57], 0, v[58:59]
	v_cmp_ne_u32_e64 s[0:1], 1, v55
	s_andn2_b64 vcc, exec, s[18:19]
	global_store_dwordx4 v[56:57], v[34:37], off
	s_cbranch_vccnz .LBB0_603
	s_and_b64 s[16:17], s[22:23], exec
	s_cselect_b32 s16, s63, 0
	s_add_i32 s16, s58, s16
	s_waitcnt vmcnt(8)
	v_pk_mul_f32 v[36:37], s[14:15], v[4:5] op_sel_hi:[0,1]
	v_pk_mul_f32 v[34:35], s[14:15], v[2:3] op_sel_hi:[0,1]
	v_add_u32_e32 v55, s16, v45
	ds_write_b128 v55, v[34:37]
	s_waitcnt vmcnt(7)
	v_pk_mul_f32 v[36:37], s[14:15], v[8:9] op_sel_hi:[0,1]
	v_pk_mul_f32 v[34:35], s[14:15], v[6:7] op_sel_hi:[0,1]
	ds_write_b128 v55, v[34:37] offset:1040
	s_waitcnt vmcnt(6)
	v_pk_mul_f32 v[36:37], s[14:15], v[12:13] op_sel_hi:[0,1]
	v_pk_mul_f32 v[34:35], s[14:15], v[10:11] op_sel_hi:[0,1]
	ds_write_b128 v55, v[34:37] offset:2080
	s_waitcnt vmcnt(5)
	v_pk_mul_f32 v[36:37], s[14:15], v[16:17] op_sel_hi:[0,1]
	v_pk_mul_f32 v[34:35], s[14:15], v[14:15] op_sel_hi:[0,1]
	ds_write_b128 v55, v[34:37] offset:3120
	s_waitcnt vmcnt(4)
	v_pk_mul_f32 v[36:37], s[14:15], v[20:21] op_sel_hi:[0,1]
	v_pk_mul_f32 v[34:35], s[14:15], v[18:19] op_sel_hi:[0,1]
	ds_write_b128 v55, v[34:37] offset:4160
	s_waitcnt vmcnt(3)
	v_pk_mul_f32 v[36:37], s[14:15], v[24:25] op_sel_hi:[0,1]
	v_pk_mul_f32 v[34:35], s[14:15], v[22:23] op_sel_hi:[0,1]
	ds_write_b128 v55, v[34:37] offset:5200
	s_waitcnt vmcnt(2)
	v_pk_mul_f32 v[36:37], s[14:15], v[28:29] op_sel_hi:[0,1]
	v_pk_mul_f32 v[34:35], s[14:15], v[26:27] op_sel_hi:[0,1]
	ds_write_b128 v55, v[34:37] offset:6240
	s_waitcnt vmcnt(1)
	v_pk_mul_f32 v[36:37], s[14:15], v[32:33] op_sel_hi:[0,1]
	v_pk_mul_f32 v[34:35], s[14:15], v[30:31] op_sel_hi:[0,1]
	s_mov_b32 s30, s72
	s_mov_b32 s62, s74
	s_mov_b64 s[16:17], s[20:21]
	s_mov_b32 s29, s73
	ds_write_b128 v55, v[34:37] offset:7280

; __device__ __forceinline__ unsigned cvt_pk_bf16(float lo, float hi) { unsigned r; asm volatile("v_cvt_pk_bf16_f32 %0, %1, %2" : "=v"(r) : "v"(lo), "v"(hi)); return r; }
;     __device__ __forceinline__ void operator()(const f32x4 (&acc)[2][2][4][2], const Unit& u, int wr, int wc, int fr, int fq) const {
;     ...
; #pragma unroll
;             for (int ai = 0; ai < 2; ++ai)
; #pragma unroll
;                 for (int m = 0; m < 4; ++m) {
;                     const int row = row0 + ai * HALF + m * 16;
;                     const float* gp = gate + (size_t)modrow_of(row) * NMOD + col0;
;                     bf16_t* op = (bf16_t*)((char*)X + SLAB_MINUS_X) + ((size_t)u.kp * MS + (row - MP)) * DM + col0;
; #pragma unroll
;                     for (int bj = 0; bj < 2; ++bj) {
;                         const f32x4 g0 = (*(const f32x4*)(gp + bj * HALF) + *(const f32x4*)(gp + MODSB_DELTA + bj * HALF)) * coef, g1 = (*(const f32x4*)(gp + bj * HALF + 4) + *(const f32x4*)(gp + MODSB_DELTA + bj * HALF + 4)) * coef;
;                         const f32x4 o0 = g0 * acc[ai][bj][m][0], o1 = g1 * acc[ai][bj][m][1];
;                         u32x4 w; w.x = cvt_pk_bf16(o0[0], o0[1]); w.y = cvt_pk_bf16(o0[2], o0[3]); w.z = cvt_pk_bf16(o1[0], o1[1]); w.w = cvt_pk_bf16(o1[2], o1[3]);
;                         *(u32x4*)(op + bj * HALF) = w;
;                     }
;                     if (m & 1) asm volatile("" ::: "memory");
;                 }
.LBB0_1190:
	s_lshl_b32 s19, s28, 8
	s_nop 15
	s_nop 15
	s_add_i32 s19, s19, s68
	v_or_b32_e32 v10, s19, v183
	v_lshl_or_b32 v8, s52, 8, v186
	s_mov_b64 s[34:35], -1
	s_andn2_b64 vcc, exec, s[54:55]
	v_ashrrev_i32_e32 v9, 31, v8
	v_or_b32_e32 v6, 16, v10
	v_or_b32_e32 v4, 32, v10
	v_or_b32_e32 v2, 48, v10
	s_cbranch_vccnz .LBB0_1193
	v_add_u32_e32 v174, 0xffffe000, v10
	s_ashr_i32 s21, s19, 11
	v_lshrrev_b32_e32 v3, 2, v174
	v_or_b32_e32 v5, 4, v3
	v_mov_b32_e32 v3, s21
	v_cmp_gt_i32_e32 vcc, s64, v10
	v_mov_b64_e32 v[14:15], s[8:9]
	v_lshlrev_b64 v[16:17], 2, v[8:9]
	v_cndmask_b32_e32 v5, v5, v3, vcc
	v_mad_i64_i32 v[12:13], s[34:35], v5, s65, v[14:15]
	v_lshl_add_u64 v[176:177], v[12:13], 0, v[16:17]
	v_add_co_u32_e32 v178, vcc, s73, v176
	v_lshl_add_u64 v[12:13], v[176:177], 0, s[14:15]
	s_nop 0
	v_addc_co_u32_e32 v179, vcc, 0, v177, vcc
	global_load_dwordx4 v[18:21], v[176:177], off offset:16
	global_load_dwordx4 v[22:25], v[176:177], off
	global_load_dwordx4 v[26:29], v[178:179], off
	global_load_dwordx4 v[30:33], v[12:13], off offset:16
	s_mov_b32 s31, s1
	s_lshl_b64 s[30:31], s[30:31], 21
	v_ashrrev_i32_e32 v175, 31, v174
	s_add_u32 s30, s66, s30
	v_lshlrev_b64 v[174:175], 12, v[174:175]
	s_addc_u32 s31, s67, s31
	v_lshlrev_b64 v[12:13], 1, v[8:9]
	v_lshl_add_u64 v[174:175], s[30:31], 0, v[174:175]
	v_lshl_add_u64 v[174:175], v[174:175], 0, v[12:13]
	v_cmp_gt_i32_e32 vcc, s64, v6
	s_addk_i32 s19, 0x80
	s_movk_i32 s21, 0x1f80
	s_ashr_i32 s19, s19, 11
	s_waitcnt vmcnt(0)
	v_pk_add_f32 v[24:25], v[24:25], v[28:29]
	v_pk_add_f32 v[20:21], v[20:21], v[32:33]
	v_pk_add_f32 v[18:19], v[18:19], v[30:31]
	v_pk_add_f32 v[22:23], v[22:23], v[26:27]
	v_pk_mul_f32 v[26:27], v[156:157], v[20:21]
	v_pk_mul_f32 v[20:21], v[154:155], v[18:19]
	v_pk_mul_f32 v[24:25], v[160:161], v[24:25]
	v_pk_mul_f32 v[22:23], v[158:159], v[22:23]
	v_lshl_add_u64 v[30:31], v[176:177], 0, s[16:17]
	v_cvt_pk_bf16_f32 v18, v22, v23
	v_cvt_pk_bf16_f32 v19, v24, v25
	v_cvt_pk_bf16_f32 v20, v20, v21
	v_cvt_pk_bf16_f32 v21, v26, v27
	global_store_dwordx4 v[174:175], v[18:21], off
	global_load_dwordx4 v[18:21], v[176:177], off offset:528
	s_nop 0
	global_load_dwordx4 v[22:25], v[176:177], off offset:512
	global_load_dwordx4 v[26:29], v[178:179], off offset:512
	v_add_u32_e32 v176, 0xffffe010, v10
	global_load_dwordx4 v[30:33], v[30:31], off offset:16
	v_lshrrev_b32_e32 v5, 2, v176
	v_add_u32_e32 v5, 4, v5
	v_cndmask_b32_e32 v5, v5, v3, vcc
	v_mad_i64_i32 v[178:179], s[34:35], v5, s65, v[14:15]
	v_lshl_add_u64 v[178:179], v[178:179], 0, v[16:17]
	v_add_co_u32_e32 v180, vcc, s73, v178
	v_ashrrev_i32_e32 v177, 31, v176
	s_nop 0
	v_addc_co_u32_e32 v181, vcc, 0, v179, vcc
	v_cmp_gt_i32_e32 vcc, s64, v4
	s_waitcnt vmcnt(1)
	v_pk_add_f32 v[24:25], v[24:25], v[28:29]
	v_pk_add_f32 v[22:23], v[22:23], v[26:27]
	s_waitcnt vmcnt(0)
	v_pk_add_f32 v[20:21], v[20:21], v[32:33]
	v_pk_add_f32 v[18:19], v[18:19], v[30:31]
	v_pk_mul_f32 v[26:27], v[144:145], v[20:21]
	v_pk_mul_f32 v[20:21], v[142:143], v[18:19]
	v_pk_mul_f32 v[24:25], v[148:149], v[24:25]
	v_pk_mul_f32 v[22:23], v[146:147], v[22:23]
	v_lshl_add_u64 v[30:31], v[178:179], 0, s[14:15]
	v_cvt_pk_bf16_f32 v18, v22, v23
	v_cvt_pk_bf16_f32 v19, v24, v25
	v_cvt_pk_bf16_f32 v20, v20, v21
	v_cvt_pk_bf16_f32 v21, v26, v27
	global_store_dwordx4 v[174:175], v[18:21], off offset:256
	global_load_dwordx4 v[18:21], v[178:179], off offset:16
	s_nop 0
	global_load_dwordx4 v[22:25], v[178:179], off
	global_load_dwordx4 v[26:29], v[180:181], off
	v_lshlrev_b64 v[174:175], 12, v[176:177]
	global_load_dwordx4 v[30:33], v[30:31], off offset:16
	v_lshl_add_u64 v[174:175], s[30:31], 0, v[174:175]
	v_lshl_add_u64 v[174:175], v[174:175], 0, v[12:13]
	v_add_u32_e32 v176, 0xffffe020, v10
	v_lshrrev_b32_e32 v5, 2, v176
	v_or_b32_e32 v5, 4, v5
	v_cndmask_b32_e32 v5, v5, v3, vcc
	v_ashrrev_i32_e32 v177, 31, v176
	s_waitcnt vmcnt(1)
	v_pk_add_f32 v[24:25], v[24:25], v[28:29]
	v_pk_add_f32 v[22:23], v[22:23], v[26:27]
	s_waitcnt vmcnt(0)
	v_pk_add_f32 v[20:21], v[20:21], v[32:33]
	v_pk_add_f32 v[18:19], v[18:19], v[30:31]
	v_pk_mul_f32 v[26:27], v[140:141], v[20:21]
	v_pk_mul_f32 v[20:21], v[138:139], v[18:19]
	v_pk_mul_f32 v[24:25], v[152:153], v[24:25]
	v_pk_mul_f32 v[22:23], v[150:151], v[22:23]
	v_lshl_add_u64 v[30:31], v[178:179], 0, s[16:17]
	v_cvt_pk_bf16_f32 v18, v22, v23
	v_cvt_pk_bf16_f32 v19, v24, v25
	v_cvt_pk_bf16_f32 v20, v20, v21
	v_cvt_pk_bf16_f32 v21, v26, v27
	global_store_dwordx4 v[174:175], v[18:21], off
	global_load_dwordx4 v[18:21], v[178:179], off offset:528
	s_nop 0
	global_load_dwordx4 v[22:25], v[178:179], off offset:512
	global_load_dwordx4 v[26:29], v[180:181], off offset:512
	v_mad_i64_i32 v[178:179], s[34:35], v5, s65, v[14:15]
	global_load_dwordx4 v[30:33], v[30:31], off offset:16
	v_lshl_add_u64 v[178:179], v[178:179], 0, v[16:17]
	v_add_co_u32_e32 v180, vcc, s73, v178
	s_waitcnt vmcnt(1)
	v_pk_add_f32 v[24:25], v[24:25], v[28:29]
	v_pk_add_f32 v[22:23], v[22:23], v[26:27]
	v_pk_mul_f32 v[24:25], v[136:137], v[24:25]
	s_waitcnt vmcnt(0)
	v_pk_add_f32 v[20:21], v[20:21], v[32:33]
	v_pk_add_f32 v[18:19], v[18:19], v[30:31]
	v_pk_mul_f32 v[26:27], v[128:129], v[20:21]
	v_pk_mul_f32 v[20:21], v[126:127], v[18:19]
	v_pk_mul_f32 v[22:23], v[134:135], v[22:23]
	v_lshl_add_u64 v[30:31], v[178:179], 0, s[14:15]
	v_cvt_pk_bf16_f32 v18, v22, v23
	v_cvt_pk_bf16_f32 v19, v24, v25
	v_cvt_pk_bf16_f32 v20, v20, v21
	v_cvt_pk_bf16_f32 v21, v26, v27
	global_store_dwordx4 v[174:175], v[18:21], off offset:256
	v_addc_co_u32_e32 v181, vcc, 0, v179, vcc
	global_load_dwordx4 v[18:21], v[178:179], off offset:16
	global_load_dwordx4 v[22:25], v[178:179], off
	global_load_dwordx4 v[26:29], v[180:181], off
	v_lshlrev_b64 v[174:175], 12, v[176:177]
	global_load_dwordx4 v[30:33], v[30:31], off offset:16
	v_lshl_add_u64 v[174:175], s[30:31], 0, v[174:175]
	v_lshl_add_u64 v[174:175], v[174:175], 0, v[12:13]
	v_add_u32_e32 v176, 0xffffe030, v10
	v_lshrrev_b32_e32 v5, 2, v176
	v_add_u32_e32 v5, 4, v5
	v_cmp_gt_i32_e32 vcc, s64, v2
	v_ashrrev_i32_e32 v177, 31, v176
	s_waitcnt vmcnt(1)
; __device__ __forceinline__ unsigned cvt_pk_bf16(float lo, float hi) { unsigned r; asm volatile("v_cvt_pk_bf16_f32 %0, %1, %2" : "=v"(r) : "v"(lo), "v"(hi)); return r; }
;     __device__ __forceinline__ void operator()(const f32x4 (&acc)[2][2][4][2], const Unit& u, int wr, int wc, int fr, int fq) const {
;     ...
; #pragma unroll
;             for (int ai = 0; ai < 2; ++ai)
; #pragma unroll
;                 for (int m = 0; m < 4; ++m) {
;                     const int row = row0 + ai * HALF + m * 16;
;                     const float* gp = gate + (size_t)modrow_of(row) * NMOD + col0;
;                     bf16_t* op = (bf16_t*)((char*)X + SLAB_MINUS_X) + ((size_t)u.kp * MS + (row - MP)) * DM + col0;
; #pragma unroll
;                     for (int bj = 0; bj < 2; ++bj) {
;                         const f32x4 g0 = (*(const f32x4*)(gp + bj * HALF) + *(const f32x4*)(gp + MODSB_DELTA + bj * HALF)) * coef, g1 = (*(const f32x4*)(gp + bj * HALF + 4) + *(const f32x4*)(gp + MODSB_DELTA + bj * HALF + 4)) * coef;
;                         const f32x4 o0 = g0 * acc[ai][bj][m][0], o1 = g1 * acc[ai][bj][m][1];
;                         u32x4 w; w.x = cvt_pk_bf16(o0[0], o0[1]); w.y = cvt_pk_bf16(o0[2], o0[3]); w.z = cvt_pk_bf16(o1[0], o1[1]); w.w = cvt_pk_bf16(o1[2], o1[3]);
;                         *(u32x4*)(op + bj * HALF) = w;
;                     }
;                     if (m & 1) asm volatile("" ::: "memory");
;                 }
	v_pk_add_f32 v[24:25], v[24:25], v[28:29]
	v_pk_add_f32 v[22:23], v[22:23], v[26:27]
	s_waitcnt vmcnt(0)
	v_pk_add_f32 v[20:21], v[20:21], v[32:33]
	v_pk_add_f32 v[18:19], v[18:19], v[30:31]
	v_pk_mul_f32 v[26:27], v[124:125], v[20:21]
	v_pk_mul_f32 v[20:21], v[122:123], v[18:19]
	v_pk_mul_f32 v[24:25], v[132:133], v[24:25]
	v_pk_mul_f32 v[22:23], v[130:131], v[22:23]
	v_lshl_add_u64 v[30:31], v[178:179], 0, s[16:17]
	v_cvt_pk_bf16_f32 v18, v22, v23
	v_cvt_pk_bf16_f32 v19, v24, v25
	v_cvt_pk_bf16_f32 v20, v20, v21
	v_cvt_pk_bf16_f32 v21, v26, v27
	global_store_dwordx4 v[174:175], v[18:21], off
	global_load_dwordx4 v[18:21], v[178:179], off offset:528
	s_nop 0
	global_load_dwordx4 v[22:25], v[178:179], off offset:512
	global_load_dwordx4 v[26:29], v[180:181], off offset:512
	v_cndmask_b32_e32 v3, v5, v3, vcc
	global_load_dwordx4 v[30:33], v[30:31], off offset:16
	v_mad_i64_i32 v[178:179], s[34:35], v3, s65, v[14:15]
	v_lshl_add_u64 v[178:179], v[178:179], 0, v[16:17]
	v_add_co_u32_e32 v180, vcc, s73, v178
	s_waitcnt vmcnt(1)
	v_pk_add_f32 v[24:25], v[24:25], v[28:29]
	v_pk_add_f32 v[22:23], v[22:23], v[26:27]
	s_waitcnt vmcnt(0)
	v_pk_add_f32 v[20:21], v[20:21], v[32:33]
	v_pk_add_f32 v[18:19], v[18:19], v[30:31]
	v_pk_mul_f32 v[26:27], v[112:113], v[20:21]
	v_pk_mul_f32 v[20:21], v[110:111], v[18:19]
	v_pk_mul_f32 v[24:25], v[116:117], v[24:25]
	v_pk_mul_f32 v[22:23], v[114:115], v[22:23]
	v_lshl_add_u64 v[30:31], v[178:179], 0, s[14:15]
	v_cvt_pk_bf16_f32 v18, v22, v23
	v_cvt_pk_bf16_f32 v19, v24, v25
	v_cvt_pk_bf16_f32 v20, v20, v21
	v_cvt_pk_bf16_f32 v21, v26, v27
	global_store_dwordx4 v[174:175], v[18:21], off offset:256
	v_addc_co_u32_e32 v181, vcc, 0, v179, vcc
	global_load_dwordx4 v[18:21], v[178:179], off offset:16
	global_load_dwordx4 v[22:25], v[178:179], off
	global_load_dwordx4 v[26:29], v[180:181], off
	v_lshlrev_b64 v[174:175], 12, v[176:177]
	global_load_dwordx4 v[30:33], v[30:31], off offset:16
	v_lshl_add_u64 v[174:175], s[30:31], 0, v[174:175]
	v_lshl_add_u64 v[174:175], v[174:175], 0, v[12:13]
	v_add_u32_e32 v176, 0xffffe080, v10
	v_lshrrev_b32_e32 v3, 2, v176
	v_or_b32_e32 v5, 4, v3
	v_mov_b32_e32 v3, s19
	v_cmp_gt_i32_e32 vcc, s21, v10
	v_ashrrev_i32_e32 v177, 31, v176
	s_movk_i32 s19, 0x1f70
	v_cndmask_b32_e32 v5, v5, v3, vcc
	s_waitcnt vmcnt(1)
	v_pk_add_f32 v[24:25], v[24:25], v[28:29]
	v_pk_add_f32 v[22:23], v[22:23], v[26:27]
	s_waitcnt vmcnt(0)
	v_pk_add_f32 v[20:21], v[20:21], v[32:33]
	v_pk_add_f32 v[18:19], v[18:19], v[30:31]
	v_pk_mul_f32 v[26:27], v[108:109], v[20:21]
	v_pk_mul_f32 v[20:21], v[106:107], v[18:19]
	v_pk_mul_f32 v[24:25], v[120:121], v[24:25]
	v_pk_mul_f32 v[22:23], v[118:119], v[22:23]
	v_lshl_add_u64 v[30:31], v[178:179], 0, s[16:17]
	v_cvt_pk_bf16_f32 v18, v22, v23
	v_cvt_pk_bf16_f32 v19, v24, v25
	v_cvt_pk_bf16_f32 v20, v20, v21
	v_cvt_pk_bf16_f32 v21, v26, v27
	global_store_dwordx4 v[174:175], v[18:21], off
	global_load_dwordx4 v[18:21], v[178:179], off offset:528
	s_nop 0
	global_load_dwordx4 v[22:25], v[178:179], off offset:512
	global_load_dwordx4 v[26:29], v[180:181], off offset:512
	v_mad_i64_i32 v[178:179], s[34:35], v5, s65, v[14:15]
	global_load_dwordx4 v[30:33], v[30:31], off offset:16
	v_lshl_add_u64 v[178:179], v[178:179], 0, v[16:17]
	v_add_co_u32_e32 v180, vcc, s73, v178
	s_waitcnt vmcnt(1)
	v_pk_add_f32 v[24:25], v[24:25], v[28:29]
	v_pk_add_f32 v[22:23], v[22:23], v[26:27]
	v_pk_mul_f32 v[24:25], v[104:105], v[24:25]
	s_waitcnt vmcnt(0)
	v_pk_add_f32 v[20:21], v[20:21], v[32:33]
	v_pk_add_f32 v[18:19], v[18:19], v[30:31]
	v_pk_mul_f32 v[26:27], v[100:101], v[20:21]
	v_pk_mul_f32 v[20:21], v[98:99], v[18:19]
	v_pk_mul_f32 v[22:23], v[102:103], v[22:23]
	v_lshl_add_u64 v[30:31], v[178:179], 0, s[14:15]
	v_cvt_pk_bf16_f32 v18, v22, v23
	v_cvt_pk_bf16_f32 v19, v24, v25
	v_cvt_pk_bf16_f32 v20, v20, v21
	v_cvt_pk_bf16_f32 v21, v26, v27
	global_store_dwordx4 v[174:175], v[18:21], off offset:256
	v_addc_co_u32_e32 v181, vcc, 0, v179, vcc
	global_load_dwordx4 v[18:21], v[178:179], off offset:16
	global_load_dwordx4 v[22:25], v[178:179], off
	global_load_dwordx4 v[26:29], v[180:181], off
	v_lshlrev_b64 v[174:175], 12, v[176:177]
	global_load_dwordx4 v[30:33], v[30:31], off offset:16
	v_lshl_add_u64 v[174:175], s[30:31], 0, v[174:175]
	v_lshl_add_u64 v[174:175], v[174:175], 0, v[12:13]
	v_add_u32_e32 v176, 0xffffe090, v10
	v_lshrrev_b32_e32 v5, 2, v176
	v_add_u32_e32 v5, 4, v5
	v_cmp_gt_i32_e32 vcc, s19, v10
	v_ashrrev_i32_e32 v177, 31, v176
	s_movk_i32 s19, 0x1f60
	v_cndmask_b32_e32 v5, v5, v3, vcc
	s_waitcnt vmcnt(1)
	v_pk_add_f32 v[24:25], v[24:25], v[28:29]
	v_pk_add_f32 v[22:23], v[22:23], v[26:27]
	s_waitcnt vmcnt(0)
	v_pk_add_f32 v[20:21], v[20:21], v[32:33]
	v_pk_add_f32 v[18:19], v[18:19], v[30:31]
	v_pk_mul_f32 v[26:27], v[92:93], v[20:21]
	v_pk_mul_f32 v[20:21], v[90:91], v[18:19]
	v_pk_mul_f32 v[24:25], v[96:97], v[24:25]
	v_pk_mul_f32 v[22:23], v[94:95], v[22:23]
	v_lshl_add_u64 v[30:31], v[178:179], 0, s[16:17]
	v_cvt_pk_bf16_f32 v18, v22, v23
	v_cvt_pk_bf16_f32 v19, v24, v25
	v_cvt_pk_bf16_f32 v20, v20, v21
	v_cvt_pk_bf16_f32 v21, v26, v27
	global_store_dwordx4 v[174:175], v[18:21], off
	global_load_dwordx4 v[18:21], v[178:179], off offset:528
	s_nop 0
	global_load_dwordx4 v[22:25], v[178:179], off offset:512
	global_load_dwordx4 v[26:29], v[180:181], off offset:512
	v_mad_i64_i32 v[178:179], s[34:35], v5, s65, v[14:15]
	global_load_dwordx4 v[30:33], v[30:31], off offset:16
	v_lshl_add_u64 v[178:179], v[178:179], 0, v[16:17]
	v_add_co_u32_e32 v180, vcc, s73, v178
	s_waitcnt vmcnt(1)
	v_pk_add_f32 v[24:25], v[24:25], v[28:29]
	v_pk_add_f32 v[22:23], v[22:23], v[26:27]
	v_pk_mul_f32 v[24:25], v[88:89], v[24:25]
	s_waitcnt vmcnt(0)
; __device__ __forceinline__ unsigned cvt_pk_bf16(float lo, float hi) { unsigned r; asm volatile("v_cvt_pk_bf16_f32 %0, %1, %2" : "=v"(r) : "v"(lo), "v"(hi)); return r; }
;     __device__ __forceinline__ void operator()(const f32x4 (&acc)[2][2][4][2], const Unit& u, int wr, int wc, int fr, int fq) const {
;     ...
; #pragma unroll
;             for (int ai = 0; ai < 2; ++ai)
; #pragma unroll
;                 for (int m = 0; m < 4; ++m) {
;                     const int row = row0 + ai * HALF + m * 16;
;                     const float* gp = gate + (size_t)modrow_of(row) * NMOD + col0;
;                     bf16_t* op = (bf16_t*)((char*)X + SLAB_MINUS_X) + ((size_t)u.kp * MS + (row - MP)) * DM + col0;
; #pragma unroll
;                     for (int bj = 0; bj < 2; ++bj) {
;                         const f32x4 g0 = (*(const f32x4*)(gp + bj * HALF) + *(const f32x4*)(gp + MODSB_DELTA + bj * HALF)) * coef, g1 = (*(const f32x4*)(gp + bj * HALF + 4) + *(const f32x4*)(gp + MODSB_DELTA + bj * HALF + 4)) * coef;
;                         const f32x4 o0 = g0 * acc[ai][bj][m][0], o1 = g1 * acc[ai][bj][m][1];
;                         u32x4 w; w.x = cvt_pk_bf16(o0[0], o0[1]); w.y = cvt_pk_bf16(o0[2], o0[3]); w.z = cvt_pk_bf16(o1[0], o1[1]); w.w = cvt_pk_bf16(o1[2], o1[3]);
;                         *(u32x4*)(op + bj * HALF) = w;
;                     }
;                     if (m & 1) asm volatile("" ::: "memory");
;                 }
	v_pk_add_f32 v[20:21], v[20:21], v[32:33]
	v_pk_add_f32 v[18:19], v[18:19], v[30:31]
	v_pk_mul_f32 v[26:27], v[80:81], v[20:21]
	v_pk_mul_f32 v[20:21], v[78:79], v[18:19]
	v_pk_mul_f32 v[22:23], v[86:87], v[22:23]
	v_lshl_add_u64 v[30:31], v[178:179], 0, s[14:15]
	v_cvt_pk_bf16_f32 v18, v22, v23
	v_cvt_pk_bf16_f32 v19, v24, v25
	v_cvt_pk_bf16_f32 v20, v20, v21
	v_cvt_pk_bf16_f32 v21, v26, v27
	global_store_dwordx4 v[174:175], v[18:21], off offset:256
	v_addc_co_u32_e32 v181, vcc, 0, v179, vcc
	global_load_dwordx4 v[18:21], v[178:179], off offset:16
	global_load_dwordx4 v[22:25], v[178:179], off
	global_load_dwordx4 v[26:29], v[180:181], off
	v_lshlrev_b64 v[174:175], 12, v[176:177]
	global_load_dwordx4 v[30:33], v[30:31], off offset:16
	v_lshl_add_u64 v[174:175], s[30:31], 0, v[174:175]
	v_lshl_add_u64 v[174:175], v[174:175], 0, v[12:13]
	v_add_u32_e32 v176, 0xffffe0a0, v10
	v_lshrrev_b32_e32 v5, 2, v176
	v_or_b32_e32 v5, 4, v5
	v_cmp_gt_i32_e32 vcc, s19, v10
	v_ashrrev_i32_e32 v177, 31, v176
	s_movk_i32 s19, 0x1f50
	v_cndmask_b32_e32 v5, v5, v3, vcc
	s_waitcnt vmcnt(1)
	v_pk_add_f32 v[24:25], v[24:25], v[28:29]
	v_pk_add_f32 v[22:23], v[22:23], v[26:27]
	s_waitcnt vmcnt(0)
	v_pk_add_f32 v[20:21], v[20:21], v[32:33]
	v_pk_add_f32 v[18:19], v[18:19], v[30:31]
	v_pk_mul_f32 v[26:27], v[76:77], v[20:21]
	v_pk_mul_f32 v[20:21], v[74:75], v[18:19]
	v_pk_mul_f32 v[24:25], v[84:85], v[24:25]
	v_pk_mul_f32 v[22:23], v[82:83], v[22:23]
	v_lshl_add_u64 v[30:31], v[178:179], 0, s[16:17]
	v_cvt_pk_bf16_f32 v18, v22, v23
	v_cvt_pk_bf16_f32 v19, v24, v25
	v_cvt_pk_bf16_f32 v20, v20, v21
	v_cvt_pk_bf16_f32 v21, v26, v27
	global_store_dwordx4 v[174:175], v[18:21], off
	global_load_dwordx4 v[18:21], v[178:179], off offset:528
	s_nop 0
	global_load_dwordx4 v[22:25], v[178:179], off offset:512
	global_load_dwordx4 v[26:29], v[180:181], off offset:512
	v_mad_i64_i32 v[178:179], s[34:35], v5, s65, v[14:15]
	global_load_dwordx4 v[30:33], v[30:31], off offset:16
	v_lshl_add_u64 v[178:179], v[178:179], 0, v[16:17]
	v_add_co_u32_e32 v180, vcc, s73, v178
	s_waitcnt vmcnt(1)
	v_pk_add_f32 v[24:25], v[24:25], v[28:29]
	v_pk_add_f32 v[22:23], v[22:23], v[26:27]
	v_pk_mul_f32 v[24:25], v[72:73], v[24:25]
	s_waitcnt vmcnt(0)
	v_pk_add_f32 v[20:21], v[20:21], v[32:33]
	v_pk_add_f32 v[18:19], v[18:19], v[30:31]
	v_pk_mul_f32 v[26:27], v[64:65], v[20:21]
	v_pk_mul_f32 v[20:21], v[62:63], v[18:19]
	v_pk_mul_f32 v[22:23], v[70:71], v[22:23]
	v_lshl_add_u64 v[30:31], v[178:179], 0, s[14:15]
	v_cvt_pk_bf16_f32 v18, v22, v23
	v_cvt_pk_bf16_f32 v19, v24, v25
	v_cvt_pk_bf16_f32 v20, v20, v21
	v_cvt_pk_bf16_f32 v21, v26, v27
	global_store_dwordx4 v[174:175], v[18:21], off offset:256
	v_addc_co_u32_e32 v181, vcc, 0, v179, vcc
	global_load_dwordx4 v[18:21], v[178:179], off offset:16
	global_load_dwordx4 v[22:25], v[178:179], off
	global_load_dwordx4 v[26:29], v[180:181], off
	v_lshlrev_b64 v[174:175], 12, v[176:177]
	global_load_dwordx4 v[30:33], v[30:31], off offset:16
	v_lshl_add_u64 v[174:175], s[30:31], 0, v[174:175]
	v_lshl_add_u64 v[174:175], v[174:175], 0, v[12:13]
	v_add_u32_e32 v176, 0xffffe0b0, v10
	v_lshrrev_b32_e32 v5, 2, v176
	v_add_u32_e32 v5, 4, v5
	v_cmp_gt_i32_e32 vcc, s19, v10
	v_ashrrev_i32_e32 v177, 31, v176
	s_waitcnt vmcnt(1)
	v_pk_add_f32 v[24:25], v[24:25], v[28:29]
	v_pk_add_f32 v[22:23], v[22:23], v[26:27]
	s_waitcnt vmcnt(0)
	v_pk_add_f32 v[20:21], v[20:21], v[32:33]
	v_pk_add_f32 v[18:19], v[18:19], v[30:31]
	v_pk_mul_f32 v[26:27], v[60:61], v[20:21]
	v_pk_mul_f32 v[20:21], v[58:59], v[18:19]
	v_pk_mul_f32 v[24:25], v[68:69], v[24:25]
	v_pk_mul_f32 v[22:23], v[66:67], v[22:23]
	v_lshl_add_u64 v[30:31], v[178:179], 0, s[16:17]
	v_cvt_pk_bf16_f32 v18, v22, v23
	v_cvt_pk_bf16_f32 v19, v24, v25
	v_cvt_pk_bf16_f32 v20, v20, v21
	v_cvt_pk_bf16_f32 v21, v26, v27
	global_store_dwordx4 v[174:175], v[18:21], off
	global_load_dwordx4 v[18:21], v[178:179], off offset:528
	s_nop 0
	global_load_dwordx4 v[22:25], v[178:179], off offset:512
	global_load_dwordx4 v[26:29], v[180:181], off offset:512
	v_cndmask_b32_e32 v3, v5, v3, vcc
	global_load_dwordx4 v[30:33], v[30:31], off offset:16
	v_mad_i64_i32 v[14:15], s[34:35], v3, s65, v[14:15]
	v_lshl_add_u64 v[178:179], v[14:15], 0, v[16:17]
	v_add_co_u32_e32 v180, vcc, s73, v178
	s_nop 1
	v_addc_co_u32_e32 v181, vcc, 0, v179, vcc
	s_waitcnt vmcnt(1)
	v_pk_add_f32 v[14:15], v[24:25], v[28:29]
	v_pk_add_f32 v[16:17], v[22:23], v[26:27]
	s_waitcnt vmcnt(0)
	v_pk_add_f32 v[18:19], v[18:19], v[30:31]
	v_pk_add_f32 v[20:21], v[20:21], v[32:33]
	v_pk_mul_f32 v[22:23], v[56:57], v[14:15]
	v_pk_mul_f32 v[14:15], v[54:55], v[16:17]
	v_pk_mul_f32 v[16:17], v[46:47], v[18:19]
	v_pk_mul_f32 v[20:21], v[48:49], v[20:21]
	v_cvt_pk_bf16_f32 v14, v14, v15
	v_cvt_pk_bf16_f32 v15, v22, v23
	v_cvt_pk_bf16_f32 v16, v16, v17
	v_lshl_add_u64 v[26:27], v[178:179], 0, s[14:15]
	v_cvt_pk_bf16_f32 v17, v20, v21
	global_store_dwordx4 v[174:175], v[14:17], off offset:256
	global_load_dwordx4 v[14:17], v[178:179], off offset:16
	s_nop 0
	global_load_dwordx4 v[18:21], v[178:179], off
	global_load_dwordx4 v[22:25], v[180:181], off
	v_lshlrev_b64 v[30:31], 12, v[176:177]
	global_load_dwordx4 v[26:29], v[26:27], off offset:16
	v_lshl_add_u64 v[30:31], s[30:31], 0, v[30:31]
	v_lshl_add_u64 v[30:31], v[30:31], 0, v[12:13]
	s_waitcnt vmcnt(1)
	v_pk_add_f32 v[12:13], v[20:21], v[24:25]
	v_pk_add_f32 v[18:19], v[18:19], v[22:23]
	s_waitcnt vmcnt(0)
	v_pk_add_f32 v[14:15], v[14:15], v[26:27]
	v_pk_add_f32 v[16:17], v[16:17], v[28:29]
	v_pk_mul_f32 v[20:21], v[52:53], v[12:13]
	v_pk_mul_f32 v[12:13], v[50:51], v[18:19]
	v_pk_mul_f32 v[14:15], v[42:43], v[14:15]
	v_pk_mul_f32 v[16:17], v[44:45], v[16:17]
	v_cvt_pk_bf16_f32 v12, v12, v13
	v_cvt_pk_bf16_f32 v13, v20, v21
	v_cvt_pk_bf16_f32 v14, v14, v15
	v_lshl_add_u64 v[24:25], v[178:179], 0, s[16:17]
	v_cvt_pk_bf16_f32 v15, v16, v17
	global_store_dwordx4 v[30:31], v[12:15], off
	global_load_dwordx4 v[12:15], v[178:179], off offset:528
	s_nop 0
	global_load_dwordx4 v[16:19], v[178:179], off offset:512
	global_load_dwordx4 v[20:23], v[180:181], off offset:512
	s_waitcnt vmcnt(0)
	v_pk_add_f32 v[18:19], v[18:19], v[22:23]
	global_load_dwordx4 v[24:27], v[24:25], off offset:16
	v_pk_add_f32 v[16:17], v[16:17], v[20:21]
	v_pk_mul_f32 v[18:19], v[40:41], v[18:19]
	v_pk_mul_f32 v[16:17], v[38:39], v[16:17]
	s_waitcnt vmcnt(0)
	v_pk_add_f32 v[14:15], v[14:15], v[26:27]
	v_pk_add_f32 v[12:13], v[12:13], v[24:25]
	v_pk_mul_f32 v[20:21], v[36:37], v[14:15]
	v_pk_mul_f32 v[14:15], v[34:35], v[12:13]
	v_cvt_pk_bf16_f32 v12, v16, v17
	v_cvt_pk_bf16_f32 v13, v18, v19
	s_nop 0
	v_cvt_pk_bf16_f32 v14, v14, v15
	v_cvt_pk_bf16_f32 v15, v20, v21
	global_store_dwordx4 v[30:31], v[12:15], off offset:256
	s_cbranch_execz .LBB0_1194

; __device__ __forceinline__ unsigned cvt_pk_bf16(float lo, float hi) { unsigned r; asm volatile("v_cvt_pk_bf16_f32 %0, %1, %2" : "=v"(r) : "v"(lo), "v"(hi)); return r; }
;     __device__ __forceinline__ void operator()(const f32x4 (&acc)[2][2][4][2], const Unit& u, int wr, int wc, int fr, int fq) const {
;     ...
;         if (u.kp < 0) {
;             const float* gp = gate + (size_t)(u.pm >> 3) * NMOD + col0;
;             f32x4 gg[2][2];
; #pragma unroll
;             for (int bj = 0; bj < 2; ++bj)
; #pragma unroll
;                 for (int n = 0; n < 2; ++n) gg[bj][n] = (*(const f32x4*)(gp + bj * HALF + 4 * n) + *(const f32x4*)(gp + MODSB_DELTA + bj * HALF + 4 * n)) * coef;
; #pragma unroll
;             for (int ai = 0; ai < 2; ++ai)
; #pragma unroll
;                 for (int m = 0; m < 4; ++m) {
;                     const int row = row0 + ai * HALF + m * 16;
;                     bf16_t* xp = X + (size_t)row * DM + col0;
; #pragma unroll
;                     for (int bj = 0; bj < 2; ++bj) {
;                         f32x4 b0, b1;
;                         if (BASE16) { const u32x4 bv = *(const u32x4*)(xp + bj * HALF);
;                             b0 = (f32x4){__builtin_bit_cast(float, bv.x << 16), __builtin_bit_cast(float, bv.x & 0xffff0000u), __builtin_bit_cast(float, bv.y << 16), __builtin_bit_cast(float, bv.y & 0xffff0000u)};
;                             b1 = (f32x4){__builtin_bit_cast(float, bv.z << 16), __builtin_bit_cast(float, bv.z & 0xffff0000u), __builtin_bit_cast(float, bv.w << 16), __builtin_bit_cast(float, bv.w & 0xffff0000u)}; }
;                         else { const float* bp = base32 + (size_t)row * DM + col0 + bj * HALF; b0 = __builtin_nontemporal_load((const f32x4*)bp); b1 = __builtin_nontemporal_load((const f32x4*)(bp + 4)); }
;                         const f32x4 o0 = b0 + gg[bj][0] * acc[ai][bj][m][0], o1 = b1 + gg[bj][1] * acc[ai][bj][m][1];
;                         u32x4 w; w.x = cvt_pk_bf16(o0[0], o0[1]); w.y = cvt_pk_bf16(o0[2], o0[3]); w.z = cvt_pk_bf16(o1[0], o1[1]); w.w = cvt_pk_bf16(o1[2], o1[3]);
;                         *(u32x4*)(xp + bj * HALF) = w;
;                     }
;                     if (m & 1) asm volatile("" ::: "memory");
;                 }
.LBB0_1194:
	s_ashr_i32 s19, s28, 3
	s_mul_hi_i32 s21, s19, 0x12000
	s_mul_i32 s19, s19, 0x12000
	s_add_u32 s30, s8, s19
	s_addc_u32 s31, s9, s21
	v_ashrrev_i32_e32 v11, 31, v10
	v_lshl_add_u64 v[22:23], v[8:9], 2, s[30:31]
	v_lshlrev_b64 v[10:11], 12, v[10:11]
	v_lshl_add_u64 v[10:11], s[6:7], 0, v[10:11]
	v_lshlrev_b64 v[24:25], 1, v[8:9]
	v_add_co_u32_e32 v194, vcc, s73, v22
	v_lshl_add_u64 v[8:9], v[10:11], 0, v[24:25]
	s_nop 0
	v_addc_co_u32_e32 v195, vcc, 0, v23, vcc
	v_lshl_add_u64 v[30:31], v[22:23], 0, s[14:15]
	global_load_dwordx4 v[10:13], v[8:9], off
	global_load_dwordx4 v[18:21], v[22:23], off offset:16
	global_load_dwordx4 v[14:17], v[22:23], off
	global_load_dwordx4 v[26:29], v[194:195], off
	v_lshl_add_u64 v[198:199], v[22:23], 0, s[16:17]
	global_load_dwordx4 v[30:33], v[30:31], off offset:16
	s_nop 0
	global_load_dwordx4 v[174:177], v[22:23], off offset:528
	global_load_dwordx4 v[178:181], v[22:23], off offset:512
	s_nop 0
	global_load_dwordx4 v[194:197], v[194:195], off offset:512
	s_nop 0
	global_load_dwordx4 v[198:201], v[198:199], off offset:16
	v_ashrrev_i32_e32 v7, 31, v6
	v_lshlrev_b64 v[6:7], 12, v[6:7]
	v_lshl_add_u64 v[6:7], s[6:7], 0, v[6:7]
	v_ashrrev_i32_e32 v5, 31, v4
	v_lshlrev_b64 v[4:5], 12, v[4:5]
	v_lshl_add_u64 v[4:5], s[6:7], 0, v[4:5]
	v_ashrrev_i32_e32 v3, 31, v2
	v_lshlrev_b64 v[2:3], 12, v[2:3]
	v_lshl_add_u64 v[2:3], s[6:7], 0, v[2:3]
	s_mov_b32 s19, 0x80000
	s_mov_b64 s[30:31], 0x80000
	s_waitcnt vmcnt(0)
	v_lshlrev_b32_e32 v22, 16, v10
	v_and_b32_e32 v23, 0xffff0000, v10
	v_lshlrev_b32_e32 v202, 16, v11
	v_and_b32_e32 v203, 0xffff0000, v11
	v_lshlrev_b32_e32 v204, 16, v12
	v_and_b32_e32 v205, 0xffff0000, v12
	v_pk_add_f32 v[10:11], v[18:19], v[30:31]
	v_lshlrev_b32_e32 v206, 16, v13
	v_and_b32_e32 v207, 0xffff0000, v13
	v_pk_add_f32 v[16:17], v[16:17], v[28:29]
	v_pk_add_f32 v[14:15], v[14:15], v[26:27]
	v_pk_add_f32 v[12:13], v[20:21], v[32:33]
	v_pk_fma_f32 v[28:29], v[154:155], v[10:11], v[204:205]
	v_pk_fma_f32 v[18:19], v[160:161], v[16:17], v[202:203]
	v_pk_fma_f32 v[20:21], v[158:159], v[14:15], v[22:23]
	v_pk_fma_f32 v[22:23], v[156:157], v[12:13], v[206:207]
	v_cvt_pk_bf16_f32 v26, v20, v21
	v_cvt_pk_bf16_f32 v27, v18, v19
	v_cvt_pk_bf16_f32 v28, v28, v29
	v_lshl_add_u64 v[154:155], v[6:7], 0, v[24:25]
	v_cvt_pk_bf16_f32 v29, v22, v23
	global_load_dwordx4 v[30:33], v[8:9], off offset:256
	v_pk_add_f32 v[22:23], v[180:181], v[196:197]
	v_pk_add_f32 v[20:21], v[178:179], v[194:195]
	v_pk_add_f32 v[18:19], v[176:177], v[200:201]
	v_pk_add_f32 v[6:7], v[174:175], v[198:199]
	global_store_dwordx4 v[8:9], v[26:29], off
	s_waitcnt vmcnt(1)
	s_nop 0
	v_lshlrev_b32_e32 v26, 16, v30
	v_and_b32_e32 v27, 0xffff0000, v30
	v_lshlrev_b32_e32 v28, 16, v31
	v_and_b32_e32 v29, 0xffff0000, v31
	v_lshlrev_b32_e32 v30, 16, v32
	v_and_b32_e32 v31, 0xffff0000, v32
	v_lshlrev_b32_e32 v32, 16, v33
	v_and_b32_e32 v33, 0xffff0000, v33
	v_pk_fma_f32 v[28:29], v[148:149], v[22:23], v[28:29]
	v_pk_fma_f32 v[26:27], v[146:147], v[20:21], v[26:27]
	v_pk_fma_f32 v[32:33], v[144:145], v[18:19], v[32:33]
	v_pk_fma_f32 v[30:31], v[142:143], v[6:7], v[30:31]
	v_cvt_pk_bf16_f32 v26, v26, v27
	v_cvt_pk_bf16_f32 v27, v28, v29
	s_nop 0
	v_cvt_pk_bf16_f32 v28, v30, v31
	v_cvt_pk_bf16_f32 v29, v32, v33
	global_load_dwordx4 v[30:33], v[154:155], off
	s_nop 0
	global_store_dwordx4 v[8:9], v[26:29], off offset:256
	s_waitcnt vmcnt(1)
	s_nop 0
	v_lshlrev_b32_e32 v26, 16, v30
	v_and_b32_e32 v27, 0xffff0000, v30
	v_lshlrev_b32_e32 v28, 16, v31
	v_and_b32_e32 v29, 0xffff0000, v31
	v_lshlrev_b32_e32 v30, 16, v32
	v_and_b32_e32 v31, 0xffff0000, v32
	v_lshlrev_b32_e32 v32, 16, v33
	v_and_b32_e32 v33, 0xffff0000, v33
	v_pk_fma_f32 v[28:29], v[152:153], v[16:17], v[28:29]
	v_pk_fma_f32 v[26:27], v[150:151], v[14:15], v[26:27]
	v_pk_fma_f32 v[32:33], v[140:141], v[12:13], v[32:33]
	v_pk_fma_f32 v[30:31], v[138:139], v[10:11], v[30:31]
	v_cvt_pk_bf16_f32 v26, v26, v27
	v_cvt_pk_bf16_f32 v27, v28, v29
	v_lshl_add_u64 v[138:139], v[4:5], 0, v[24:25]
	v_cvt_pk_bf16_f32 v28, v30, v31
	v_cvt_pk_bf16_f32 v29, v32, v33
	global_load_dwordx4 v[30:33], v[154:155], off offset:256
	s_waitcnt vmcnt(0)
	v_lshlrev_b32_e32 v4, 16, v30
	global_store_dwordx4 v[154:155], v[26:29], off
	v_and_b32_e32 v5, 0xffff0000, v30
	v_lshlrev_b32_e32 v30, 16, v33
	v_lshlrev_b32_e32 v28, 16, v32
	v_and_b32_e32 v29, 0xffff0000, v32
	v_lshlrev_b32_e32 v26, 16, v31
	v_and_b32_e32 v27, 0xffff0000, v31
	v_and_b32_e32 v31, 0xffff0000, v33
	v_pk_fma_f32 v[28:29], v[126:127], v[6:7], v[28:29]
	v_pk_fma_f32 v[32:33], v[136:137], v[22:23], v[26:27]
	v_pk_fma_f32 v[4:5], v[134:135], v[20:21], v[4:5]
	v_pk_fma_f32 v[30:31], v[128:129], v[18:19], v[30:31]
	v_cvt_pk_bf16_f32 v26, v4, v5
	v_cvt_pk_bf16_f32 v27, v32, v33
	v_cvt_pk_bf16_f32 v28, v28, v29
	s_nop 0
	v_cvt_pk_bf16_f32 v29, v30, v31
	global_store_dwordx4 v[154:155], v[26:29], off offset:256
	global_load_dwordx4 v[26:29], v[138:139], off
	s_waitcnt vmcnt(0)
	v_lshlrev_b32_e32 v4, 16, v26
	v_and_b32_e32 v5, 0xffff0000, v26
	v_lshlrev_b32_e32 v26, 16, v27
	v_and_b32_e32 v27, 0xffff0000, v27
	v_lshlrev_b32_e32 v30, 16, v28
	v_and_b32_e32 v31, 0xffff0000, v28
	v_lshlrev_b32_e32 v28, 16, v29
	v_and_b32_e32 v29, 0xffff0000, v29
	v_pk_fma_f32 v[32:33], v[132:133], v[16:17], v[26:27]
	v_pk_fma_f32 v[124:125], v[124:125], v[12:13], v[28:29]
	v_pk_fma_f32 v[28:29], v[122:123], v[10:11], v[30:31]
	v_pk_fma_f32 v[4:5], v[130:131], v[14:15], v[4:5]
	v_lshl_add_u64 v[122:123], v[2:3], 0, v[24:25]
	v_cvt_pk_bf16_f32 v26, v4, v5
	v_cvt_pk_bf16_f32 v27, v32, v33
	v_cvt_pk_bf16_f32 v28, v28, v29
	v_cvt_pk_bf16_f32 v29, v124, v125
	global_load_dwordx4 v[30:33], v[138:139], off offset:256
	s_waitcnt vmcnt(0)
; __device__ __forceinline__ unsigned cvt_pk_bf16(float lo, float hi) { unsigned r; asm volatile("v_cvt_pk_bf16_f32 %0, %1, %2" : "=v"(r) : "v"(lo), "v"(hi)); return r; }
;     __device__ __forceinline__ void operator()(const f32x4 (&acc)[2][2][4][2], const Unit& u, int wr, int wc, int fr, int fq) const {
;     ...
;         if (u.kp < 0) {
;             const float* gp = gate + (size_t)(u.pm >> 3) * NMOD + col0;
;             f32x4 gg[2][2];
; #pragma unroll
;             for (int bj = 0; bj < 2; ++bj)
; #pragma unroll
;                 for (int n = 0; n < 2; ++n) gg[bj][n] = (*(const f32x4*)(gp + bj * HALF + 4 * n) + *(const f32x4*)(gp + MODSB_DELTA + bj * HALF + 4 * n)) * coef;
; #pragma unroll
;             for (int ai = 0; ai < 2; ++ai)
; #pragma unroll
;                 for (int m = 0; m < 4; ++m) {
;                     const int row = row0 + ai * HALF + m * 16;
;                     bf16_t* xp = X + (size_t)row * DM + col0;
; #pragma unroll
;                     for (int bj = 0; bj < 2; ++bj) {
;                         f32x4 b0, b1;
;                         if (BASE16) { const u32x4 bv = *(const u32x4*)(xp + bj * HALF);
;                             b0 = (f32x4){__builtin_bit_cast(float, bv.x << 16), __builtin_bit_cast(float, bv.x & 0xffff0000u), __builtin_bit_cast(float, bv.y << 16), __builtin_bit_cast(float, bv.y & 0xffff0000u)};
;                             b1 = (f32x4){__builtin_bit_cast(float, bv.z << 16), __builtin_bit_cast(float, bv.z & 0xffff0000u), __builtin_bit_cast(float, bv.w << 16), __builtin_bit_cast(float, bv.w & 0xffff0000u)}; }
;                         else { const float* bp = base32 + (size_t)row * DM + col0 + bj * HALF; b0 = __builtin_nontemporal_load((const f32x4*)bp); b1 = __builtin_nontemporal_load((const f32x4*)(bp + 4)); }
;                         const f32x4 o0 = b0 + gg[bj][0] * acc[ai][bj][m][0], o1 = b1 + gg[bj][1] * acc[ai][bj][m][1];
;                         u32x4 w; w.x = cvt_pk_bf16(o0[0], o0[1]); w.y = cvt_pk_bf16(o0[2], o0[3]); w.z = cvt_pk_bf16(o1[0], o1[1]); w.w = cvt_pk_bf16(o1[2], o1[3]);
;                         *(u32x4*)(xp + bj * HALF) = w;
;                     }
;                     if (m & 1) asm volatile("" ::: "memory");
;                 }
	v_lshlrev_b32_e32 v2, 16, v30
	global_store_dwordx4 v[138:139], v[26:29], off
	v_and_b32_e32 v3, 0xffff0000, v30
	v_lshlrev_b32_e32 v4, 16, v31
	v_and_b32_e32 v5, 0xffff0000, v31
	v_lshlrev_b32_e32 v24, 16, v32
	v_and_b32_e32 v25, 0xffff0000, v32
	v_lshlrev_b32_e32 v26, 16, v33
	v_and_b32_e32 v27, 0xffff0000, v33
	v_pk_fma_f32 v[4:5], v[116:117], v[22:23], v[4:5]
	v_pk_fma_f32 v[2:3], v[114:115], v[20:21], v[2:3]
	v_pk_fma_f32 v[26:27], v[112:113], v[18:19], v[26:27]
	v_pk_fma_f32 v[24:25], v[110:111], v[6:7], v[24:25]
	v_cvt_pk_bf16_f32 v2, v2, v3
	v_cvt_pk_bf16_f32 v3, v4, v5
	v_add_co_u32_e32 v28, vcc, s19, v8
	v_cvt_pk_bf16_f32 v4, v24, v25
	v_cvt_pk_bf16_f32 v5, v26, v27
	global_load_dwordx4 v[24:27], v[122:123], off
	s_nop 0
	v_addc_co_u32_e32 v29, vcc, 0, v9, vcc
	global_store_dwordx4 v[138:139], v[2:5], off offset:256
	v_lshl_add_u64 v[30:31], v[8:9], 0, s[30:31]
	s_mov_b32 s19, 0x90000
	s_mov_b64 s[30:31], 0x90000
	s_waitcnt vmcnt(1)
	v_lshlrev_b32_e32 v2, 16, v24
	v_and_b32_e32 v3, 0xffff0000, v24
	v_lshlrev_b32_e32 v4, 16, v25
	v_and_b32_e32 v5, 0xffff0000, v25
	v_lshlrev_b32_e32 v24, 16, v26
	v_and_b32_e32 v25, 0xffff0000, v26
	v_lshlrev_b32_e32 v26, 16, v27
	v_and_b32_e32 v27, 0xffff0000, v27
	v_pk_fma_f32 v[4:5], v[120:121], v[16:17], v[4:5]
	v_pk_fma_f32 v[2:3], v[118:119], v[14:15], v[2:3]
	v_pk_fma_f32 v[26:27], v[108:109], v[12:13], v[26:27]
	v_pk_fma_f32 v[24:25], v[106:107], v[10:11], v[24:25]
	v_cvt_pk_bf16_f32 v2, v2, v3
	v_cvt_pk_bf16_f32 v3, v4, v5
	s_nop 0
	v_cvt_pk_bf16_f32 v4, v24, v25
	v_cvt_pk_bf16_f32 v5, v26, v27
	global_load_dwordx4 v[24:27], v[122:123], off offset:256
	s_nop 0
	global_store_dwordx4 v[122:123], v[2:5], off
	s_waitcnt vmcnt(1)
	s_nop 0
	v_lshlrev_b32_e32 v2, 16, v24
	v_and_b32_e32 v3, 0xffff0000, v24
	v_lshlrev_b32_e32 v4, 16, v25
	v_and_b32_e32 v5, 0xffff0000, v25
	v_lshlrev_b32_e32 v24, 16, v26
	v_and_b32_e32 v25, 0xffff0000, v26
	v_lshlrev_b32_e32 v26, 16, v27
	v_and_b32_e32 v27, 0xffff0000, v27
	v_pk_fma_f32 v[4:5], v[104:105], v[22:23], v[4:5]
	v_pk_fma_f32 v[2:3], v[102:103], v[20:21], v[2:3]
	v_pk_fma_f32 v[26:27], v[100:101], v[18:19], v[26:27]
	v_pk_fma_f32 v[24:25], v[98:99], v[6:7], v[24:25]
	v_cvt_pk_bf16_f32 v2, v2, v3
	v_cvt_pk_bf16_f32 v3, v4, v5
	s_nop 0
	v_cvt_pk_bf16_f32 v4, v24, v25
	v_cvt_pk_bf16_f32 v5, v26, v27
	global_store_dwordx4 v[122:123], v[2:5], off offset:256
	global_load_dwordx4 v[2:5], v[28:29], off
	s_waitcnt vmcnt(0)
	v_lshlrev_b32_e32 v24, 16, v2
	v_and_b32_e32 v25, 0xffff0000, v2
	v_lshlrev_b32_e32 v2, 16, v3
	v_and_b32_e32 v3, 0xffff0000, v3
	v_lshlrev_b32_e32 v26, 16, v4
	v_and_b32_e32 v27, 0xffff0000, v4
	v_lshlrev_b32_e32 v4, 16, v5
	v_and_b32_e32 v5, 0xffff0000, v5
	v_pk_fma_f32 v[32:33], v[96:97], v[16:17], v[2:3]
	v_pk_fma_f32 v[2:3], v[94:95], v[14:15], v[24:25]
	v_pk_fma_f32 v[24:25], v[92:93], v[12:13], v[4:5]
	v_pk_fma_f32 v[4:5], v[90:91], v[10:11], v[26:27]
	v_cvt_pk_bf16_f32 v2, v2, v3
	v_cvt_pk_bf16_f32 v3, v32, v33
	v_add_co_u32_e32 v32, vcc, s19, v8
	v_cvt_pk_bf16_f32 v4, v4, v5
	v_cvt_pk_bf16_f32 v5, v24, v25
	global_load_dwordx4 v[24:27], v[30:31], off offset:256
	s_nop 0
	v_addc_co_u32_e32 v33, vcc, 0, v9, vcc
	global_store_dwordx4 v[28:29], v[2:5], off
	v_lshl_add_u64 v[28:29], v[8:9], 0, s[30:31]
	s_mov_b32 s19, 0xa0000
	s_mov_b64 s[30:31], 0xa0000
	s_waitcnt vmcnt(1)
	v_lshlrev_b32_e32 v2, 16, v24
	v_and_b32_e32 v3, 0xffff0000, v24
	v_lshlrev_b32_e32 v4, 16, v25
	v_and_b32_e32 v5, 0xffff0000, v25
	v_lshlrev_b32_e32 v24, 16, v26
	v_and_b32_e32 v25, 0xffff0000, v26
	v_lshlrev_b32_e32 v26, 16, v27
	v_and_b32_e32 v27, 0xffff0000, v27
	v_pk_fma_f32 v[4:5], v[88:89], v[22:23], v[4:5]
	v_pk_fma_f32 v[2:3], v[86:87], v[20:21], v[2:3]
	v_pk_fma_f32 v[26:27], v[80:81], v[18:19], v[26:27]
	v_pk_fma_f32 v[24:25], v[78:79], v[6:7], v[24:25]
	v_cvt_pk_bf16_f32 v2, v2, v3
	v_cvt_pk_bf16_f32 v3, v4, v5
	s_nop 0
	v_cvt_pk_bf16_f32 v4, v24, v25
	v_cvt_pk_bf16_f32 v5, v26, v27
	global_load_dwordx4 v[24:27], v[32:33], off
	s_nop 0
	global_store_dwordx4 v[30:31], v[2:5], off offset:256
	v_add_co_u32_e32 v30, vcc, s19, v8
	s_mov_b32 s19, 0xb0000
	s_nop 0
	v_addc_co_u32_e32 v31, vcc, 0, v9, vcc
	s_waitcnt vmcnt(1)
; __device__ __forceinline__ unsigned cvt_pk_bf16(float lo, float hi) { unsigned r; asm volatile("v_cvt_pk_bf16_f32 %0, %1, %2" : "=v"(r) : "v"(lo), "v"(hi)); return r; }
;     __device__ __forceinline__ void operator()(const f32x4 (&acc)[2][2][4][2], const Unit& u, int wr, int wc, int fr, int fq) const {
;     ...
;         if (u.kp < 0) {
;             const float* gp = gate + (size_t)(u.pm >> 3) * NMOD + col0;
;             f32x4 gg[2][2];
; #pragma unroll
;             for (int bj = 0; bj < 2; ++bj)
; #pragma unroll
;                 for (int n = 0; n < 2; ++n) gg[bj][n] = (*(const f32x4*)(gp + bj * HALF + 4 * n) + *(const f32x4*)(gp + MODSB_DELTA + bj * HALF + 4 * n)) * coef;
; #pragma unroll
;             for (int ai = 0; ai < 2; ++ai)
; #pragma unroll
;                 for (int m = 0; m < 4; ++m) {
;                     const int row = row0 + ai * HALF + m * 16;
;                     bf16_t* xp = X + (size_t)row * DM + col0;
; #pragma unroll
;                     for (int bj = 0; bj < 2; ++bj) {
;                         f32x4 b0, b1;
;                         if (BASE16) { const u32x4 bv = *(const u32x4*)(xp + bj * HALF);
;                             b0 = (f32x4){__builtin_bit_cast(float, bv.x << 16), __builtin_bit_cast(float, bv.x & 0xffff0000u), __builtin_bit_cast(float, bv.y << 16), __builtin_bit_cast(float, bv.y & 0xffff0000u)};
;                             b1 = (f32x4){__builtin_bit_cast(float, bv.z << 16), __builtin_bit_cast(float, bv.z & 0xffff0000u), __builtin_bit_cast(float, bv.w << 16), __builtin_bit_cast(float, bv.w & 0xffff0000u)}; }
;                         else { const float* bp = base32 + (size_t)row * DM + col0 + bj * HALF; b0 = __builtin_nontemporal_load((const f32x4*)bp); b1 = __builtin_nontemporal_load((const f32x4*)(bp + 4)); }
;                         const f32x4 o0 = b0 + gg[bj][0] * acc[ai][bj][m][0], o1 = b1 + gg[bj][1] * acc[ai][bj][m][1];
;                         u32x4 w; w.x = cvt_pk_bf16(o0[0], o0[1]); w.y = cvt_pk_bf16(o0[2], o0[3]); w.z = cvt_pk_bf16(o1[0], o1[1]); w.w = cvt_pk_bf16(o1[2], o1[3]);
;                         *(u32x4*)(xp + bj * HALF) = w;
;                     }
;                     if (m & 1) asm volatile("" ::: "memory");
;                 }
	v_lshlrev_b32_e32 v2, 16, v24
	v_and_b32_e32 v3, 0xffff0000, v24
	v_lshlrev_b32_e32 v4, 16, v25
	v_and_b32_e32 v5, 0xffff0000, v25
	v_lshlrev_b32_e32 v24, 16, v26
	v_and_b32_e32 v25, 0xffff0000, v26
	v_lshlrev_b32_e32 v26, 16, v27
	v_and_b32_e32 v27, 0xffff0000, v27
	v_pk_fma_f32 v[4:5], v[84:85], v[16:17], v[4:5]
	v_pk_fma_f32 v[2:3], v[82:83], v[14:15], v[2:3]
	v_pk_fma_f32 v[26:27], v[76:77], v[12:13], v[26:27]
	v_pk_fma_f32 v[24:25], v[74:75], v[10:11], v[24:25]
	v_cvt_pk_bf16_f32 v2, v2, v3
	v_cvt_pk_bf16_f32 v3, v4, v5
	s_nop 0
	v_cvt_pk_bf16_f32 v4, v24, v25
	v_cvt_pk_bf16_f32 v5, v26, v27
	global_load_dwordx4 v[24:27], v[28:29], off offset:256
	s_nop 0
	global_store_dwordx4 v[32:33], v[2:5], off
	s_waitcnt vmcnt(1)
	s_nop 0
	v_lshlrev_b32_e32 v2, 16, v24
	v_and_b32_e32 v3, 0xffff0000, v24
	v_lshlrev_b32_e32 v4, 16, v25
	v_and_b32_e32 v5, 0xffff0000, v25
	v_lshlrev_b32_e32 v24, 16, v26
	v_and_b32_e32 v25, 0xffff0000, v26
	v_lshlrev_b32_e32 v26, 16, v27
	v_and_b32_e32 v27, 0xffff0000, v27
	v_pk_fma_f32 v[4:5], v[72:73], v[22:23], v[4:5]
	v_pk_fma_f32 v[2:3], v[70:71], v[20:21], v[2:3]
	v_pk_fma_f32 v[26:27], v[64:65], v[18:19], v[26:27]
	v_pk_fma_f32 v[24:25], v[62:63], v[6:7], v[24:25]
	v_cvt_pk_bf16_f32 v2, v2, v3
	v_cvt_pk_bf16_f32 v3, v4, v5
	s_nop 0
	v_cvt_pk_bf16_f32 v4, v24, v25
	v_cvt_pk_bf16_f32 v5, v26, v27
	global_store_dwordx4 v[28:29], v[2:5], off offset:256
	global_load_dwordx4 v[2:5], v[30:31], off
	v_lshl_add_u64 v[28:29], v[8:9], 0, s[30:31]
	s_mov_b64 s[30:31], 0xb0000
	s_waitcnt vmcnt(0)
	v_lshlrev_b32_e32 v24, 16, v2
	v_and_b32_e32 v25, 0xffff0000, v2
	v_lshlrev_b32_e32 v2, 16, v3
	v_and_b32_e32 v3, 0xffff0000, v3
	v_lshlrev_b32_e32 v26, 16, v4
	v_and_b32_e32 v27, 0xffff0000, v4
	v_lshlrev_b32_e32 v4, 16, v5
	v_and_b32_e32 v5, 0xffff0000, v5
	v_pk_fma_f32 v[32:33], v[68:69], v[16:17], v[2:3]
	v_pk_fma_f32 v[2:3], v[66:67], v[14:15], v[24:25]
	v_pk_fma_f32 v[24:25], v[60:61], v[12:13], v[4:5]
	v_pk_fma_f32 v[4:5], v[58:59], v[10:11], v[26:27]
	v_cvt_pk_bf16_f32 v2, v2, v3
	v_cvt_pk_bf16_f32 v3, v32, v33
	v_add_co_u32_e32 v32, vcc, s19, v8
	v_cvt_pk_bf16_f32 v4, v4, v5
	v_cvt_pk_bf16_f32 v5, v24, v25
	global_load_dwordx4 v[24:27], v[28:29], off offset:256
	s_nop 0
	v_addc_co_u32_e32 v33, vcc, 0, v9, vcc
	global_store_dwordx4 v[30:31], v[2:5], off
	v_lshl_add_u64 v[30:31], v[8:9], 0, s[30:31]
	s_waitcnt vmcnt(1)
	v_lshlrev_b32_e32 v2, 16, v24
	v_and_b32_e32 v3, 0xffff0000, v24
	v_lshlrev_b32_e32 v4, 16, v25
	v_and_b32_e32 v5, 0xffff0000, v25
	v_lshlrev_b32_e32 v24, 16, v26
	v_and_b32_e32 v25, 0xffff0000, v26
	v_lshlrev_b32_e32 v26, 16, v27
	v_and_b32_e32 v27, 0xffff0000, v27
	v_pk_fma_f32 v[4:5], v[56:57], v[22:23], v[4:5]
	v_pk_fma_f32 v[2:3], v[54:55], v[20:21], v[2:3]
	v_pk_fma_f32 v[26:27], v[48:49], v[18:19], v[26:27]
	v_pk_fma_f32 v[24:25], v[46:47], v[6:7], v[24:25]
	v_cvt_pk_bf16_f32 v2, v2, v3
	v_cvt_pk_bf16_f32 v3, v4, v5
	s_nop 0
	v_cvt_pk_bf16_f32 v4, v24, v25
	v_cvt_pk_bf16_f32 v5, v26, v27
	global_load_dwordx4 v[24:27], v[32:33], off
	s_waitcnt vmcnt(0)
	v_lshlrev_b32_e32 v8, 16, v26
	global_store_dwordx4 v[28:29], v[2:5], off offset:256
	v_and_b32_e32 v9, 0xffff0000, v26
	v_pk_fma_f32 v[8:9], v[42:43], v[10:11], v[8:9]
	v_lshlrev_b32_e32 v2, 16, v24
	v_and_b32_e32 v3, 0xffff0000, v24
	v_lshlrev_b32_e32 v4, 16, v25
	v_and_b32_e32 v5, 0xffff0000, v25
	v_lshlrev_b32_e32 v24, 16, v27
	v_and_b32_e32 v25, 0xffff0000, v27
	v_pk_fma_f32 v[4:5], v[52:53], v[16:17], v[4:5]
	v_pk_fma_f32 v[2:3], v[50:51], v[14:15], v[2:3]
	v_pk_fma_f32 v[12:13], v[44:45], v[12:13], v[24:25]
	v_cvt_pk_bf16_f32 v2, v2, v3
	v_cvt_pk_bf16_f32 v3, v4, v5
	v_cvt_pk_bf16_f32 v4, v8, v9
	s_nop 0
	v_cvt_pk_bf16_f32 v5, v12, v13
	global_load_dwordx4 v[8:11], v[30:31], off offset:256
	s_nop 0
	global_store_dwordx4 v[32:33], v[2:5], off
	s_waitcnt vmcnt(1)
	s_nop 0
	v_lshlrev_b32_e32 v2, 16, v8
	v_and_b32_e32 v3, 0xffff0000, v8
	v_lshlrev_b32_e32 v4, 16, v9
	v_and_b32_e32 v5, 0xffff0000, v9
	v_lshlrev_b32_e32 v8, 16, v10
	v_and_b32_e32 v9, 0xffff0000, v10
	v_lshlrev_b32_e32 v10, 16, v11
	v_and_b32_e32 v11, 0xffff0000, v11
	v_pk_fma_f32 v[4:5], v[40:41], v[22:23], v[4:5]
	v_pk_fma_f32 v[2:3], v[38:39], v[20:21], v[2:3]
	v_pk_fma_f32 v[10:11], v[36:37], v[18:19], v[10:11]
	v_pk_fma_f32 v[6:7], v[34:35], v[6:7], v[8:9]
	v_cvt_pk_bf16_f32 v2, v2, v3
	v_cvt_pk_bf16_f32 v3, v4, v5
	s_nop 0
	v_cvt_pk_bf16_f32 v4, v6, v7
	v_cvt_pk_bf16_f32 v5, v10, v11
	global_store_dwordx4 v[30:31], v[2:5], off offset:256
	s_andn2_b64 vcc, exec, s[22:23]
	s_mov_b64 s[22:23], -1
	s_cbranch_vccnz .LBB0_1181

; __device__ __forceinline__ float silu_f(float x) { return x * __builtin_amdgcn_rcpf(1.0f + __builtin_amdgcn_exp2f(-1.4426950408889634f * x)); }
;     __device__ __forceinline__ void operator()(const f32x4 (&acc)[2][2][4][2], const Unit& u, int wr, int wc, int fr, int fq) const {
;         const int row0 = u.pm * BM + wr * 64 + fr, col0 = u.pn * HALF + wc * 32 + 8 * fq;
; #pragma unroll
;         for (int ai = 0; ai < 2; ++ai)
; #pragma unroll
;             for (int m = 0; m < 4; ++m) {
;                 unsigned char* rowp = O + (size_t)(row0 + ai * HALF + m * 16) * DFF + col0;
;                 const f32x4 g0 = acc[ai][0][m][0], g1 = acc[ai][0][m][1], u0 = acc[ai][1][m][0], u1 = acc[ai][1][m][1];
;                 u32x2 w;
;                 w.x = pk4_fp8_nc(silu_f(g0[0]) * u0[0], silu_f(g0[1]) * u0[1], silu_f(g0[2]) * u0[2], silu_f(g0[3]) * u0[3]);
;                 w.y = pk4_fp8_nc(silu_f(g1[0]) * u1[0], silu_f(g1[1]) * u1[1], silu_f(g1[2]) * u1[2], silu_f(g1[3]) * u1[3]);
;                 *(u32x2*)rowp = w;
;             }
.LBB0_1425:
	s_mov_b32 s98, 0xbfb8aa3b
	s_mov_b32 s99, 0xbfb8aa3b
	v_lshl_add_u32 v230, s18, 8, v189
	v_lshl_or_b32 v231, s44, 7, v190
	v_mad_u32_u24 v197, v230, s43, v231
	v_pk_mul_f32 v[198:199], v[158:159], s[98:99] op_sel_hi:[1,0]
	v_pk_mul_f32 v[200:201], v[160:161], s[98:99] op_sel_hi:[1,0]
	v_pk_mul_f32 v[202:203], v[150:151], s[98:99] op_sel_hi:[1,0]
	v_pk_mul_f32 v[204:205], v[152:153], s[98:99] op_sel_hi:[1,0]
	v_pk_mul_f32 v[206:207], v[142:143], s[98:99] op_sel_hi:[1,0]
	v_pk_mul_f32 v[208:209], v[144:145], s[98:99] op_sel_hi:[1,0]
	v_pk_mul_f32 v[210:211], v[134:135], s[98:99] op_sel_hi:[1,0]
	v_pk_mul_f32 v[212:213], v[136:137], s[98:99] op_sel_hi:[1,0]
	v_exp_f32_e32 v198, v198
	v_exp_f32_e32 v199, v199
	v_exp_f32_e32 v200, v200
	v_exp_f32_e32 v201, v201
	v_exp_f32_e32 v202, v202
	v_exp_f32_e32 v203, v203
	v_exp_f32_e32 v204, v204
	v_exp_f32_e32 v205, v205
	v_exp_f32_e32 v206, v206
	v_exp_f32_e32 v207, v207
	v_exp_f32_e32 v208, v208
	v_exp_f32_e32 v209, v209
	v_exp_f32_e32 v210, v210
	v_exp_f32_e32 v211, v211
	v_exp_f32_e32 v212, v212
	v_exp_f32_e32 v213, v213
	v_pk_add_f32 v[198:199], v[198:199], 1.0 op_sel_hi:[1,0]
	v_pk_add_f32 v[200:201], v[200:201], 1.0 op_sel_hi:[1,0]
	v_pk_add_f32 v[202:203], v[202:203], 1.0 op_sel_hi:[1,0]
	v_pk_add_f32 v[204:205], v[204:205], 1.0 op_sel_hi:[1,0]
	v_pk_add_f32 v[206:207], v[206:207], 1.0 op_sel_hi:[1,0]
	v_pk_add_f32 v[208:209], v[208:209], 1.0 op_sel_hi:[1,0]
	v_pk_add_f32 v[210:211], v[210:211], 1.0 op_sel_hi:[1,0]
	v_pk_add_f32 v[212:213], v[212:213], 1.0 op_sel_hi:[1,0]
	v_rcp_f32_e32 v198, v198
	v_rcp_f32_e32 v199, v199
	v_rcp_f32_e32 v200, v200
	v_rcp_f32_e32 v201, v201
	v_rcp_f32_e32 v202, v202
	v_rcp_f32_e32 v203, v203
	v_rcp_f32_e32 v204, v204
	v_rcp_f32_e32 v205, v205
	v_rcp_f32_e32 v206, v206
	v_rcp_f32_e32 v207, v207
	v_rcp_f32_e32 v208, v208
	v_rcp_f32_e32 v209, v209
	v_rcp_f32_e32 v210, v210
	v_rcp_f32_e32 v211, v211
	v_rcp_f32_e32 v212, v212
	v_rcp_f32_e32 v213, v213
	v_pk_mul_f32 v[198:199], v[158:159], v[198:199]
	v_pk_mul_f32 v[200:201], v[160:161], v[200:201]
	v_pk_mul_f32 v[202:203], v[150:151], v[202:203]
	v_pk_mul_f32 v[204:205], v[152:153], v[204:205]
	v_pk_mul_f32 v[206:207], v[142:143], v[206:207]
	v_pk_mul_f32 v[208:209], v[144:145], v[208:209]
	v_pk_mul_f32 v[210:211], v[134:135], v[210:211]
	v_pk_mul_f32 v[212:213], v[136:137], v[212:213]
	v_pk_mul_f32 v[198:199], v[198:199], v[154:155]
	v_pk_mul_f32 v[200:201], v[200:201], v[156:157]
	v_pk_mul_f32 v[202:203], v[202:203], v[146:147]
	v_pk_mul_f32 v[204:205], v[204:205], v[148:149]
	v_pk_mul_f32 v[206:207], v[206:207], v[138:139]
	v_pk_mul_f32 v[208:209], v[208:209], v[140:141]
	v_pk_mul_f32 v[210:211], v[210:211], v[130:131]
	v_pk_mul_f32 v[212:213], v[212:213], v[132:133]
	v_cvt_pk_fp8_f32 v214, v198, v199
	v_cvt_pk_fp8_f32 v215, v202, v203
	v_cvt_pk_fp8_f32 v216, v206, v207
	v_cvt_pk_fp8_f32 v217, v210, v211
	v_cvt_pk_fp8_f32 v214, v200, v201 op_sel:[0,0,1]
	v_cvt_pk_fp8_f32 v215, v204, v205 op_sel:[0,0,1]
	v_cvt_pk_fp8_f32 v216, v208, v209 op_sel:[0,0,1]
	v_cvt_pk_fp8_f32 v217, v212, v213 op_sel:[0,0,1]
	global_store_dwordx2 v197, v[214:215], s[4:5]
	s_add_u32 s20, s4, 0x16000
	s_addc_u32 s21, s5, 0
	global_store_dwordx2 v197, v[216:217], s[20:21]
	v_pk_mul_f32 v[198:199], v[126:127], s[98:99] op_sel_hi:[1,0]
	v_pk_mul_f32 v[200:201], v[128:129], s[98:99] op_sel_hi:[1,0]
	v_pk_mul_f32 v[202:203], v[118:119], s[98:99] op_sel_hi:[1,0]
	v_pk_mul_f32 v[204:205], v[120:121], s[98:99] op_sel_hi:[1,0]
	v_pk_mul_f32 v[206:207], v[110:111], s[98:99] op_sel_hi:[1,0]
	v_pk_mul_f32 v[208:209], v[112:113], s[98:99] op_sel_hi:[1,0]
	v_pk_mul_f32 v[210:211], v[102:103], s[98:99] op_sel_hi:[1,0]
	v_pk_mul_f32 v[212:213], v[104:105], s[98:99] op_sel_hi:[1,0]
	v_exp_f32_e32 v198, v198
	v_exp_f32_e32 v199, v199
	v_exp_f32_e32 v200, v200
	v_exp_f32_e32 v201, v201
	v_exp_f32_e32 v202, v202
	v_exp_f32_e32 v203, v203
	v_exp_f32_e32 v204, v204
	v_exp_f32_e32 v205, v205
	v_exp_f32_e32 v206, v206
	v_exp_f32_e32 v207, v207
	v_exp_f32_e32 v208, v208
	v_exp_f32_e32 v209, v209
	v_exp_f32_e32 v210, v210
	v_exp_f32_e32 v211, v211
	v_exp_f32_e32 v212, v212
	v_exp_f32_e32 v213, v213
	v_pk_add_f32 v[198:199], v[198:199], 1.0 op_sel_hi:[1,0]
	v_pk_add_f32 v[200:201], v[200:201], 1.0 op_sel_hi:[1,0]
	v_pk_add_f32 v[202:203], v[202:203], 1.0 op_sel_hi:[1,0]
	v_pk_add_f32 v[204:205], v[204:205], 1.0 op_sel_hi:[1,0]
	v_pk_add_f32 v[206:207], v[206:207], 1.0 op_sel_hi:[1,0]
	v_pk_add_f32 v[208:209], v[208:209], 1.0 op_sel_hi:[1,0]
	v_pk_add_f32 v[210:211], v[210:211], 1.0 op_sel_hi:[1,0]
	v_pk_add_f32 v[212:213], v[212:213], 1.0 op_sel_hi:[1,0]
	v_rcp_f32_e32 v198, v198
	v_rcp_f32_e32 v199, v199
	v_rcp_f32_e32 v200, v200
	v_rcp_f32_e32 v201, v201
	v_rcp_f32_e32 v202, v202
	v_rcp_f32_e32 v203, v203
	v_rcp_f32_e32 v204, v204
	v_rcp_f32_e32 v205, v205
	v_rcp_f32_e32 v206, v206
	v_rcp_f32_e32 v207, v207
	v_rcp_f32_e32 v208, v208
	v_rcp_f32_e32 v209, v209
	v_rcp_f32_e32 v210, v210
	v_rcp_f32_e32 v211, v211
	v_rcp_f32_e32 v212, v212
	v_rcp_f32_e32 v213, v213
	v_pk_mul_f32 v[198:199], v[126:127], v[198:199]
	v_pk_mul_f32 v[200:201], v[128:129], v[200:201]
	v_pk_mul_f32 v[202:203], v[118:119], v[202:203]
	v_pk_mul_f32 v[204:205], v[120:121], v[204:205]
	v_pk_mul_f32 v[206:207], v[110:111], v[206:207]
	v_pk_mul_f32 v[208:209], v[112:113], v[208:209]
	v_pk_mul_f32 v[210:211], v[102:103], v[210:211]
	v_pk_mul_f32 v[212:213], v[104:105], v[212:213]
	v_pk_mul_f32 v[198:199], v[198:199], v[122:123]
	v_pk_mul_f32 v[200:201], v[200:201], v[124:125]
	v_pk_mul_f32 v[202:203], v[202:203], v[114:115]
	v_pk_mul_f32 v[204:205], v[204:205], v[116:117]
; __device__ __forceinline__ float silu_f(float x) { return x * __builtin_amdgcn_rcpf(1.0f + __builtin_amdgcn_exp2f(-1.4426950408889634f * x)); }
;     __device__ __forceinline__ void operator()(const f32x4 (&acc)[2][2][4][2], const Unit& u, int wr, int wc, int fr, int fq) const {
;         const int row0 = u.pm * BM + wr * 64 + fr, col0 = u.pn * HALF + wc * 32 + 8 * fq;
; #pragma unroll
;         for (int ai = 0; ai < 2; ++ai)
; #pragma unroll
;             for (int m = 0; m < 4; ++m) {
;                 unsigned char* rowp = O + (size_t)(row0 + ai * HALF + m * 16) * DFF + col0;
;                 const f32x4 g0 = acc[ai][0][m][0], g1 = acc[ai][0][m][1], u0 = acc[ai][1][m][0], u1 = acc[ai][1][m][1];
;                 u32x2 w;
;                 w.x = pk4_fp8_nc(silu_f(g0[0]) * u0[0], silu_f(g0[1]) * u0[1], silu_f(g0[2]) * u0[2], silu_f(g0[3]) * u0[3]);
;                 w.y = pk4_fp8_nc(silu_f(g1[0]) * u1[0], silu_f(g1[1]) * u1[1], silu_f(g1[2]) * u1[2], silu_f(g1[3]) * u1[3]);
;                 *(u32x2*)rowp = w;
;             }
	v_pk_mul_f32 v[206:207], v[206:207], v[106:107]
	v_pk_mul_f32 v[208:209], v[208:209], v[108:109]
	v_pk_mul_f32 v[210:211], v[210:211], v[98:99]
	v_pk_mul_f32 v[212:213], v[212:213], v[100:101]
	v_cvt_pk_fp8_f32 v218, v198, v199
	v_cvt_pk_fp8_f32 v219, v202, v203
	v_cvt_pk_fp8_f32 v220, v206, v207
	v_cvt_pk_fp8_f32 v221, v210, v211
	v_cvt_pk_fp8_f32 v218, v200, v201 op_sel:[0,0,1]
	v_cvt_pk_fp8_f32 v219, v204, v205 op_sel:[0,0,1]
	v_cvt_pk_fp8_f32 v220, v208, v209 op_sel:[0,0,1]
	v_cvt_pk_fp8_f32 v221, v212, v213 op_sel:[0,0,1]
	s_add_u32 s20, s4, 0x2c000
	s_addc_u32 s21, s5, 0
	global_store_dwordx2 v197, v[218:219], s[20:21]
	s_add_u32 s20, s4, 0x42000
	s_addc_u32 s21, s5, 0
	global_store_dwordx2 v197, v[220:221], s[20:21]
	v_pk_mul_f32 v[198:199], v[94:95], s[98:99] op_sel_hi:[1,0]
	v_pk_mul_f32 v[200:201], v[96:97], s[98:99] op_sel_hi:[1,0]
	v_pk_mul_f32 v[202:203], v[86:87], s[98:99] op_sel_hi:[1,0]
	v_pk_mul_f32 v[204:205], v[88:89], s[98:99] op_sel_hi:[1,0]
	v_pk_mul_f32 v[206:207], v[78:79], s[98:99] op_sel_hi:[1,0]
	v_pk_mul_f32 v[208:209], v[80:81], s[98:99] op_sel_hi:[1,0]
	v_pk_mul_f32 v[210:211], v[70:71], s[98:99] op_sel_hi:[1,0]
	v_pk_mul_f32 v[212:213], v[72:73], s[98:99] op_sel_hi:[1,0]
	v_exp_f32_e32 v198, v198
	v_exp_f32_e32 v199, v199
	v_exp_f32_e32 v200, v200
	v_exp_f32_e32 v201, v201
	v_exp_f32_e32 v202, v202
	v_exp_f32_e32 v203, v203
	v_exp_f32_e32 v204, v204
	v_exp_f32_e32 v205, v205
	v_exp_f32_e32 v206, v206
	v_exp_f32_e32 v207, v207
	v_exp_f32_e32 v208, v208
	v_exp_f32_e32 v209, v209
	v_exp_f32_e32 v210, v210
	v_exp_f32_e32 v211, v211
	v_exp_f32_e32 v212, v212
	v_exp_f32_e32 v213, v213
	v_pk_add_f32 v[198:199], v[198:199], 1.0 op_sel_hi:[1,0]
	v_pk_add_f32 v[200:201], v[200:201], 1.0 op_sel_hi:[1,0]
	v_pk_add_f32 v[202:203], v[202:203], 1.0 op_sel_hi:[1,0]
	v_pk_add_f32 v[204:205], v[204:205], 1.0 op_sel_hi:[1,0]
	v_pk_add_f32 v[206:207], v[206:207], 1.0 op_sel_hi:[1,0]
	v_pk_add_f32 v[208:209], v[208:209], 1.0 op_sel_hi:[1,0]
	v_pk_add_f32 v[210:211], v[210:211], 1.0 op_sel_hi:[1,0]
	v_pk_add_f32 v[212:213], v[212:213], 1.0 op_sel_hi:[1,0]
	v_rcp_f32_e32 v198, v198
	v_rcp_f32_e32 v199, v199
	v_rcp_f32_e32 v200, v200
	v_rcp_f32_e32 v201, v201
	v_rcp_f32_e32 v202, v202
	v_rcp_f32_e32 v203, v203
	v_rcp_f32_e32 v204, v204
	v_rcp_f32_e32 v205, v205
	v_rcp_f32_e32 v206, v206
	v_rcp_f32_e32 v207, v207
	v_rcp_f32_e32 v208, v208
	v_rcp_f32_e32 v209, v209
	v_rcp_f32_e32 v210, v210
	v_rcp_f32_e32 v211, v211
	v_rcp_f32_e32 v212, v212
	v_rcp_f32_e32 v213, v213
	v_pk_mul_f32 v[198:199], v[94:95], v[198:199]
	v_pk_mul_f32 v[200:201], v[96:97], v[200:201]
	v_pk_mul_f32 v[202:203], v[86:87], v[202:203]
	v_pk_mul_f32 v[204:205], v[88:89], v[204:205]
	v_pk_mul_f32 v[206:207], v[78:79], v[206:207]
	v_pk_mul_f32 v[208:209], v[80:81], v[208:209]
	v_pk_mul_f32 v[210:211], v[70:71], v[210:211]
	v_pk_mul_f32 v[212:213], v[72:73], v[212:213]
	v_pk_mul_f32 v[198:199], v[198:199], v[90:91]
	v_pk_mul_f32 v[200:201], v[200:201], v[92:93]
	v_pk_mul_f32 v[202:203], v[202:203], v[82:83]
	v_pk_mul_f32 v[204:205], v[204:205], v[84:85]
	v_pk_mul_f32 v[206:207], v[206:207], v[74:75]
	v_pk_mul_f32 v[208:209], v[208:209], v[76:77]
	v_pk_mul_f32 v[210:211], v[210:211], v[66:67]
	v_pk_mul_f32 v[212:213], v[212:213], v[68:69]
	v_cvt_pk_fp8_f32 v222, v198, v199
	v_cvt_pk_fp8_f32 v223, v202, v203
	v_cvt_pk_fp8_f32 v224, v206, v207
	v_cvt_pk_fp8_f32 v225, v210, v211
	v_cvt_pk_fp8_f32 v222, v200, v201 op_sel:[0,0,1]
	v_cvt_pk_fp8_f32 v223, v204, v205 op_sel:[0,0,1]
	v_cvt_pk_fp8_f32 v224, v208, v209 op_sel:[0,0,1]
	v_cvt_pk_fp8_f32 v225, v212, v213 op_sel:[0,0,1]
	s_add_u32 s20, s4, 0xb0000
	s_addc_u32 s21, s5, 0
	global_store_dwordx2 v197, v[222:223], s[20:21]
	s_add_u32 s20, s4, 0xc6000
	s_addc_u32 s21, s5, 0
	global_store_dwordx2 v197, v[224:225], s[20:21]
	v_pk_mul_f32 v[198:199], v[62:63], s[98:99] op_sel_hi:[1,0]
	v_pk_mul_f32 v[200:201], v[64:65], s[98:99] op_sel_hi:[1,0]
	v_pk_mul_f32 v[202:203], v[54:55], s[98:99] op_sel_hi:[1,0]
	v_pk_mul_f32 v[204:205], v[56:57], s[98:99] op_sel_hi:[1,0]
	v_pk_mul_f32 v[206:207], v[46:47], s[98:99] op_sel_hi:[1,0]
	v_pk_mul_f32 v[208:209], v[48:49], s[98:99] op_sel_hi:[1,0]
	v_pk_mul_f32 v[210:211], v[38:39], s[98:99] op_sel_hi:[1,0]
	v_pk_mul_f32 v[212:213], v[40:41], s[98:99] op_sel_hi:[1,0]
	v_exp_f32_e32 v198, v198
	v_exp_f32_e32 v199, v199
	v_exp_f32_e32 v200, v200
	v_exp_f32_e32 v201, v201
	v_exp_f32_e32 v202, v202
	v_exp_f32_e32 v203, v203
	v_exp_f32_e32 v204, v204
	v_exp_f32_e32 v205, v205
	v_exp_f32_e32 v206, v206
	v_exp_f32_e32 v207, v207
	v_exp_f32_e32 v208, v208
	v_exp_f32_e32 v209, v209
	v_exp_f32_e32 v210, v210
	v_exp_f32_e32 v211, v211
	v_exp_f32_e32 v212, v212
	v_exp_f32_e32 v213, v213
	v_pk_add_f32 v[198:199], v[198:199], 1.0 op_sel_hi:[1,0]
	v_pk_add_f32 v[200:201], v[200:201], 1.0 op_sel_hi:[1,0]
	v_pk_add_f32 v[202:203], v[202:203], 1.0 op_sel_hi:[1,0]
	v_pk_add_f32 v[204:205], v[204:205], 1.0 op_sel_hi:[1,0]
	v_pk_add_f32 v[206:207], v[206:207], 1.0 op_sel_hi:[1,0]
	v_pk_add_f32 v[208:209], v[208:209], 1.0 op_sel_hi:[1,0]
	v_pk_add_f32 v[210:211], v[210:211], 1.0 op_sel_hi:[1,0]
	v_pk_add_f32 v[212:213], v[212:213], 1.0 op_sel_hi:[1,0]
	v_rcp_f32_e32 v198, v198
	v_rcp_f32_e32 v199, v199
	v_rcp_f32_e32 v200, v200
	v_rcp_f32_e32 v201, v201
	v_rcp_f32_e32 v202, v202
	v_rcp_f32_e32 v203, v203
	v_rcp_f32_e32 v204, v204
	v_rcp_f32_e32 v205, v205
	v_rcp_f32_e32 v206, v206
	v_rcp_f32_e32 v207, v207
	v_rcp_f32_e32 v208, v208
	v_rcp_f32_e32 v209, v209
	v_rcp_f32_e32 v210, v210
	v_rcp_f32_e32 v211, v211
	v_rcp_f32_e32 v212, v212
	v_rcp_f32_e32 v213, v213
	v_pk_mul_f32 v[198:199], v[62:63], v[198:199]
	v_pk_mul_f32 v[200:201], v[64:65], v[200:201]
	v_pk_mul_f32 v[202:203], v[54:55], v[202:203]
	v_pk_mul_f32 v[204:205], v[56:57], v[204:205]
	v_pk_mul_f32 v[206:207], v[46:47], v[206:207]
	v_pk_mul_f32 v[208:209], v[48:49], v[208:209]
	v_pk_mul_f32 v[210:211], v[38:39], v[210:211]
	v_pk_mul_f32 v[212:213], v[40:41], v[212:213]
	v_pk_mul_f32 v[198:199], v[198:199], v[58:59]
	v_pk_mul_f32 v[200:201], v[200:201], v[60:61]
	v_pk_mul_f32 v[202:203], v[202:203], v[50:51]
	v_pk_mul_f32 v[204:205], v[204:205], v[52:53]
	v_pk_mul_f32 v[206:207], v[206:207], v[42:43]
	v_pk_mul_f32 v[208:209], v[208:209], v[44:45]
	v_pk_mul_f32 v[210:211], v[210:211], v[34:35]
	v_pk_mul_f32 v[212:213], v[212:213], v[36:37]
	v_cvt_pk_fp8_f32 v226, v198, v199
	v_cvt_pk_fp8_f32 v227, v202, v203
	v_cvt_pk_fp8_f32 v228, v206, v207
	v_cvt_pk_fp8_f32 v229, v210, v211
	v_cvt_pk_fp8_f32 v226, v200, v201 op_sel:[0,0,1]
	v_cvt_pk_fp8_f32 v227, v204, v205 op_sel:[0,0,1]
	v_cvt_pk_fp8_f32 v228, v208, v209 op_sel:[0,0,1]
	v_cvt_pk_fp8_f32 v229, v212, v213 op_sel:[0,0,1]
	s_add_u32 s20, s4, 0xdc000
	s_addc_u32 s21, s5, 0
	global_store_dwordx2 v197, v[226:227], s[20:21]
	s_add_u32 s20, s4, 0xf2000
	s_addc_u32 s21, s5, 0
	global_store_dwordx2 v197, v[228:229], s[20:21]
	s_andn2_b64 vcc, exec, s[2:3]
	s_mov_b64 s[2:3], -1
	s_cbranch_vccnz .LBB0_1418
; #define PG8_BAR __builtin_amdgcn_s_barrier()
; #define PG8_BAR __builtin_amdgcn_s_barrier()
; template <class Epi, class Sched, bool ALIGN_EPI = false>
; __device__ __forceinline__ void gemm_phase(PG8_LAS unsigned char* lds, const Gemm g, const Sched& S, const Epi& E) {
;     ...
;         E(acc, cur, wr, wc, fr, fq); S.done(cur);
;         if (!has_next) break;
; #pragma unroll
;         for (int a = 0; a < 2; ++a)
; #pragma unroll
;             for (int b = 0; b < 2; ++b)
; #pragma unroll
;                 for (int m = 0; m < 4; ++m)
; #pragma unroll
;                     for (int n = 0; n < 2; ++n) acc[a][b][m][n] = (f32x4){0.f, 0.f, 0.f, 0.f};
;         cur = nxt; cA = nA; cB = nB; ++ui;
;         if constexpr (ALIGN_EPI) { if (wr == 1) PG8_BAR; }
;     }
	s_andn2_b64 vcc, exec, s[0:1]
	s_cbranch_vccnz .LBB0_1417
	s_barrier
	s_branch .LBB0_1417

; __device__ __forceinline__ unsigned cvt_pk_bf16(float lo, float hi) { unsigned r; asm volatile("v_cvt_pk_bf16_f32 %0, %1, %2" : "=v"(r) : "v"(lo), "v"(hi)); return r; }
;     __device__ __forceinline__ void operator()(const f32x4 (&acc)[2][2][4][2], const Unit& u, int wr, int wc, int fr, int fq) const {
;     ...
; #pragma unroll
;             for (int ai = 0; ai < 2; ++ai)
; #pragma unroll
;                 for (int m = 0; m < 4; ++m) {
;                     const int row = row0 + ai * HALF + m * 16;
;                     const float* gp = gate + (size_t)modrow_of(row) * NMOD + col0;
;                     bf16_t* op = (bf16_t*)((char*)X + SLAB_MINUS_X) + ((size_t)u.kp * MS + (row - MP)) * DM + col0;
; #pragma unroll
;                     for (int bj = 0; bj < 2; ++bj) {
;                         const f32x4 g0 = (*(const f32x4*)(gp + bj * HALF) + *(const f32x4*)(gp + MODSB_DELTA + bj * HALF)) * coef, g1 = (*(const f32x4*)(gp + bj * HALF + 4) + *(const f32x4*)(gp + MODSB_DELTA + bj * HALF + 4)) * coef;
;                         const f32x4 o0 = g0 * acc[ai][bj][m][0], o1 = g1 * acc[ai][bj][m][1];
;                         u32x4 w; w.x = cvt_pk_bf16(o0[0], o0[1]); w.y = cvt_pk_bf16(o0[2], o0[3]); w.z = cvt_pk_bf16(o1[0], o1[1]); w.w = cvt_pk_bf16(o1[2], o1[3]);
;                         *(u32x4*)(op + bj * HALF) = w;
;                     }
;                     if (m & 1) asm volatile("" ::: "memory");
;                 }
.LBB0_1514:
	s_lshl_b32 s38, s77, 8
	s_nop 15
	s_nop 15
	s_add_i32 s38, s38, s60
	v_or_b32_e32 v10, s38, v183
	v_lshl_or_b32 v8, s78, 8, v186
	s_mov_b64 s[34:35], -1
	s_andn2_b64 vcc, exec, s[36:37]
	v_ashrrev_i32_e32 v9, 31, v8
	v_or_b32_e32 v6, 16, v10
	v_or_b32_e32 v4, 32, v10
	v_or_b32_e32 v2, 48, v10
	s_cbranch_vccnz .LBB0_1517
	v_add_u32_e32 v174, 0xffffe000, v10
	s_ashr_i32 s31, s38, 11
	v_lshrrev_b32_e32 v3, 2, v174
	v_or_b32_e32 v3, 4, v3
	v_mov_b32_e32 v5, s31
	v_cmp_gt_i32_e32 vcc, s57, v10
	v_mov_b64_e32 v[14:15], s[10:11]
	v_lshlrev_b64 v[16:17], 2, v[8:9]
	v_cndmask_b32_e32 v3, v3, v5, vcc
	v_mad_i64_i32 v[12:13], s[34:35], v3, s56, v[14:15]
	v_lshl_add_u64 v[176:177], v[12:13], 0, v[16:17]
	v_add_co_u32_e32 v178, vcc, s65, v176
	v_lshl_add_u64 v[12:13], v[176:177], 0, s[16:17]
	s_nop 0
	v_addc_co_u32_e32 v179, vcc, 0, v177, vcc
	global_load_dwordx4 v[18:21], v[176:177], off offset:16
	global_load_dwordx4 v[22:25], v[176:177], off
	global_load_dwordx4 v[26:29], v[178:179], off
	global_load_dwordx4 v[30:33], v[12:13], off offset:16
	s_mov_b32 s31, s1
	s_lshl_b64 s[30:31], s[30:31], 21
	v_ashrrev_i32_e32 v175, 31, v174
	s_add_u32 s30, s58, s30
	v_lshlrev_b64 v[174:175], 12, v[174:175]
	s_addc_u32 s31, s59, s31
	v_lshlrev_b64 v[12:13], 1, v[8:9]
	v_lshl_add_u64 v[174:175], s[30:31], 0, v[174:175]
	v_lshl_add_u64 v[174:175], v[174:175], 0, v[12:13]
	v_cmp_gt_i32_e32 vcc, s57, v6
	s_addk_i32 s38, 0x80
	s_waitcnt vmcnt(0)
	v_pk_add_f32 v[24:25], v[24:25], v[28:29]
	v_pk_add_f32 v[20:21], v[20:21], v[32:33]
	v_pk_add_f32 v[18:19], v[18:19], v[30:31]
	v_pk_add_f32 v[22:23], v[22:23], v[26:27]
	v_pk_mul_f32 v[20:21], v[20:21], 0.5 op_sel_hi:[1,0]
	v_pk_mul_f32 v[18:19], v[18:19], 0.5 op_sel_hi:[1,0]
	v_pk_mul_f32 v[24:25], v[24:25], 0.5 op_sel_hi:[1,0]
	v_pk_mul_f32 v[22:23], v[22:23], 0.5 op_sel_hi:[1,0]
	v_pk_mul_f32 v[26:27], v[156:157], v[20:21]
	v_pk_mul_f32 v[20:21], v[154:155], v[18:19]
	v_pk_mul_f32 v[24:25], v[160:161], v[24:25]
	v_pk_mul_f32 v[22:23], v[158:159], v[22:23]
	v_lshl_add_u64 v[30:31], v[176:177], 0, s[18:19]
	v_cvt_pk_bf16_f32 v18, v22, v23
	v_cvt_pk_bf16_f32 v19, v24, v25
	v_cvt_pk_bf16_f32 v20, v20, v21
	v_cvt_pk_bf16_f32 v21, v26, v27
	global_store_dwordx4 v[174:175], v[18:21], off
	global_load_dwordx4 v[18:21], v[176:177], off offset:528
	s_nop 0
	global_load_dwordx4 v[22:25], v[176:177], off offset:512
	global_load_dwordx4 v[26:29], v[178:179], off offset:512
	v_add_u32_e32 v176, 0xffffe010, v10
	global_load_dwordx4 v[30:33], v[30:31], off offset:16
	v_lshrrev_b32_e32 v3, 2, v176
	v_add_u32_e32 v3, 4, v3
	v_cndmask_b32_e32 v3, v3, v5, vcc
	v_mad_i64_i32 v[178:179], s[34:35], v3, s56, v[14:15]
	v_lshl_add_u64 v[178:179], v[178:179], 0, v[16:17]
	v_add_co_u32_e32 v180, vcc, s65, v178
	v_ashrrev_i32_e32 v177, 31, v176
	s_nop 0
	v_addc_co_u32_e32 v181, vcc, 0, v179, vcc
	v_cmp_gt_i32_e32 vcc, s57, v4
	s_waitcnt vmcnt(1)
	v_pk_add_f32 v[24:25], v[24:25], v[28:29]
	v_pk_add_f32 v[22:23], v[22:23], v[26:27]
	s_waitcnt vmcnt(0)
	v_pk_add_f32 v[20:21], v[20:21], v[32:33]
	v_pk_add_f32 v[18:19], v[18:19], v[30:31]
	v_pk_mul_f32 v[20:21], v[20:21], 0.5 op_sel_hi:[1,0]
	v_pk_mul_f32 v[18:19], v[18:19], 0.5 op_sel_hi:[1,0]
	v_pk_mul_f32 v[24:25], v[24:25], 0.5 op_sel_hi:[1,0]
	v_pk_mul_f32 v[22:23], v[22:23], 0.5 op_sel_hi:[1,0]
	v_pk_mul_f32 v[26:27], v[144:145], v[20:21]
	v_pk_mul_f32 v[20:21], v[142:143], v[18:19]
	v_pk_mul_f32 v[24:25], v[148:149], v[24:25]
	v_pk_mul_f32 v[22:23], v[146:147], v[22:23]
	v_lshl_add_u64 v[30:31], v[178:179], 0, s[16:17]
	v_cvt_pk_bf16_f32 v18, v22, v23
	v_cvt_pk_bf16_f32 v19, v24, v25
	v_cvt_pk_bf16_f32 v20, v20, v21
	v_cvt_pk_bf16_f32 v21, v26, v27
	global_store_dwordx4 v[174:175], v[18:21], off offset:256
	global_load_dwordx4 v[18:21], v[178:179], off offset:16
	s_nop 0
	global_load_dwordx4 v[22:25], v[178:179], off
	global_load_dwordx4 v[26:29], v[180:181], off
	v_lshlrev_b64 v[174:175], 12, v[176:177]
	global_load_dwordx4 v[30:33], v[30:31], off offset:16
	v_lshl_add_u64 v[174:175], s[30:31], 0, v[174:175]
	v_lshl_add_u64 v[174:175], v[174:175], 0, v[12:13]
	v_add_u32_e32 v176, 0xffffe020, v10
	v_lshrrev_b32_e32 v3, 2, v176
	v_or_b32_e32 v3, 4, v3
	v_cndmask_b32_e32 v3, v3, v5, vcc
	v_ashrrev_i32_e32 v177, 31, v176
	s_waitcnt vmcnt(1)
	v_pk_add_f32 v[24:25], v[24:25], v[28:29]
	v_pk_add_f32 v[22:23], v[22:23], v[26:27]
	s_waitcnt vmcnt(0)
	v_pk_add_f32 v[20:21], v[20:21], v[32:33]
	v_pk_add_f32 v[18:19], v[18:19], v[30:31]
	v_pk_mul_f32 v[20:21], v[20:21], 0.5 op_sel_hi:[1,0]
	v_pk_mul_f32 v[18:19], v[18:19], 0.5 op_sel_hi:[1,0]
	v_pk_mul_f32 v[24:25], v[24:25], 0.5 op_sel_hi:[1,0]
	v_pk_mul_f32 v[22:23], v[22:23], 0.5 op_sel_hi:[1,0]
	v_pk_mul_f32 v[26:27], v[140:141], v[20:21]
	v_pk_mul_f32 v[20:21], v[138:139], v[18:19]
	v_pk_mul_f32 v[24:25], v[152:153], v[24:25]
	v_pk_mul_f32 v[22:23], v[150:151], v[22:23]
	v_lshl_add_u64 v[30:31], v[178:179], 0, s[18:19]
	v_cvt_pk_bf16_f32 v18, v22, v23
	v_cvt_pk_bf16_f32 v19, v24, v25
	v_cvt_pk_bf16_f32 v20, v20, v21
	v_cvt_pk_bf16_f32 v21, v26, v27
	global_store_dwordx4 v[174:175], v[18:21], off
	global_load_dwordx4 v[18:21], v[178:179], off offset:528
	s_nop 0
	global_load_dwordx4 v[22:25], v[178:179], off offset:512
	global_load_dwordx4 v[26:29], v[180:181], off offset:512
	v_mad_i64_i32 v[178:179], s[34:35], v3, s56, v[14:15]
	global_load_dwordx4 v[30:33], v[30:31], off offset:16
	v_lshl_add_u64 v[178:179], v[178:179], 0, v[16:17]
	v_add_co_u32_e32 v180, vcc, s65, v178
	s_waitcnt vmcnt(1)
	v_pk_add_f32 v[24:25], v[24:25], v[28:29]
	v_pk_add_f32 v[22:23], v[22:23], v[26:27]
	v_pk_mul_f32 v[24:25], v[24:25], 0.5 op_sel_hi:[1,0]
	s_waitcnt vmcnt(0)
; __device__ __forceinline__ unsigned cvt_pk_bf16(float lo, float hi) { unsigned r; asm volatile("v_cvt_pk_bf16_f32 %0, %1, %2" : "=v"(r) : "v"(lo), "v"(hi)); return r; }
;     __device__ __forceinline__ void operator()(const f32x4 (&acc)[2][2][4][2], const Unit& u, int wr, int wc, int fr, int fq) const {
;     ...
; #pragma unroll
;             for (int ai = 0; ai < 2; ++ai)
; #pragma unroll
;                 for (int m = 0; m < 4; ++m) {
;                     const int row = row0 + ai * HALF + m * 16;
;                     const float* gp = gate + (size_t)modrow_of(row) * NMOD + col0;
;                     bf16_t* op = (bf16_t*)((char*)X + SLAB_MINUS_X) + ((size_t)u.kp * MS + (row - MP)) * DM + col0;
; #pragma unroll
;                     for (int bj = 0; bj < 2; ++bj) {
;                         const f32x4 g0 = (*(const f32x4*)(gp + bj * HALF) + *(const f32x4*)(gp + MODSB_DELTA + bj * HALF)) * coef, g1 = (*(const f32x4*)(gp + bj * HALF + 4) + *(const f32x4*)(gp + MODSB_DELTA + bj * HALF + 4)) * coef;
;                         const f32x4 o0 = g0 * acc[ai][bj][m][0], o1 = g1 * acc[ai][bj][m][1];
;                         u32x4 w; w.x = cvt_pk_bf16(o0[0], o0[1]); w.y = cvt_pk_bf16(o0[2], o0[3]); w.z = cvt_pk_bf16(o1[0], o1[1]); w.w = cvt_pk_bf16(o1[2], o1[3]);
;                         *(u32x4*)(op + bj * HALF) = w;
;                     }
;                     if (m & 1) asm volatile("" ::: "memory");
;                 }
	v_pk_add_f32 v[20:21], v[20:21], v[32:33]
	v_pk_add_f32 v[18:19], v[18:19], v[30:31]
	v_pk_mul_f32 v[20:21], v[20:21], 0.5 op_sel_hi:[1,0]
	v_pk_mul_f32 v[18:19], v[18:19], 0.5 op_sel_hi:[1,0]
	v_pk_mul_f32 v[22:23], v[22:23], 0.5 op_sel_hi:[1,0]
	v_pk_mul_f32 v[26:27], v[128:129], v[20:21]
	v_pk_mul_f32 v[20:21], v[126:127], v[18:19]
	v_pk_mul_f32 v[24:25], v[136:137], v[24:25]
	v_pk_mul_f32 v[22:23], v[134:135], v[22:23]
	v_lshl_add_u64 v[30:31], v[178:179], 0, s[16:17]
	v_cvt_pk_bf16_f32 v18, v22, v23
	v_cvt_pk_bf16_f32 v19, v24, v25
	v_cvt_pk_bf16_f32 v20, v20, v21
	v_cvt_pk_bf16_f32 v21, v26, v27
	global_store_dwordx4 v[174:175], v[18:21], off offset:256
	v_addc_co_u32_e32 v181, vcc, 0, v179, vcc
	global_load_dwordx4 v[18:21], v[178:179], off offset:16
	global_load_dwordx4 v[22:25], v[178:179], off
	global_load_dwordx4 v[26:29], v[180:181], off
	v_lshlrev_b64 v[174:175], 12, v[176:177]
	global_load_dwordx4 v[30:33], v[30:31], off offset:16
	v_lshl_add_u64 v[174:175], s[30:31], 0, v[174:175]
	v_lshl_add_u64 v[174:175], v[174:175], 0, v[12:13]
	v_add_u32_e32 v176, 0xffffe030, v10
	v_lshrrev_b32_e32 v3, 2, v176
	v_add_u32_e32 v3, 4, v3
	v_cmp_gt_i32_e32 vcc, s57, v2
	v_ashrrev_i32_e32 v177, 31, v176
	s_waitcnt vmcnt(1)
	v_pk_add_f32 v[24:25], v[24:25], v[28:29]
	v_pk_add_f32 v[22:23], v[22:23], v[26:27]
	s_waitcnt vmcnt(0)
	v_pk_add_f32 v[20:21], v[20:21], v[32:33]
	v_pk_add_f32 v[18:19], v[18:19], v[30:31]
	v_pk_mul_f32 v[20:21], v[20:21], 0.5 op_sel_hi:[1,0]
	v_pk_mul_f32 v[18:19], v[18:19], 0.5 op_sel_hi:[1,0]
	v_pk_mul_f32 v[24:25], v[24:25], 0.5 op_sel_hi:[1,0]
	v_pk_mul_f32 v[22:23], v[22:23], 0.5 op_sel_hi:[1,0]
	v_pk_mul_f32 v[26:27], v[124:125], v[20:21]
	v_pk_mul_f32 v[20:21], v[122:123], v[18:19]
	v_pk_mul_f32 v[24:25], v[132:133], v[24:25]
	v_pk_mul_f32 v[22:23], v[130:131], v[22:23]
	v_lshl_add_u64 v[30:31], v[178:179], 0, s[18:19]
	v_cvt_pk_bf16_f32 v18, v22, v23
	v_cvt_pk_bf16_f32 v19, v24, v25
	v_cvt_pk_bf16_f32 v20, v20, v21
	v_cvt_pk_bf16_f32 v21, v26, v27
	global_store_dwordx4 v[174:175], v[18:21], off
	global_load_dwordx4 v[18:21], v[178:179], off offset:528
	s_nop 0
	global_load_dwordx4 v[22:25], v[178:179], off offset:512
	global_load_dwordx4 v[26:29], v[180:181], off offset:512
	v_cndmask_b32_e32 v3, v3, v5, vcc
	global_load_dwordx4 v[30:33], v[30:31], off offset:16
	v_mad_i64_i32 v[178:179], s[34:35], v3, s56, v[14:15]
	v_lshl_add_u64 v[178:179], v[178:179], 0, v[16:17]
	v_add_co_u32_e32 v180, vcc, s65, v178
	s_ashr_i32 s34, s38, 11
	s_nop 0
	v_addc_co_u32_e32 v181, vcc, 0, v179, vcc
	v_mov_b32_e32 v5, s34
	v_cmp_gt_i32_e32 vcc, s66, v10
	s_waitcnt vmcnt(1)
	v_pk_add_f32 v[24:25], v[24:25], v[28:29]
	v_pk_add_f32 v[22:23], v[22:23], v[26:27]
	s_waitcnt vmcnt(0)
	v_pk_add_f32 v[20:21], v[20:21], v[32:33]
	v_pk_add_f32 v[18:19], v[18:19], v[30:31]
	v_pk_mul_f32 v[20:21], v[20:21], 0.5 op_sel_hi:[1,0]
	v_pk_mul_f32 v[18:19], v[18:19], 0.5 op_sel_hi:[1,0]
	v_pk_mul_f32 v[24:25], v[24:25], 0.5 op_sel_hi:[1,0]
	v_pk_mul_f32 v[22:23], v[22:23], 0.5 op_sel_hi:[1,0]
	v_pk_mul_f32 v[26:27], v[112:113], v[20:21]
	v_pk_mul_f32 v[20:21], v[110:111], v[18:19]
	v_pk_mul_f32 v[24:25], v[116:117], v[24:25]
	v_pk_mul_f32 v[22:23], v[114:115], v[22:23]
	v_lshl_add_u64 v[30:31], v[178:179], 0, s[16:17]
	v_cvt_pk_bf16_f32 v18, v22, v23
	v_cvt_pk_bf16_f32 v19, v24, v25
	v_cvt_pk_bf16_f32 v20, v20, v21
	v_cvt_pk_bf16_f32 v21, v26, v27
	global_store_dwordx4 v[174:175], v[18:21], off offset:256
	global_load_dwordx4 v[18:21], v[178:179], off offset:16
	s_nop 0
	global_load_dwordx4 v[22:25], v[178:179], off
	global_load_dwordx4 v[26:29], v[180:181], off
	v_lshlrev_b64 v[174:175], 12, v[176:177]
	global_load_dwordx4 v[30:33], v[30:31], off offset:16
	v_lshl_add_u64 v[174:175], s[30:31], 0, v[174:175]
	v_lshl_add_u64 v[174:175], v[174:175], 0, v[12:13]
	v_add_u32_e32 v176, 0xffffe080, v10
	v_lshrrev_b32_e32 v3, 2, v176
	v_or_b32_e32 v3, 4, v3
	v_cndmask_b32_e32 v3, v3, v5, vcc
	v_ashrrev_i32_e32 v177, 31, v176
	s_waitcnt vmcnt(1)
	v_pk_add_f32 v[24:25], v[24:25], v[28:29]
	v_pk_add_f32 v[22:23], v[22:23], v[26:27]
	s_waitcnt vmcnt(0)
	v_pk_add_f32 v[20:21], v[20:21], v[32:33]
	v_pk_add_f32 v[18:19], v[18:19], v[30:31]
	v_pk_mul_f32 v[20:21], v[20:21], 0.5 op_sel_hi:[1,0]
	v_pk_mul_f32 v[18:19], v[18:19], 0.5 op_sel_hi:[1,0]
	v_pk_mul_f32 v[24:25], v[24:25], 0.5 op_sel_hi:[1,0]
	v_pk_mul_f32 v[22:23], v[22:23], 0.5 op_sel_hi:[1,0]
	v_pk_mul_f32 v[26:27], v[108:109], v[20:21]
	v_pk_mul_f32 v[20:21], v[106:107], v[18:19]
	v_pk_mul_f32 v[24:25], v[120:121], v[24:25]
	v_pk_mul_f32 v[22:23], v[118:119], v[22:23]
	v_lshl_add_u64 v[30:31], v[178:179], 0, s[18:19]
	v_cvt_pk_bf16_f32 v18, v22, v23
	v_cvt_pk_bf16_f32 v19, v24, v25
	v_cvt_pk_bf16_f32 v20, v20, v21
	v_cvt_pk_bf16_f32 v21, v26, v27
	global_store_dwordx4 v[174:175], v[18:21], off
	global_load_dwordx4 v[18:21], v[178:179], off offset:528
	s_nop 0
	global_load_dwordx4 v[22:25], v[178:179], off offset:512
	global_load_dwordx4 v[26:29], v[180:181], off offset:512
	v_mad_i64_i32 v[178:179], s[34:35], v3, s56, v[14:15]
	global_load_dwordx4 v[30:33], v[30:31], off offset:16
	v_lshl_add_u64 v[178:179], v[178:179], 0, v[16:17]
	v_add_co_u32_e32 v180, vcc, s65, v178
	s_waitcnt vmcnt(1)
	v_pk_add_f32 v[24:25], v[24:25], v[28:29]
	v_pk_add_f32 v[22:23], v[22:23], v[26:27]
	v_pk_mul_f32 v[24:25], v[24:25], 0.5 op_sel_hi:[1,0]
	s_waitcnt vmcnt(0)
; __device__ __forceinline__ unsigned cvt_pk_bf16(float lo, float hi) { unsigned r; asm volatile("v_cvt_pk_bf16_f32 %0, %1, %2" : "=v"(r) : "v"(lo), "v"(hi)); return r; }
;     __device__ __forceinline__ void operator()(const f32x4 (&acc)[2][2][4][2], const Unit& u, int wr, int wc, int fr, int fq) const {
;     ...
; #pragma unroll
;             for (int ai = 0; ai < 2; ++ai)
; #pragma unroll
;                 for (int m = 0; m < 4; ++m) {
;                     const int row = row0 + ai * HALF + m * 16;
;                     const float* gp = gate + (size_t)modrow_of(row) * NMOD + col0;
;                     bf16_t* op = (bf16_t*)((char*)X + SLAB_MINUS_X) + ((size_t)u.kp * MS + (row - MP)) * DM + col0;
; #pragma unroll
;                     for (int bj = 0; bj < 2; ++bj) {
;                         const f32x4 g0 = (*(const f32x4*)(gp + bj * HALF) + *(const f32x4*)(gp + MODSB_DELTA + bj * HALF)) * coef, g1 = (*(const f32x4*)(gp + bj * HALF + 4) + *(const f32x4*)(gp + MODSB_DELTA + bj * HALF + 4)) * coef;
;                         const f32x4 o0 = g0 * acc[ai][bj][m][0], o1 = g1 * acc[ai][bj][m][1];
;                         u32x4 w; w.x = cvt_pk_bf16(o0[0], o0[1]); w.y = cvt_pk_bf16(o0[2], o0[3]); w.z = cvt_pk_bf16(o1[0], o1[1]); w.w = cvt_pk_bf16(o1[2], o1[3]);
;                         *(u32x4*)(op + bj * HALF) = w;
;                     }
;                     if (m & 1) asm volatile("" ::: "memory");
;                 }
	v_pk_add_f32 v[20:21], v[20:21], v[32:33]
	v_pk_add_f32 v[18:19], v[18:19], v[30:31]
	v_pk_mul_f32 v[20:21], v[20:21], 0.5 op_sel_hi:[1,0]
	v_pk_mul_f32 v[18:19], v[18:19], 0.5 op_sel_hi:[1,0]
	v_pk_mul_f32 v[22:23], v[22:23], 0.5 op_sel_hi:[1,0]
	v_pk_mul_f32 v[26:27], v[100:101], v[20:21]
	v_pk_mul_f32 v[20:21], v[98:99], v[18:19]
	v_pk_mul_f32 v[24:25], v[104:105], v[24:25]
	v_pk_mul_f32 v[22:23], v[102:103], v[22:23]
	v_lshl_add_u64 v[30:31], v[178:179], 0, s[16:17]
	v_cvt_pk_bf16_f32 v18, v22, v23
	v_cvt_pk_bf16_f32 v19, v24, v25
	v_cvt_pk_bf16_f32 v20, v20, v21
	v_cvt_pk_bf16_f32 v21, v26, v27
	global_store_dwordx4 v[174:175], v[18:21], off offset:256
	v_addc_co_u32_e32 v181, vcc, 0, v179, vcc
	global_load_dwordx4 v[18:21], v[178:179], off offset:16
	global_load_dwordx4 v[22:25], v[178:179], off
	global_load_dwordx4 v[26:29], v[180:181], off
	v_lshlrev_b64 v[174:175], 12, v[176:177]
	global_load_dwordx4 v[30:33], v[30:31], off offset:16
	v_lshl_add_u64 v[174:175], s[30:31], 0, v[174:175]
	v_lshl_add_u64 v[174:175], v[174:175], 0, v[12:13]
	v_add_u32_e32 v176, 0xffffe090, v10
	v_lshrrev_b32_e32 v3, 2, v176
	v_add_u32_e32 v3, 4, v3
	v_cmp_gt_i32_e32 vcc, s67, v10
	v_ashrrev_i32_e32 v177, 31, v176
	s_waitcnt vmcnt(1)
	v_pk_add_f32 v[24:25], v[24:25], v[28:29]
	v_pk_add_f32 v[22:23], v[22:23], v[26:27]
	s_waitcnt vmcnt(0)
	v_pk_add_f32 v[20:21], v[20:21], v[32:33]
	v_pk_add_f32 v[18:19], v[18:19], v[30:31]
	v_pk_mul_f32 v[20:21], v[20:21], 0.5 op_sel_hi:[1,0]
	v_pk_mul_f32 v[18:19], v[18:19], 0.5 op_sel_hi:[1,0]
	v_pk_mul_f32 v[24:25], v[24:25], 0.5 op_sel_hi:[1,0]
	v_pk_mul_f32 v[22:23], v[22:23], 0.5 op_sel_hi:[1,0]
	v_pk_mul_f32 v[26:27], v[92:93], v[20:21]
	v_pk_mul_f32 v[20:21], v[90:91], v[18:19]
	v_pk_mul_f32 v[24:25], v[96:97], v[24:25]
	v_pk_mul_f32 v[22:23], v[94:95], v[22:23]
	v_lshl_add_u64 v[30:31], v[178:179], 0, s[18:19]
	v_cvt_pk_bf16_f32 v18, v22, v23
	v_cvt_pk_bf16_f32 v19, v24, v25
	v_cvt_pk_bf16_f32 v20, v20, v21
	v_cvt_pk_bf16_f32 v21, v26, v27
	global_store_dwordx4 v[174:175], v[18:21], off
	global_load_dwordx4 v[18:21], v[178:179], off offset:528
	s_nop 0
	global_load_dwordx4 v[22:25], v[178:179], off offset:512
	global_load_dwordx4 v[26:29], v[180:181], off offset:512
	v_cndmask_b32_e32 v3, v3, v5, vcc
	global_load_dwordx4 v[30:33], v[30:31], off offset:16
	v_mad_i64_i32 v[178:179], s[34:35], v3, s56, v[14:15]
	v_lshl_add_u64 v[178:179], v[178:179], 0, v[16:17]
	v_add_co_u32_e32 v180, vcc, s65, v178
	s_waitcnt vmcnt(1)
	v_pk_add_f32 v[24:25], v[24:25], v[28:29]
	v_pk_add_f32 v[22:23], v[22:23], v[26:27]
	s_waitcnt vmcnt(0)
	v_pk_add_f32 v[20:21], v[20:21], v[32:33]
	v_pk_add_f32 v[18:19], v[18:19], v[30:31]
	v_pk_mul_f32 v[20:21], v[20:21], 0.5 op_sel_hi:[1,0]
	v_pk_mul_f32 v[18:19], v[18:19], 0.5 op_sel_hi:[1,0]
	v_pk_mul_f32 v[24:25], v[24:25], 0.5 op_sel_hi:[1,0]
	v_pk_mul_f32 v[22:23], v[22:23], 0.5 op_sel_hi:[1,0]
	v_pk_mul_f32 v[26:27], v[80:81], v[20:21]
	v_pk_mul_f32 v[20:21], v[78:79], v[18:19]
	v_pk_mul_f32 v[24:25], v[88:89], v[24:25]
	v_pk_mul_f32 v[22:23], v[86:87], v[22:23]
	v_lshl_add_u64 v[30:31], v[178:179], 0, s[16:17]
	v_cvt_pk_bf16_f32 v18, v22, v23
	v_cvt_pk_bf16_f32 v19, v24, v25
	v_cvt_pk_bf16_f32 v20, v20, v21
	v_cvt_pk_bf16_f32 v21, v26, v27
	global_store_dwordx4 v[174:175], v[18:21], off offset:256
	v_addc_co_u32_e32 v181, vcc, 0, v179, vcc
	global_load_dwordx4 v[18:21], v[178:179], off offset:16
	global_load_dwordx4 v[22:25], v[178:179], off
	global_load_dwordx4 v[26:29], v[180:181], off
	v_lshlrev_b64 v[174:175], 12, v[176:177]
	global_load_dwordx4 v[30:33], v[30:31], off offset:16
	v_lshl_add_u64 v[174:175], s[30:31], 0, v[174:175]
	v_lshl_add_u64 v[174:175], v[174:175], 0, v[12:13]
	v_add_u32_e32 v176, 0xffffe0a0, v10
	v_lshrrev_b32_e32 v3, 2, v176
	v_or_b32_e32 v3, 4, v3
	v_cmp_gt_i32_e32 vcc, s68, v10
	v_ashrrev_i32_e32 v177, 31, v176
	s_waitcnt vmcnt(1)
	v_pk_add_f32 v[24:25], v[24:25], v[28:29]
	v_pk_add_f32 v[22:23], v[22:23], v[26:27]
	s_waitcnt vmcnt(0)
	v_pk_add_f32 v[20:21], v[20:21], v[32:33]
	v_pk_add_f32 v[18:19], v[18:19], v[30:31]
	v_pk_mul_f32 v[20:21], v[20:21], 0.5 op_sel_hi:[1,0]
	v_pk_mul_f32 v[18:19], v[18:19], 0.5 op_sel_hi:[1,0]
	v_pk_mul_f32 v[24:25], v[24:25], 0.5 op_sel_hi:[1,0]
	v_pk_mul_f32 v[22:23], v[22:23], 0.5 op_sel_hi:[1,0]
	v_pk_mul_f32 v[26:27], v[76:77], v[20:21]
	v_pk_mul_f32 v[20:21], v[74:75], v[18:19]
	v_pk_mul_f32 v[24:25], v[84:85], v[24:25]
	v_pk_mul_f32 v[22:23], v[82:83], v[22:23]
	v_lshl_add_u64 v[30:31], v[178:179], 0, s[18:19]
	v_cvt_pk_bf16_f32 v18, v22, v23
	v_cvt_pk_bf16_f32 v19, v24, v25
	v_cvt_pk_bf16_f32 v20, v20, v21
	v_cvt_pk_bf16_f32 v21, v26, v27
	global_store_dwordx4 v[174:175], v[18:21], off
	global_load_dwordx4 v[18:21], v[178:179], off offset:528
	s_nop 0
	global_load_dwordx4 v[22:25], v[178:179], off offset:512
	global_load_dwordx4 v[26:29], v[180:181], off offset:512
	v_cndmask_b32_e32 v3, v3, v5, vcc
	global_load_dwordx4 v[30:33], v[30:31], off offset:16
	v_mad_i64_i32 v[178:179], s[34:35], v3, s56, v[14:15]
	v_lshl_add_u64 v[178:179], v[178:179], 0, v[16:17]
	v_add_co_u32_e32 v180, vcc, s65, v178
	s_waitcnt vmcnt(1)
	v_pk_add_f32 v[24:25], v[24:25], v[28:29]
	v_pk_add_f32 v[22:23], v[22:23], v[26:27]
	s_waitcnt vmcnt(0)
; __device__ __forceinline__ unsigned cvt_pk_bf16(float lo, float hi) { unsigned r; asm volatile("v_cvt_pk_bf16_f32 %0, %1, %2" : "=v"(r) : "v"(lo), "v"(hi)); return r; }
;     __device__ __forceinline__ void operator()(const f32x4 (&acc)[2][2][4][2], const Unit& u, int wr, int wc, int fr, int fq) const {
;     ...
; #pragma unroll
;             for (int ai = 0; ai < 2; ++ai)
; #pragma unroll
;                 for (int m = 0; m < 4; ++m) {
;                     const int row = row0 + ai * HALF + m * 16;
;                     const float* gp = gate + (size_t)modrow_of(row) * NMOD + col0;
;                     bf16_t* op = (bf16_t*)((char*)X + SLAB_MINUS_X) + ((size_t)u.kp * MS + (row - MP)) * DM + col0;
; #pragma unroll
;                     for (int bj = 0; bj < 2; ++bj) {
;                         const f32x4 g0 = (*(const f32x4*)(gp + bj * HALF) + *(const f32x4*)(gp + MODSB_DELTA + bj * HALF)) * coef, g1 = (*(const f32x4*)(gp + bj * HALF + 4) + *(const f32x4*)(gp + MODSB_DELTA + bj * HALF + 4)) * coef;
;                         const f32x4 o0 = g0 * acc[ai][bj][m][0], o1 = g1 * acc[ai][bj][m][1];
;                         u32x4 w; w.x = cvt_pk_bf16(o0[0], o0[1]); w.y = cvt_pk_bf16(o0[2], o0[3]); w.z = cvt_pk_bf16(o1[0], o1[1]); w.w = cvt_pk_bf16(o1[2], o1[3]);
;                         *(u32x4*)(op + bj * HALF) = w;
;                     }
;                     if (m & 1) asm volatile("" ::: "memory");
;                 }
	v_pk_add_f32 v[20:21], v[20:21], v[32:33]
	v_pk_add_f32 v[18:19], v[18:19], v[30:31]
	v_pk_mul_f32 v[20:21], v[20:21], 0.5 op_sel_hi:[1,0]
	v_pk_mul_f32 v[18:19], v[18:19], 0.5 op_sel_hi:[1,0]
	v_pk_mul_f32 v[24:25], v[24:25], 0.5 op_sel_hi:[1,0]
	v_pk_mul_f32 v[22:23], v[22:23], 0.5 op_sel_hi:[1,0]
	v_pk_mul_f32 v[26:27], v[64:65], v[20:21]
	v_pk_mul_f32 v[20:21], v[62:63], v[18:19]
	v_pk_mul_f32 v[24:25], v[72:73], v[24:25]
	v_pk_mul_f32 v[22:23], v[70:71], v[22:23]
	v_lshl_add_u64 v[30:31], v[178:179], 0, s[16:17]
	v_cvt_pk_bf16_f32 v18, v22, v23
	v_cvt_pk_bf16_f32 v19, v24, v25
	v_cvt_pk_bf16_f32 v20, v20, v21
	v_cvt_pk_bf16_f32 v21, v26, v27
	global_store_dwordx4 v[174:175], v[18:21], off offset:256
	v_addc_co_u32_e32 v181, vcc, 0, v179, vcc
	global_load_dwordx4 v[18:21], v[178:179], off offset:16
	global_load_dwordx4 v[22:25], v[178:179], off
	global_load_dwordx4 v[26:29], v[180:181], off
	v_lshlrev_b64 v[174:175], 12, v[176:177]
	global_load_dwordx4 v[30:33], v[30:31], off offset:16
	v_lshl_add_u64 v[174:175], s[30:31], 0, v[174:175]
	v_lshl_add_u64 v[174:175], v[174:175], 0, v[12:13]
	v_add_u32_e32 v176, 0xffffe0b0, v10
	v_lshrrev_b32_e32 v3, 2, v176
	v_add_u32_e32 v3, 4, v3
	v_cmp_gt_i32_e32 vcc, s69, v10
	v_ashrrev_i32_e32 v177, 31, v176
	s_waitcnt vmcnt(1)
	v_pk_add_f32 v[24:25], v[24:25], v[28:29]
	v_pk_add_f32 v[22:23], v[22:23], v[26:27]
	s_waitcnt vmcnt(0)
	v_pk_add_f32 v[20:21], v[20:21], v[32:33]
	v_pk_add_f32 v[18:19], v[18:19], v[30:31]
	v_pk_mul_f32 v[20:21], v[20:21], 0.5 op_sel_hi:[1,0]
	v_pk_mul_f32 v[18:19], v[18:19], 0.5 op_sel_hi:[1,0]
	v_pk_mul_f32 v[24:25], v[24:25], 0.5 op_sel_hi:[1,0]
	v_pk_mul_f32 v[22:23], v[22:23], 0.5 op_sel_hi:[1,0]
	v_pk_mul_f32 v[26:27], v[60:61], v[20:21]
	v_pk_mul_f32 v[20:21], v[58:59], v[18:19]
	v_pk_mul_f32 v[24:25], v[68:69], v[24:25]
	v_pk_mul_f32 v[22:23], v[66:67], v[22:23]
	v_lshl_add_u64 v[30:31], v[178:179], 0, s[18:19]
	v_cvt_pk_bf16_f32 v18, v22, v23
	v_cvt_pk_bf16_f32 v19, v24, v25
	v_cvt_pk_bf16_f32 v20, v20, v21
	v_cvt_pk_bf16_f32 v21, v26, v27
	global_store_dwordx4 v[174:175], v[18:21], off
	global_load_dwordx4 v[18:21], v[178:179], off offset:528
	s_nop 0
	global_load_dwordx4 v[22:25], v[178:179], off offset:512
	global_load_dwordx4 v[26:29], v[180:181], off offset:512
	v_cndmask_b32_e32 v3, v3, v5, vcc
	global_load_dwordx4 v[30:33], v[30:31], off offset:16
	v_mad_i64_i32 v[14:15], s[34:35], v3, s56, v[14:15]
	v_lshl_add_u64 v[178:179], v[14:15], 0, v[16:17]
	v_add_co_u32_e32 v180, vcc, s65, v178
	s_nop 1
	v_addc_co_u32_e32 v181, vcc, 0, v179, vcc
	s_waitcnt vmcnt(1)
	v_pk_add_f32 v[14:15], v[24:25], v[28:29]
	v_pk_add_f32 v[16:17], v[22:23], v[26:27]
	s_waitcnt vmcnt(0)
	v_pk_add_f32 v[18:19], v[18:19], v[30:31]
	v_pk_add_f32 v[20:21], v[20:21], v[32:33]
	v_pk_mul_f32 v[14:15], v[14:15], 0.5 op_sel_hi:[1,0]
	v_pk_mul_f32 v[16:17], v[16:17], 0.5 op_sel_hi:[1,0]
	v_pk_mul_f32 v[18:19], v[18:19], 0.5 op_sel_hi:[1,0]
	v_pk_mul_f32 v[20:21], v[20:21], 0.5 op_sel_hi:[1,0]
	v_pk_mul_f32 v[22:23], v[56:57], v[14:15]
	v_pk_mul_f32 v[14:15], v[54:55], v[16:17]
	v_pk_mul_f32 v[16:17], v[46:47], v[18:19]
	v_pk_mul_f32 v[20:21], v[48:49], v[20:21]
	v_cvt_pk_bf16_f32 v14, v14, v15
	v_cvt_pk_bf16_f32 v15, v22, v23
	v_cvt_pk_bf16_f32 v16, v16, v17
	v_lshl_add_u64 v[26:27], v[178:179], 0, s[16:17]
	v_cvt_pk_bf16_f32 v17, v20, v21
	global_store_dwordx4 v[174:175], v[14:17], off offset:256
	global_load_dwordx4 v[14:17], v[178:179], off offset:16
	s_nop 0
	global_load_dwordx4 v[18:21], v[178:179], off
	global_load_dwordx4 v[22:25], v[180:181], off
	v_lshlrev_b64 v[30:31], 12, v[176:177]
	global_load_dwordx4 v[26:29], v[26:27], off offset:16
	v_lshl_add_u64 v[30:31], s[30:31], 0, v[30:31]
	v_lshl_add_u64 v[30:31], v[30:31], 0, v[12:13]
	s_waitcnt vmcnt(1)
	v_pk_add_f32 v[12:13], v[20:21], v[24:25]
	v_pk_add_f32 v[18:19], v[18:19], v[22:23]
	s_waitcnt vmcnt(0)
	v_pk_add_f32 v[14:15], v[14:15], v[26:27]
	v_pk_add_f32 v[16:17], v[16:17], v[28:29]
	v_pk_mul_f32 v[12:13], v[12:13], 0.5 op_sel_hi:[1,0]
	v_pk_mul_f32 v[18:19], v[18:19], 0.5 op_sel_hi:[1,0]
	v_pk_mul_f32 v[14:15], v[14:15], 0.5 op_sel_hi:[1,0]
	v_pk_mul_f32 v[16:17], v[16:17], 0.5 op_sel_hi:[1,0]
	v_pk_mul_f32 v[20:21], v[52:53], v[12:13]
	v_pk_mul_f32 v[12:13], v[50:51], v[18:19]
	v_pk_mul_f32 v[14:15], v[42:43], v[14:15]
	v_pk_mul_f32 v[16:17], v[44:45], v[16:17]
	v_cvt_pk_bf16_f32 v12, v12, v13
	v_cvt_pk_bf16_f32 v13, v20, v21
	v_cvt_pk_bf16_f32 v14, v14, v15
	v_lshl_add_u64 v[24:25], v[178:179], 0, s[18:19]
	v_cvt_pk_bf16_f32 v15, v16, v17
	global_store_dwordx4 v[30:31], v[12:15], off
	global_load_dwordx4 v[12:15], v[178:179], off offset:528
	s_nop 0
	global_load_dwordx4 v[16:19], v[178:179], off offset:512
	global_load_dwordx4 v[20:23], v[180:181], off offset:512
	s_waitcnt vmcnt(0)
	v_pk_add_f32 v[18:19], v[18:19], v[22:23]
	global_load_dwordx4 v[24:27], v[24:25], off offset:16
	v_pk_add_f32 v[16:17], v[16:17], v[20:21]
	v_pk_mul_f32 v[18:19], v[18:19], 0.5 op_sel_hi:[1,0]
	v_pk_mul_f32 v[16:17], v[16:17], 0.5 op_sel_hi:[1,0]
	v_pk_mul_f32 v[18:19], v[40:41], v[18:19]
	v_pk_mul_f32 v[16:17], v[38:39], v[16:17]
	s_waitcnt vmcnt(0)
	v_pk_add_f32 v[14:15], v[14:15], v[26:27]
	v_pk_add_f32 v[12:13], v[12:13], v[24:25]
	v_pk_mul_f32 v[14:15], v[14:15], 0.5 op_sel_hi:[1,0]
	v_pk_mul_f32 v[12:13], v[12:13], 0.5 op_sel_hi:[1,0]
	v_pk_mul_f32 v[20:21], v[36:37], v[14:15]
	v_pk_mul_f32 v[14:15], v[34:35], v[12:13]
	v_cvt_pk_bf16_f32 v12, v16, v17
	v_cvt_pk_bf16_f32 v13, v18, v19
	s_nop 0
	v_cvt_pk_bf16_f32 v14, v14, v15
	v_cvt_pk_bf16_f32 v15, v20, v21
	global_store_dwordx4 v[30:31], v[12:15], off offset:256
	s_cbranch_execz .LBB0_1518

; __device__ __forceinline__ unsigned cvt_pk_bf16(float lo, float hi) { unsigned r; asm volatile("v_cvt_pk_bf16_f32 %0, %1, %2" : "=v"(r) : "v"(lo), "v"(hi)); return r; }
;     __device__ __forceinline__ void operator()(const f32x4 (&acc)[2][2][4][2], const Unit& u, int wr, int wc, int fr, int fq) const {
;     ...
;         if (u.kp < 0) {
;             const float* gp = gate + (size_t)(u.pm >> 3) * NMOD + col0;
;             f32x4 gg[2][2];
; #pragma unroll
;             for (int bj = 0; bj < 2; ++bj)
; #pragma unroll
;                 for (int n = 0; n < 2; ++n) gg[bj][n] = (*(const f32x4*)(gp + bj * HALF + 4 * n) + *(const f32x4*)(gp + MODSB_DELTA + bj * HALF + 4 * n)) * coef;
; #pragma unroll
;             for (int ai = 0; ai < 2; ++ai)
; #pragma unroll
;                 for (int m = 0; m < 4; ++m) {
;                     const int row = row0 + ai * HALF + m * 16;
;                     bf16_t* xp = X + (size_t)row * DM + col0;
; #pragma unroll
;                     for (int bj = 0; bj < 2; ++bj) {
;                         f32x4 b0, b1;
;                         if (BASE16) { const u32x4 bv = *(const u32x4*)(xp + bj * HALF);
;                             b0 = (f32x4){__builtin_bit_cast(float, bv.x << 16), __builtin_bit_cast(float, bv.x & 0xffff0000u), __builtin_bit_cast(float, bv.y << 16), __builtin_bit_cast(float, bv.y & 0xffff0000u)};
;                             b1 = (f32x4){__builtin_bit_cast(float, bv.z << 16), __builtin_bit_cast(float, bv.z & 0xffff0000u), __builtin_bit_cast(float, bv.w << 16), __builtin_bit_cast(float, bv.w & 0xffff0000u)}; }
;                         else { const float* bp = base32 + (size_t)row * DM + col0 + bj * HALF; b0 = __builtin_nontemporal_load((const f32x4*)bp); b1 = __builtin_nontemporal_load((const f32x4*)(bp + 4)); }
;                         const f32x4 o0 = b0 + gg[bj][0] * acc[ai][bj][m][0], o1 = b1 + gg[bj][1] * acc[ai][bj][m][1];
;                         u32x4 w; w.x = cvt_pk_bf16(o0[0], o0[1]); w.y = cvt_pk_bf16(o0[2], o0[3]); w.z = cvt_pk_bf16(o1[0], o1[1]); w.w = cvt_pk_bf16(o1[2], o1[3]);
;                         *(u32x4*)(xp + bj * HALF) = w;
;                     }
;                     if (m & 1) asm volatile("" ::: "memory");
;                 }
.LBB0_1518:
	s_ashr_i32 s30, s77, 3
	s_mul_hi_i32 s31, s30, 0x12000
	s_mul_i32 s30, s30, 0x12000
	s_add_u32 s30, s10, s30
	s_addc_u32 s31, s11, s31
	v_ashrrev_i32_e32 v11, 31, v10
	v_lshl_add_u64 v[22:23], v[8:9], 2, s[30:31]
	v_lshlrev_b64 v[10:11], 12, v[10:11]
	v_lshl_add_u64 v[10:11], s[8:9], 0, v[10:11]
	v_lshlrev_b64 v[24:25], 1, v[8:9]
	v_add_co_u32_e32 v194, vcc, s65, v22
	v_lshl_add_u64 v[8:9], v[10:11], 0, v[24:25]
	s_nop 0
	v_addc_co_u32_e32 v195, vcc, 0, v23, vcc
	v_lshl_add_u64 v[30:31], v[22:23], 0, s[16:17]
	global_load_dwordx4 v[10:13], v[8:9], off
	global_load_dwordx4 v[14:17], v[22:23], off offset:16
	global_load_dwordx4 v[18:21], v[22:23], off
	global_load_dwordx4 v[26:29], v[194:195], off
	v_lshl_add_u64 v[198:199], v[22:23], 0, s[18:19]
	global_load_dwordx4 v[30:33], v[30:31], off offset:16
	s_nop 0
	global_load_dwordx4 v[174:177], v[22:23], off offset:528
	global_load_dwordx4 v[178:181], v[22:23], off offset:512
	s_nop 0
	global_load_dwordx4 v[194:197], v[194:195], off offset:512
	s_nop 0
	global_load_dwordx4 v[198:201], v[198:199], off offset:16
	v_ashrrev_i32_e32 v7, 31, v6
	v_lshlrev_b64 v[6:7], 12, v[6:7]
	v_lshl_add_u64 v[6:7], s[8:9], 0, v[6:7]
	v_ashrrev_i32_e32 v5, 31, v4
	v_lshlrev_b64 v[4:5], 12, v[4:5]
	v_lshl_add_u64 v[4:5], s[8:9], 0, v[4:5]
	v_ashrrev_i32_e32 v3, 31, v2
	v_lshlrev_b64 v[2:3], 12, v[2:3]
	v_lshl_add_u64 v[2:3], s[8:9], 0, v[2:3]
	s_waitcnt vmcnt(0)
	v_lshlrev_b32_e32 v22, 16, v10
	v_and_b32_e32 v23, 0xffff0000, v10
	v_lshlrev_b32_e32 v202, 16, v11
	v_and_b32_e32 v203, 0xffff0000, v11
	v_pk_add_f32 v[10:11], v[20:21], v[28:29]
	v_pk_add_f32 v[20:21], v[14:15], v[30:31]
	v_lshlrev_b32_e32 v204, 16, v12
	v_and_b32_e32 v205, 0xffff0000, v12
	v_lshlrev_b32_e32 v206, 16, v13
	v_and_b32_e32 v207, 0xffff0000, v13
	v_pk_add_f32 v[12:13], v[18:19], v[26:27]
	v_pk_add_f32 v[18:19], v[16:17], v[32:33]
	v_pk_mul_f32 v[16:17], v[10:11], 0.5 op_sel_hi:[1,0]
	v_pk_mul_f32 v[10:11], v[20:21], 0.5 op_sel_hi:[1,0]
	v_pk_mul_f32 v[14:15], v[12:13], 0.5 op_sel_hi:[1,0]
	v_pk_mul_f32 v[12:13], v[18:19], 0.5 op_sel_hi:[1,0]
	v_pk_fma_f32 v[28:29], v[154:155], v[10:11], v[204:205]
	v_pk_fma_f32 v[18:19], v[160:161], v[16:17], v[202:203]
	v_pk_fma_f32 v[20:21], v[158:159], v[14:15], v[22:23]
	v_pk_fma_f32 v[22:23], v[156:157], v[12:13], v[206:207]
	v_cvt_pk_bf16_f32 v26, v20, v21
	v_cvt_pk_bf16_f32 v27, v18, v19
	v_cvt_pk_bf16_f32 v28, v28, v29
	v_lshl_add_u64 v[154:155], v[6:7], 0, v[24:25]
	v_cvt_pk_bf16_f32 v29, v22, v23
	global_load_dwordx4 v[30:33], v[8:9], off offset:256
	v_pk_add_f32 v[6:7], v[180:181], v[196:197]
	v_pk_add_f32 v[18:19], v[178:179], v[194:195]
	v_pk_add_f32 v[156:157], v[176:177], v[200:201]
	v_pk_add_f32 v[158:159], v[174:175], v[198:199]
	v_pk_mul_f32 v[22:23], v[6:7], 0.5 op_sel_hi:[1,0]
	v_pk_mul_f32 v[20:21], v[18:19], 0.5 op_sel_hi:[1,0]
	v_pk_mul_f32 v[18:19], v[156:157], 0.5 op_sel_hi:[1,0]
	v_pk_mul_f32 v[6:7], v[158:159], 0.5 op_sel_hi:[1,0]
	global_store_dwordx4 v[8:9], v[26:29], off
	s_waitcnt vmcnt(1)
	s_nop 0
	v_lshlrev_b32_e32 v26, 16, v30
	v_and_b32_e32 v27, 0xffff0000, v30
	v_lshlrev_b32_e32 v28, 16, v31
	v_and_b32_e32 v29, 0xffff0000, v31
	v_lshlrev_b32_e32 v30, 16, v32
	v_and_b32_e32 v31, 0xffff0000, v32
	v_lshlrev_b32_e32 v32, 16, v33
	v_and_b32_e32 v33, 0xffff0000, v33
	v_pk_fma_f32 v[28:29], v[148:149], v[22:23], v[28:29]
	v_pk_fma_f32 v[26:27], v[146:147], v[20:21], v[26:27]
	v_pk_fma_f32 v[32:33], v[144:145], v[18:19], v[32:33]
	v_pk_fma_f32 v[30:31], v[142:143], v[6:7], v[30:31]
	v_cvt_pk_bf16_f32 v26, v26, v27
	v_cvt_pk_bf16_f32 v27, v28, v29
	s_nop 0
	v_cvt_pk_bf16_f32 v28, v30, v31
	v_cvt_pk_bf16_f32 v29, v32, v33
	global_load_dwordx4 v[30:33], v[154:155], off
	s_nop 0
	global_store_dwordx4 v[8:9], v[26:29], off offset:256
	s_waitcnt vmcnt(1)
	s_nop 0
	v_lshlrev_b32_e32 v26, 16, v30
	v_and_b32_e32 v27, 0xffff0000, v30
	v_lshlrev_b32_e32 v28, 16, v31
	v_and_b32_e32 v29, 0xffff0000, v31
	v_lshlrev_b32_e32 v30, 16, v32
	v_and_b32_e32 v31, 0xffff0000, v32
	v_lshlrev_b32_e32 v32, 16, v33
	v_and_b32_e32 v33, 0xffff0000, v33
	v_pk_fma_f32 v[28:29], v[152:153], v[16:17], v[28:29]
	v_pk_fma_f32 v[26:27], v[150:151], v[14:15], v[26:27]
	v_pk_fma_f32 v[32:33], v[140:141], v[12:13], v[32:33]
	v_pk_fma_f32 v[30:31], v[138:139], v[10:11], v[30:31]
	v_cvt_pk_bf16_f32 v26, v26, v27
	v_cvt_pk_bf16_f32 v27, v28, v29
	v_lshl_add_u64 v[138:139], v[4:5], 0, v[24:25]
	v_cvt_pk_bf16_f32 v28, v30, v31
	v_cvt_pk_bf16_f32 v29, v32, v33
	global_load_dwordx4 v[30:33], v[154:155], off offset:256
	s_waitcnt vmcnt(0)
	v_lshlrev_b32_e32 v4, 16, v30
	global_store_dwordx4 v[154:155], v[26:29], off
	v_and_b32_e32 v5, 0xffff0000, v30
	v_lshlrev_b32_e32 v30, 16, v33
	v_lshlrev_b32_e32 v28, 16, v32
	v_and_b32_e32 v29, 0xffff0000, v32
	v_lshlrev_b32_e32 v26, 16, v31
	v_and_b32_e32 v27, 0xffff0000, v31
	v_and_b32_e32 v31, 0xffff0000, v33
	v_pk_fma_f32 v[28:29], v[126:127], v[6:7], v[28:29]
	v_pk_fma_f32 v[32:33], v[136:137], v[22:23], v[26:27]
	v_pk_fma_f32 v[4:5], v[134:135], v[20:21], v[4:5]
	v_pk_fma_f32 v[30:31], v[128:129], v[18:19], v[30:31]
	v_cvt_pk_bf16_f32 v26, v4, v5
	v_cvt_pk_bf16_f32 v27, v32, v33
	v_cvt_pk_bf16_f32 v28, v28, v29
	s_nop 0
	v_cvt_pk_bf16_f32 v29, v30, v31
	global_store_dwordx4 v[154:155], v[26:29], off offset:256
	global_load_dwordx4 v[26:29], v[138:139], off
	s_waitcnt vmcnt(0)
; __device__ __forceinline__ unsigned cvt_pk_bf16(float lo, float hi) { unsigned r; asm volatile("v_cvt_pk_bf16_f32 %0, %1, %2" : "=v"(r) : "v"(lo), "v"(hi)); return r; }
;     __device__ __forceinline__ void operator()(const f32x4 (&acc)[2][2][4][2], const Unit& u, int wr, int wc, int fr, int fq) const {
;     ...
;         if (u.kp < 0) {
;             const float* gp = gate + (size_t)(u.pm >> 3) * NMOD + col0;
;             f32x4 gg[2][2];
; #pragma unroll
;             for (int bj = 0; bj < 2; ++bj)
; #pragma unroll
;                 for (int n = 0; n < 2; ++n) gg[bj][n] = (*(const f32x4*)(gp + bj * HALF + 4 * n) + *(const f32x4*)(gp + MODSB_DELTA + bj * HALF + 4 * n)) * coef;
; #pragma unroll
;             for (int ai = 0; ai < 2; ++ai)
; #pragma unroll
;                 for (int m = 0; m < 4; ++m) {
;                     const int row = row0 + ai * HALF + m * 16;
;                     bf16_t* xp = X + (size_t)row * DM + col0;
; #pragma unroll
;                     for (int bj = 0; bj < 2; ++bj) {
;                         f32x4 b0, b1;
;                         if (BASE16) { const u32x4 bv = *(const u32x4*)(xp + bj * HALF);
;                             b0 = (f32x4){__builtin_bit_cast(float, bv.x << 16), __builtin_bit_cast(float, bv.x & 0xffff0000u), __builtin_bit_cast(float, bv.y << 16), __builtin_bit_cast(float, bv.y & 0xffff0000u)};
;                             b1 = (f32x4){__builtin_bit_cast(float, bv.z << 16), __builtin_bit_cast(float, bv.z & 0xffff0000u), __builtin_bit_cast(float, bv.w << 16), __builtin_bit_cast(float, bv.w & 0xffff0000u)}; }
;                         else { const float* bp = base32 + (size_t)row * DM + col0 + bj * HALF; b0 = __builtin_nontemporal_load((const f32x4*)bp); b1 = __builtin_nontemporal_load((const f32x4*)(bp + 4)); }
;                         const f32x4 o0 = b0 + gg[bj][0] * acc[ai][bj][m][0], o1 = b1 + gg[bj][1] * acc[ai][bj][m][1];
;                         u32x4 w; w.x = cvt_pk_bf16(o0[0], o0[1]); w.y = cvt_pk_bf16(o0[2], o0[3]); w.z = cvt_pk_bf16(o1[0], o1[1]); w.w = cvt_pk_bf16(o1[2], o1[3]);
;                         *(u32x4*)(xp + bj * HALF) = w;
;                     }
;                     if (m & 1) asm volatile("" ::: "memory");
;                 }
	v_lshlrev_b32_e32 v4, 16, v26
	v_and_b32_e32 v5, 0xffff0000, v26
	v_lshlrev_b32_e32 v26, 16, v27
	v_and_b32_e32 v27, 0xffff0000, v27
	v_lshlrev_b32_e32 v30, 16, v28
	v_and_b32_e32 v31, 0xffff0000, v28
	v_lshlrev_b32_e32 v28, 16, v29
	v_and_b32_e32 v29, 0xffff0000, v29
	v_pk_fma_f32 v[32:33], v[132:133], v[16:17], v[26:27]
	v_pk_fma_f32 v[124:125], v[124:125], v[12:13], v[28:29]
	v_pk_fma_f32 v[28:29], v[122:123], v[10:11], v[30:31]
	v_pk_fma_f32 v[4:5], v[130:131], v[14:15], v[4:5]
	v_lshl_add_u64 v[122:123], v[2:3], 0, v[24:25]
	v_cvt_pk_bf16_f32 v26, v4, v5
	v_cvt_pk_bf16_f32 v27, v32, v33
	v_cvt_pk_bf16_f32 v28, v28, v29
	v_cvt_pk_bf16_f32 v29, v124, v125
	global_load_dwordx4 v[30:33], v[138:139], off offset:256
	s_waitcnt vmcnt(0)
	v_lshlrev_b32_e32 v2, 16, v30
	global_store_dwordx4 v[138:139], v[26:29], off
	v_and_b32_e32 v3, 0xffff0000, v30
	v_lshlrev_b32_e32 v4, 16, v31
	v_and_b32_e32 v5, 0xffff0000, v31
	v_lshlrev_b32_e32 v24, 16, v32
	v_and_b32_e32 v25, 0xffff0000, v32
	v_lshlrev_b32_e32 v26, 16, v33
	v_and_b32_e32 v27, 0xffff0000, v33
	v_pk_fma_f32 v[4:5], v[116:117], v[22:23], v[4:5]
	v_pk_fma_f32 v[2:3], v[114:115], v[20:21], v[2:3]
	v_pk_fma_f32 v[26:27], v[112:113], v[18:19], v[26:27]
	v_pk_fma_f32 v[24:25], v[110:111], v[6:7], v[24:25]
	v_cvt_pk_bf16_f32 v2, v2, v3
	v_cvt_pk_bf16_f32 v3, v4, v5
	v_add_co_u32_e32 v28, vcc, s70, v8
	v_cvt_pk_bf16_f32 v4, v24, v25
	v_cvt_pk_bf16_f32 v5, v26, v27
	global_load_dwordx4 v[24:27], v[122:123], off
	s_nop 0
	v_addc_co_u32_e32 v29, vcc, 0, v9, vcc
	global_store_dwordx4 v[138:139], v[2:5], off offset:256
	v_lshl_add_u64 v[30:31], v[8:9], 0, s[20:21]
	s_waitcnt vmcnt(1)
	v_lshlrev_b32_e32 v2, 16, v24
	v_and_b32_e32 v3, 0xffff0000, v24
	v_lshlrev_b32_e32 v4, 16, v25
	v_and_b32_e32 v5, 0xffff0000, v25
	v_lshlrev_b32_e32 v24, 16, v26
	v_and_b32_e32 v25, 0xffff0000, v26
	v_lshlrev_b32_e32 v26, 16, v27
	v_and_b32_e32 v27, 0xffff0000, v27
	v_pk_fma_f32 v[4:5], v[120:121], v[16:17], v[4:5]
	v_pk_fma_f32 v[2:3], v[118:119], v[14:15], v[2:3]
	v_pk_fma_f32 v[26:27], v[108:109], v[12:13], v[26:27]
	v_pk_fma_f32 v[24:25], v[106:107], v[10:11], v[24:25]
	v_cvt_pk_bf16_f32 v2, v2, v3
	v_cvt_pk_bf16_f32 v3, v4, v5
	s_nop 0
	v_cvt_pk_bf16_f32 v4, v24, v25
	v_cvt_pk_bf16_f32 v5, v26, v27
	global_load_dwordx4 v[24:27], v[122:123], off offset:256
	s_nop 0
	global_store_dwordx4 v[122:123], v[2:5], off
	s_waitcnt vmcnt(1)
	s_nop 0
	v_lshlrev_b32_e32 v2, 16, v24
	v_and_b32_e32 v3, 0xffff0000, v24
	v_lshlrev_b32_e32 v4, 16, v25
	v_and_b32_e32 v5, 0xffff0000, v25
	v_lshlrev_b32_e32 v24, 16, v26
	v_and_b32_e32 v25, 0xffff0000, v26
	v_lshlrev_b32_e32 v26, 16, v27
	v_and_b32_e32 v27, 0xffff0000, v27
	v_pk_fma_f32 v[4:5], v[104:105], v[22:23], v[4:5]
	v_pk_fma_f32 v[2:3], v[102:103], v[20:21], v[2:3]
	v_pk_fma_f32 v[26:27], v[100:101], v[18:19], v[26:27]
	v_pk_fma_f32 v[24:25], v[98:99], v[6:7], v[24:25]
	v_cvt_pk_bf16_f32 v2, v2, v3
	v_cvt_pk_bf16_f32 v3, v4, v5
	s_nop 0
	v_cvt_pk_bf16_f32 v4, v24, v25
	v_cvt_pk_bf16_f32 v5, v26, v27
	global_store_dwordx4 v[122:123], v[2:5], off offset:256
	global_load_dwordx4 v[2:5], v[28:29], off
	s_waitcnt vmcnt(0)
	v_lshlrev_b32_e32 v24, 16, v2
	v_and_b32_e32 v25, 0xffff0000, v2
	v_lshlrev_b32_e32 v2, 16, v3
	v_and_b32_e32 v3, 0xffff0000, v3
	v_lshlrev_b32_e32 v26, 16, v4
	v_and_b32_e32 v27, 0xffff0000, v4
	v_lshlrev_b32_e32 v4, 16, v5
	v_and_b32_e32 v5, 0xffff0000, v5
	v_pk_fma_f32 v[32:33], v[96:97], v[16:17], v[2:3]
	v_pk_fma_f32 v[2:3], v[94:95], v[14:15], v[24:25]
	v_pk_fma_f32 v[24:25], v[92:93], v[12:13], v[4:5]
	v_pk_fma_f32 v[4:5], v[90:91], v[10:11], v[26:27]
	v_cvt_pk_bf16_f32 v2, v2, v3
	v_cvt_pk_bf16_f32 v3, v32, v33
	v_add_co_u32_e32 v32, vcc, s71, v8
	v_cvt_pk_bf16_f32 v4, v4, v5
	v_cvt_pk_bf16_f32 v5, v24, v25
	global_load_dwordx4 v[24:27], v[30:31], off offset:256
	s_nop 0
	v_addc_co_u32_e32 v33, vcc, 0, v9, vcc
	global_store_dwordx4 v[28:29], v[2:5], off
	v_lshl_add_u64 v[28:29], v[8:9], 0, s[22:23]
	s_waitcnt vmcnt(1)
	v_lshlrev_b32_e32 v2, 16, v24
	v_and_b32_e32 v3, 0xffff0000, v24
	v_lshlrev_b32_e32 v4, 16, v25
	v_and_b32_e32 v5, 0xffff0000, v25
	v_lshlrev_b32_e32 v24, 16, v26
	v_and_b32_e32 v25, 0xffff0000, v26
	v_lshlrev_b32_e32 v26, 16, v27
	v_and_b32_e32 v27, 0xffff0000, v27
	v_pk_fma_f32 v[4:5], v[88:89], v[22:23], v[4:5]
	v_pk_fma_f32 v[2:3], v[86:87], v[20:21], v[2:3]
	v_pk_fma_f32 v[26:27], v[80:81], v[18:19], v[26:27]
	v_pk_fma_f32 v[24:25], v[78:79], v[6:7], v[24:25]
	v_cvt_pk_bf16_f32 v2, v2, v3
	v_cvt_pk_bf16_f32 v3, v4, v5
	s_nop 0
	v_cvt_pk_bf16_f32 v4, v24, v25
	v_cvt_pk_bf16_f32 v5, v26, v27
	global_load_dwordx4 v[24:27], v[32:33], off
	s_nop 0
	global_store_dwordx4 v[30:31], v[2:5], off offset:256
	v_add_co_u32_e32 v30, vcc, s72, v8
	s_waitcnt vmcnt(1)
; __device__ __forceinline__ unsigned cvt_pk_bf16(float lo, float hi) { unsigned r; asm volatile("v_cvt_pk_bf16_f32 %0, %1, %2" : "=v"(r) : "v"(lo), "v"(hi)); return r; }
;     __device__ __forceinline__ void operator()(const f32x4 (&acc)[2][2][4][2], const Unit& u, int wr, int wc, int fr, int fq) const {
;     ...
;         if (u.kp < 0) {
;             const float* gp = gate + (size_t)(u.pm >> 3) * NMOD + col0;
;             f32x4 gg[2][2];
; #pragma unroll
;             for (int bj = 0; bj < 2; ++bj)
; #pragma unroll
;                 for (int n = 0; n < 2; ++n) gg[bj][n] = (*(const f32x4*)(gp + bj * HALF + 4 * n) + *(const f32x4*)(gp + MODSB_DELTA + bj * HALF + 4 * n)) * coef;
; #pragma unroll
;             for (int ai = 0; ai < 2; ++ai)
; #pragma unroll
;                 for (int m = 0; m < 4; ++m) {
;                     const int row = row0 + ai * HALF + m * 16;
;                     bf16_t* xp = X + (size_t)row * DM + col0;
; #pragma unroll
;                     for (int bj = 0; bj < 2; ++bj) {
;                         f32x4 b0, b1;
;                         if (BASE16) { const u32x4 bv = *(const u32x4*)(xp + bj * HALF);
;                             b0 = (f32x4){__builtin_bit_cast(float, bv.x << 16), __builtin_bit_cast(float, bv.x & 0xffff0000u), __builtin_bit_cast(float, bv.y << 16), __builtin_bit_cast(float, bv.y & 0xffff0000u)};
;                             b1 = (f32x4){__builtin_bit_cast(float, bv.z << 16), __builtin_bit_cast(float, bv.z & 0xffff0000u), __builtin_bit_cast(float, bv.w << 16), __builtin_bit_cast(float, bv.w & 0xffff0000u)}; }
;                         else { const float* bp = base32 + (size_t)row * DM + col0 + bj * HALF; b0 = __builtin_nontemporal_load((const f32x4*)bp); b1 = __builtin_nontemporal_load((const f32x4*)(bp + 4)); }
;                         const f32x4 o0 = b0 + gg[bj][0] * acc[ai][bj][m][0], o1 = b1 + gg[bj][1] * acc[ai][bj][m][1];
;                         u32x4 w; w.x = cvt_pk_bf16(o0[0], o0[1]); w.y = cvt_pk_bf16(o0[2], o0[3]); w.z = cvt_pk_bf16(o1[0], o1[1]); w.w = cvt_pk_bf16(o1[2], o1[3]);
;                         *(u32x4*)(xp + bj * HALF) = w;
;                     }
;                     if (m & 1) asm volatile("" ::: "memory");
;                 }
	v_lshlrev_b32_e32 v2, 16, v24
	v_and_b32_e32 v3, 0xffff0000, v24
	v_lshlrev_b32_e32 v4, 16, v25
	v_and_b32_e32 v5, 0xffff0000, v25
	v_lshlrev_b32_e32 v24, 16, v26
	v_and_b32_e32 v25, 0xffff0000, v26
	v_lshlrev_b32_e32 v26, 16, v27
	v_and_b32_e32 v27, 0xffff0000, v27
	v_pk_fma_f32 v[4:5], v[84:85], v[16:17], v[4:5]
	v_pk_fma_f32 v[2:3], v[82:83], v[14:15], v[2:3]
	v_pk_fma_f32 v[26:27], v[76:77], v[12:13], v[26:27]
	v_pk_fma_f32 v[24:25], v[74:75], v[10:11], v[24:25]
	v_cvt_pk_bf16_f32 v2, v2, v3
	v_cvt_pk_bf16_f32 v3, v4, v5
	v_addc_co_u32_e32 v31, vcc, 0, v9, vcc
	v_cvt_pk_bf16_f32 v4, v24, v25
	v_cvt_pk_bf16_f32 v5, v26, v27
	global_load_dwordx4 v[24:27], v[28:29], off offset:256
	s_nop 0
	global_store_dwordx4 v[32:33], v[2:5], off
	s_waitcnt vmcnt(1)
	s_nop 0
	v_lshlrev_b32_e32 v2, 16, v24
	v_and_b32_e32 v3, 0xffff0000, v24
	v_lshlrev_b32_e32 v4, 16, v25
	v_and_b32_e32 v5, 0xffff0000, v25
	v_lshlrev_b32_e32 v24, 16, v26
	v_and_b32_e32 v25, 0xffff0000, v26
	v_lshlrev_b32_e32 v26, 16, v27
	v_and_b32_e32 v27, 0xffff0000, v27
	v_pk_fma_f32 v[4:5], v[72:73], v[22:23], v[4:5]
	v_pk_fma_f32 v[2:3], v[70:71], v[20:21], v[2:3]
	v_pk_fma_f32 v[26:27], v[64:65], v[18:19], v[26:27]
	v_pk_fma_f32 v[24:25], v[62:63], v[6:7], v[24:25]
	v_cvt_pk_bf16_f32 v2, v2, v3
	v_cvt_pk_bf16_f32 v3, v4, v5
	s_nop 0
	v_cvt_pk_bf16_f32 v4, v24, v25
	v_cvt_pk_bf16_f32 v5, v26, v27
	global_store_dwordx4 v[28:29], v[2:5], off offset:256
	global_load_dwordx4 v[2:5], v[30:31], off
	v_lshl_add_u64 v[28:29], v[8:9], 0, s[24:25]
	s_waitcnt vmcnt(0)
	v_lshlrev_b32_e32 v24, 16, v2
	v_and_b32_e32 v25, 0xffff0000, v2
	v_lshlrev_b32_e32 v2, 16, v3
	v_and_b32_e32 v3, 0xffff0000, v3
	v_lshlrev_b32_e32 v26, 16, v4
	v_and_b32_e32 v27, 0xffff0000, v4
	v_lshlrev_b32_e32 v4, 16, v5
	v_and_b32_e32 v5, 0xffff0000, v5
	v_pk_fma_f32 v[32:33], v[68:69], v[16:17], v[2:3]
	v_pk_fma_f32 v[2:3], v[66:67], v[14:15], v[24:25]
	v_pk_fma_f32 v[24:25], v[60:61], v[12:13], v[4:5]
	v_pk_fma_f32 v[4:5], v[58:59], v[10:11], v[26:27]
	v_cvt_pk_bf16_f32 v2, v2, v3
	v_cvt_pk_bf16_f32 v3, v32, v33
	v_add_co_u32_e32 v32, vcc, s73, v8
	v_cvt_pk_bf16_f32 v4, v4, v5
	v_cvt_pk_bf16_f32 v5, v24, v25
	global_load_dwordx4 v[24:27], v[28:29], off offset:256
	s_nop 0
	v_addc_co_u32_e32 v33, vcc, 0, v9, vcc
	global_store_dwordx4 v[30:31], v[2:5], off
	v_lshl_add_u64 v[30:31], v[8:9], 0, s[4:5]
	s_waitcnt vmcnt(1)
	v_lshlrev_b32_e32 v2, 16, v24
	v_and_b32_e32 v3, 0xffff0000, v24
	v_lshlrev_b32_e32 v4, 16, v25
	v_and_b32_e32 v5, 0xffff0000, v25
	v_lshlrev_b32_e32 v24, 16, v26
	v_and_b32_e32 v25, 0xffff0000, v26
	v_lshlrev_b32_e32 v26, 16, v27
	v_and_b32_e32 v27, 0xffff0000, v27
	v_pk_fma_f32 v[4:5], v[56:57], v[22:23], v[4:5]
	v_pk_fma_f32 v[2:3], v[54:55], v[20:21], v[2:3]
	v_pk_fma_f32 v[26:27], v[48:49], v[18:19], v[26:27]
	v_pk_fma_f32 v[24:25], v[46:47], v[6:7], v[24:25]
	v_cvt_pk_bf16_f32 v2, v2, v3
	v_cvt_pk_bf16_f32 v3, v4, v5
	s_nop 0
	v_cvt_pk_bf16_f32 v4, v24, v25
	v_cvt_pk_bf16_f32 v5, v26, v27
	global_load_dwordx4 v[24:27], v[32:33], off
	s_waitcnt vmcnt(0)
	v_lshlrev_b32_e32 v8, 16, v26
	global_store_dwordx4 v[28:29], v[2:5], off offset:256
	v_and_b32_e32 v9, 0xffff0000, v26
	v_pk_fma_f32 v[8:9], v[42:43], v[10:11], v[8:9]
	v_lshlrev_b32_e32 v2, 16, v24
	v_and_b32_e32 v3, 0xffff0000, v24
	v_lshlrev_b32_e32 v4, 16, v25
	v_and_b32_e32 v5, 0xffff0000, v25
	v_lshlrev_b32_e32 v24, 16, v27
	v_and_b32_e32 v25, 0xffff0000, v27
	v_pk_fma_f32 v[4:5], v[52:53], v[16:17], v[4:5]
	v_pk_fma_f32 v[2:3], v[50:51], v[14:15], v[2:3]
	v_pk_fma_f32 v[12:13], v[44:45], v[12:13], v[24:25]
	v_cvt_pk_bf16_f32 v2, v2, v3
	v_cvt_pk_bf16_f32 v3, v4, v5
	v_cvt_pk_bf16_f32 v4, v8, v9
	s_nop 0
	v_cvt_pk_bf16_f32 v5, v12, v13
	global_load_dwordx4 v[8:11], v[30:31], off offset:256
	s_nop 0
	global_store_dwordx4 v[32:33], v[2:5], off
	s_waitcnt vmcnt(1)
	s_nop 0
	v_lshlrev_b32_e32 v2, 16, v8
	v_and_b32_e32 v3, 0xffff0000, v8
	v_lshlrev_b32_e32 v4, 16, v9
	v_and_b32_e32 v5, 0xffff0000, v9
	v_lshlrev_b32_e32 v8, 16, v10
	v_and_b32_e32 v9, 0xffff0000, v10
	v_lshlrev_b32_e32 v10, 16, v11
	v_and_b32_e32 v11, 0xffff0000, v11
	v_pk_fma_f32 v[4:5], v[40:41], v[22:23], v[4:5]
	v_pk_fma_f32 v[2:3], v[38:39], v[20:21], v[2:3]
	v_pk_fma_f32 v[10:11], v[36:37], v[18:19], v[10:11]
	v_pk_fma_f32 v[6:7], v[34:35], v[6:7], v[8:9]
	v_cvt_pk_bf16_f32 v2, v2, v3
	v_cvt_pk_bf16_f32 v3, v4, v5
	s_nop 0
	v_cvt_pk_bf16_f32 v4, v6, v7
	v_cvt_pk_bf16_f32 v5, v10, v11
	global_store_dwordx4 v[30:31], v[2:5], off offset:256
	s_and_b64 vcc, exec, s[2:3]
	s_mov_b64 s[2:3], -1
	s_cbranch_vccnz .LBB0_1501
